# add: P1 first K-tile MFMAs take C=0 (no accumulator zeroing), row-max tree interleaved into PV MFMAs, last z load of attention epilogue hoisted
# speedup vs baseline: 1.0206x; 1.0069x over previous
; #define PG8_STAGE(bufoff, gbase, voff) do { _Pragma("unroll") for (int _i = 0; _i < 2; ++_i) \
;         __builtin_amdgcn_global_load_lds((const unsigned*)((const char*)(gbase) + (voff)[_i]), (LAS unsigned*)(lds + (bufoff) + ldsw + _i * 8192), 16, 0, 0); } while (0)
; #define PG8_LDA(dst, b, h) do { _Pragma("unroll") for (int m = 0; m < 4; ++m) _Pragma("unroll") for (int k = 0; k < 2; ++k) dst[m][k] = *(const LAS bf16x8*)(lds + PG8_SA(b, h) + aoff + m * 2048 + k * 1024); } while (0)
; #define PG8_LDB(dst, b, h) do { _Pragma("unroll") for (int n = 0; n < 2; ++n) _Pragma("unroll") for (int k = 0; k < 2; ++k) dst[n][k] = *(const LAS bf16x8*)(lds + PG8_SB(b, h) + boff + n * 2048 + k * 1024); } while (0)
; #define PG8_MMA(ai, bj, At, Bt) do { __builtin_amdgcn_s_setprio(1); _Pragma("unroll") for (int m = 0; m < 4; ++m) _Pragma("unroll") for (int n = 0; n < 2; ++n) _Pragma("unroll") for (int k = 0; k < 2; ++k) \
;         acc[ai][bj][m][n] = __builtin_amdgcn_mfma_f32_16x16x32_bf16(Bt[n][k], At[m][k], acc[ai][bj][m][n], 0, 0, 0); __builtin_amdgcn_s_setprio(0); } while (0)
; #define PG8_WAIT_V(n) asm volatile("s_waitcnt vmcnt(" #n ")" ::: "memory")
; #define PG8_WAIT_L(n) asm volatile("s_waitcnt lgkmcnt(" #n ")" ::: "memory")
; #define PG8_BAR __builtin_amdgcn_s_barrier()
; #define PG8_SCHED __builtin_amdgcn_sched_barrier(0)
; template <class Epi, class Sched, int NSEG, bool ALIGN_EPI = true, bool AFTER_DRAIN = false>
; __device__ __forceinline__ void gemm_phase(LAS unsigned char* lds, const Gemm g, const Sched& S, const Epi& E) {
;     ...
;     for (;;) {
;         const bool has_next = S.next(ui + 1, nxt);
;         const char* nA = has_next ? PG8_ABASE(nxt) : cA; const char* nB = has_next ? PG8_BBASE(nxt) : cB;
;         for (int t = 0; t < nt; t += 2) {
;             const bool last = (t == nt - 2);
;             const char* a1 = cA + (size_t)(t + 1) * kstep;
;             const char* a2 = last ? nA : cA + (size_t)(t + 2) * kstep; const char* b2 = last ? nB : cB + (size_t)(t + 2) * kstep;
;             const char* a3 = a2 + kstep; const char* b3 = b2 + kstep;
;             PG8_LDB(B0, 0, 0); PG8_LDB(B1, 0, 1); PG8_SCHED; PG8_LDA(At, 0, 0); PG8_STAGE(PG8_SA(1, 1), a1 + hstep, voffA);
;             PG8_WAIT_V(8); PG8_WAIT_L(0); PG8_BAR; PG8_MMA(0, 0, At, B0); PG8_MMA(0, 1, At, B1); PG8_BAR; PG8_SCHED;
.LBB0_326:
	ds_read_b128 v[192:195], v164 offset:0
	ds_read_b128 v[196:199], v164 offset:1024
	ds_read_b128 v[200:203], v164 offset:2048
	ds_read_b128 v[204:207], v164 offset:3072
	ds_read_b128 v[208:211], v164 offset:4096
	ds_read_b128 v[212:215], v164 offset:5120
	ds_read_b128 v[216:219], v164 offset:6144
	ds_read_b128 v[220:223], v164 offset:7168
	ds_read_b128 v[128:131], v162 offset:0
	ds_read_b128 v[132:135], v162 offset:1024
	ds_read_b128 v[166:169], v162 offset:2048
	ds_read_b128 v[170:173], v162 offset:3072
	s_ashr_i32 s19, s18, 31
	s_lshl_b64 s[20:21], s[18:19], 20
	s_add_u32 s20, s4, s20
	s_addc_u32 s21, s5, s21
	v_readlane_b32 s52, v248, 29
	s_and_b64 s[22:23], s[0:1], exec
	v_readlane_b32 s53, v248, 30
	v_readlane_b32 s54, v248, 31
	v_readlane_b32 s55, v248, 32
	v_readlane_b32 s56, v248, 33
	v_readlane_b32 s57, v248, 34
	s_cselect_b32 s3, s21, s27
	s_cselect_b32 s19, s20, s26
	s_ashr_i32 s17, s16, 31
	v_readlane_b32 s58, v248, 35
	v_readlane_b32 s59, v248, 36
	s_mov_b64 s[52:53], s[56:57]
	s_lshl_b64 s[22:23], s[16:17], 20
	s_mov_b64 s[54:55], s[58:59]
	s_add_u32 s22, s54, s22
	s_addc_u32 s23, s55, s23
	s_and_b64 s[30:31], s[0:1], exec
	s_cselect_b32 s17, s23, s29
	s_cselect_b32 s25, s22, s28
	s_waitcnt lgkmcnt(0)
	s_barrier
	s_add_u32 s74, s72, 0x80000
	s_addc_u32 s75, s73, 0
	s_add_u32 s78, s76, 0x80000
	s_addc_u32 s79, s77, 0
	v_mfma_f32_16x16x32_bf16 v[124:127], v[128:131], v[192:195], 0
	ds_read_b128 v[174:177], v162 offset:16384
	v_mfma_f32_16x16x32_bf16 v[120:123], v[166:169], v[192:195], 0
	ds_read_b128 v[178:181], v162 offset:17408
	v_mfma_f32_16x16x32_bf16 v[108:111], v[128:131], v[200:203], 0
	ds_read_b128 v[182:185], v162 offset:18432
	v_mfma_f32_16x16x32_bf16 v[104:107], v[166:169], v[200:203], 0
	ds_read_b128 v[188:191], v162 offset:19456
	v_mfma_f32_16x16x32_bf16 v[92:95], v[128:131], v[208:211], 0
	s_mov_b32 m0, s33
	v_mfma_f32_16x16x32_bf16 v[88:91], v[166:169], v[208:211], 0
	global_load_lds_dwordx4 v138, s[72:73]
	v_mfma_f32_16x16x32_bf16 v[76:79], v[128:131], v[216:219], 0
	ds_read_b128 v[224:227], v164 offset:16384
	v_mfma_f32_16x16x32_bf16 v[72:75], v[166:169], v[216:219], 0
	ds_read_b128 v[228:231], v164 offset:17408
	v_mfma_f32_16x16x32_bf16 v[124:127], v[132:135], v[196:199], v[124:127]
	ds_read_b128 v[232:235], v164 offset:18432
	v_mfma_f32_16x16x32_bf16 v[120:123], v[170:173], v[196:199], v[120:123]
	ds_read_b128 v[236:239], v164 offset:19456
	v_mfma_f32_16x16x32_bf16 v[108:111], v[132:135], v[204:207], v[108:111]
	s_add_i32 m0, s33, 0x2000
	v_mfma_f32_16x16x32_bf16 v[104:107], v[170:173], v[204:207], v[104:107]
	global_load_lds_dwordx4 v142, s[72:73]
	v_mfma_f32_16x16x32_bf16 v[92:95], v[132:135], v[212:215], v[92:95]
	ds_read_b128 v[240:243], v164 offset:20480
	v_mfma_f32_16x16x32_bf16 v[88:91], v[170:173], v[212:215], v[88:91]
	ds_read_b128 v[244:247], v164 offset:21504
	v_mfma_f32_16x16x32_bf16 v[76:79], v[132:135], v[220:223], v[76:79]
	ds_read_b128 v[250:253], v164 offset:22528
	v_mfma_f32_16x16x32_bf16 v[72:75], v[170:173], v[220:223], v[72:75]
	ds_read_b128 v[150:153], v164 offset:23552
	s_waitcnt lgkmcnt(8)
	v_mfma_f32_16x16x32_bf16 v[116:119], v[174:177], v[192:195], 0
	s_add_i32 m0, s33, 0x10000
	v_mfma_f32_16x16x32_bf16 v[112:115], v[182:185], v[192:195], 0
	global_load_lds_dwordx4 v140, s[76:77]
	v_mfma_f32_16x16x32_bf16 v[100:103], v[174:177], v[200:203], 0
	v_mfma_f32_16x16x32_bf16 v[96:99], v[182:185], v[200:203], 0
	v_mfma_f32_16x16x32_bf16 v[84:87], v[174:177], v[208:211], 0
	s_add_i32 m0, s33, 0x12000
	v_mfma_f32_16x16x32_bf16 v[80:83], v[182:185], v[208:211], 0
	global_load_lds_dwordx4 v144, s[76:77]
	v_mfma_f32_16x16x32_bf16 v[68:71], v[174:177], v[216:219], 0
	v_mfma_f32_16x16x32_bf16 v[64:67], v[182:185], v[216:219], 0
	v_mfma_f32_16x16x32_bf16 v[116:119], v[178:181], v[196:199], v[116:119]
	v_mfma_f32_16x16x32_bf16 v[112:115], v[188:191], v[196:199], v[112:115]
	v_mfma_f32_16x16x32_bf16 v[100:103], v[178:181], v[204:207], v[100:103]
	v_mfma_f32_16x16x32_bf16 v[96:99], v[188:191], v[204:207], v[96:99]
	v_mfma_f32_16x16x32_bf16 v[84:87], v[178:181], v[212:215], v[84:87]
	v_mfma_f32_16x16x32_bf16 v[80:83], v[188:191], v[212:215], v[80:83]
	v_mfma_f32_16x16x32_bf16 v[68:71], v[178:181], v[220:223], v[68:71]
	v_mfma_f32_16x16x32_bf16 v[64:67], v[188:191], v[220:223], v[64:67]
	s_waitcnt vmcnt(8) lgkmcnt(0)
	s_barrier
; #define PG8_STAGE(bufoff, gbase, voff) do { _Pragma("unroll") for (int _i = 0; _i < 2; ++_i) \
;         __builtin_amdgcn_global_load_lds((const unsigned*)((const char*)(gbase) + (voff)[_i]), (LAS unsigned*)(lds + (bufoff) + ldsw + _i * 8192), 16, 0, 0); } while (0)
; #define PG8_LDA(dst, b, h) do { _Pragma("unroll") for (int m = 0; m < 4; ++m) _Pragma("unroll") for (int k = 0; k < 2; ++k) dst[m][k] = *(const LAS bf16x8*)(lds + PG8_SA(b, h) + aoff + m * 2048 + k * 1024); } while (0)
; #define PG8_LDB(dst, b, h) do { _Pragma("unroll") for (int n = 0; n < 2; ++n) _Pragma("unroll") for (int k = 0; k < 2; ++k) dst[n][k] = *(const LAS bf16x8*)(lds + PG8_SB(b, h) + boff + n * 2048 + k * 1024); } while (0)
; #define PG8_MMA(ai, bj, At, Bt) do { __builtin_amdgcn_s_setprio(1); _Pragma("unroll") for (int m = 0; m < 4; ++m) _Pragma("unroll") for (int n = 0; n < 2; ++n) _Pragma("unroll") for (int k = 0; k < 2; ++k) \
;         acc[ai][bj][m][n] = __builtin_amdgcn_mfma_f32_16x16x32_bf16(Bt[n][k], At[m][k], acc[ai][bj][m][n], 0, 0, 0); __builtin_amdgcn_s_setprio(0); } while (0)
; #define PG8_WAIT_V(n) asm volatile("s_waitcnt vmcnt(" #n ")" ::: "memory")
; #define PG8_WAIT_L(n) asm volatile("s_waitcnt lgkmcnt(" #n ")" ::: "memory")
; #define PG8_BAR __builtin_amdgcn_s_barrier()
; #define PG8_SCHED __builtin_amdgcn_sched_barrier(0)
; template <class Epi, class Sched, int NSEG, bool ALIGN_EPI = true, bool AFTER_DRAIN = false>
; __device__ __forceinline__ void gemm_phase(LAS unsigned char* lds, const Gemm g, const Sched& S, const Epi& E) {
;     ...
;             PG8_WAIT_V(8); PG8_WAIT_L(0); PG8_BAR; PG8_MMA(0, 0, At, B0); PG8_MMA(0, 1, At, B1); PG8_BAR; PG8_SCHED;
;             PG8_LDA(At, 0, 1); PG8_STAGE(PG8_SB(0, 0), b2, voffB); PG8_STAGE(PG8_SB(0, 1), b2 + hstep, voffB); PG8_STAGE(PG8_SA(0, 0), a2, voffA);
;             PG8_WAIT_V(8); PG8_WAIT_L(0); PG8_BAR; PG8_MMA(1, 0, At, B0); PG8_MMA(1, 1, At, B1); PG8_BAR; PG8_SCHED;
;             PG8_LDB(B0, 1, 0); PG8_LDB(B1, 1, 1); PG8_SCHED; PG8_LDA(At, 1, 0); PG8_STAGE(PG8_SA(0, 1), a2 + hstep, voffA);
;             PG8_WAIT_V(8); PG8_WAIT_L(0); PG8_BAR; PG8_MMA(0, 0, At, B0); PG8_MMA(0, 1, At, B1); PG8_BAR; PG8_SCHED;
	v_mfma_f32_16x16x32_bf16 v[60:63], v[128:131], v[224:227], 0
	ds_read_b128 v[192:195], v164 offset:32768
	v_mfma_f32_16x16x32_bf16 v[56:59], v[166:169], v[224:227], 0
	ds_read_b128 v[196:199], v164 offset:33792
	v_mfma_f32_16x16x32_bf16 v[44:47], v[128:131], v[232:235], 0
	ds_read_b128 v[200:203], v164 offset:34816
	v_mfma_f32_16x16x32_bf16 v[40:43], v[166:169], v[232:235], 0
	ds_read_b128 v[204:207], v164 offset:35840
	v_mfma_f32_16x16x32_bf16 v[28:31], v[128:131], v[240:243], 0
	ds_read_b128 v[208:211], v164 offset:36864
	v_mfma_f32_16x16x32_bf16 v[24:27], v[166:169], v[240:243], 0
	ds_read_b128 v[212:215], v164 offset:37888
	v_mfma_f32_16x16x32_bf16 v[12:15], v[128:131], v[250:253], 0
	ds_read_b128 v[216:219], v164 offset:38912
	v_mfma_f32_16x16x32_bf16 v[8:11], v[166:169], v[250:253], 0
	ds_read_b128 v[220:223], v164 offset:39936
	v_mfma_f32_16x16x32_bf16 v[60:63], v[132:135], v[228:231], v[60:63]
	s_add_i32 m0, s33, 0x4000
	v_mfma_f32_16x16x32_bf16 v[56:59], v[170:173], v[228:231], v[56:59]
	global_load_lds_dwordx4 v138, s[74:75]
	v_mfma_f32_16x16x32_bf16 v[44:47], v[132:135], v[236:239], v[44:47]
	v_mfma_f32_16x16x32_bf16 v[40:43], v[170:173], v[236:239], v[40:43]
	v_mfma_f32_16x16x32_bf16 v[28:31], v[132:135], v[244:247], v[28:31]
	s_add_i32 m0, s33, 0x6000
	v_mfma_f32_16x16x32_bf16 v[24:27], v[170:173], v[244:247], v[24:27]
	global_load_lds_dwordx4 v142, s[74:75]
	v_mfma_f32_16x16x32_bf16 v[12:15], v[132:135], v[150:153], v[12:15]
	v_mfma_f32_16x16x32_bf16 v[8:11], v[170:173], v[150:153], v[8:11]
	v_mfma_f32_16x16x32_bf16 v[52:55], v[174:177], v[224:227], 0
	ds_read_b128 v[128:131], v162 offset:32768
	v_mfma_f32_16x16x32_bf16 v[48:51], v[182:185], v[224:227], 0
	ds_read_b128 v[132:135], v162 offset:33792
	v_mfma_f32_16x16x32_bf16 v[36:39], v[174:177], v[232:235], 0
	ds_read_b128 v[166:169], v162 offset:34816
	v_mfma_f32_16x16x32_bf16 v[32:35], v[182:185], v[232:235], 0
	ds_read_b128 v[170:173], v162 offset:35840
	v_mfma_f32_16x16x32_bf16 v[20:23], v[174:177], v[240:243], 0
	s_add_i32 m0, s33, 0x14000
	v_mfma_f32_16x16x32_bf16 v[16:19], v[182:185], v[240:243], 0
	global_load_lds_dwordx4 v140, s[78:79]
	v_mfma_f32_16x16x32_bf16 v[4:7], v[174:177], v[250:253], 0
	v_mfma_f32_16x16x32_bf16 v[0:3], v[182:185], v[250:253], 0
	v_mfma_f32_16x16x32_bf16 v[52:55], v[178:181], v[228:231], v[52:55]
	s_add_i32 m0, s33, 0x16000
	v_mfma_f32_16x16x32_bf16 v[48:51], v[188:191], v[228:231], v[48:51]
	global_load_lds_dwordx4 v144, s[78:79]
	v_mfma_f32_16x16x32_bf16 v[36:39], v[178:181], v[236:239], v[36:39]
	v_mfma_f32_16x16x32_bf16 v[32:35], v[188:191], v[236:239], v[32:35]
	v_mfma_f32_16x16x32_bf16 v[20:23], v[178:181], v[244:247], v[20:23]
	v_mfma_f32_16x16x32_bf16 v[16:19], v[188:191], v[244:247], v[16:19]
	v_mfma_f32_16x16x32_bf16 v[4:7], v[178:181], v[150:153], v[4:7]
	v_mfma_f32_16x16x32_bf16 v[0:3], v[188:191], v[150:153], v[0:3]
	s_waitcnt vmcnt(8) lgkmcnt(0)
	s_barrier
	v_mfma_f32_16x16x32_bf16 v[124:127], v[128:131], v[192:195], v[124:127]
	ds_read_b128 v[174:177], v162 offset:49152
	s_add_u32 s72, s72, 0x80
	s_addc_u32 s73, s73, 0
	v_mfma_f32_16x16x32_bf16 v[120:123], v[166:169], v[192:195], v[120:123]
	ds_read_b128 v[178:181], v162 offset:50176
	s_add_u32 s76, s76, 0x80
	s_addc_u32 s77, s77, 0
	v_mfma_f32_16x16x32_bf16 v[108:111], v[128:131], v[200:203], v[108:111]
	ds_read_b128 v[182:185], v162 offset:51200
	v_mfma_f32_16x16x32_bf16 v[104:107], v[166:169], v[200:203], v[104:107]
	ds_read_b128 v[188:191], v162 offset:52224
	v_mfma_f32_16x16x32_bf16 v[92:95], v[128:131], v[208:211], v[92:95]
	s_add_i32 m0, s33, 0x8000
	v_mfma_f32_16x16x32_bf16 v[88:91], v[166:169], v[208:211], v[88:91]
	global_load_lds_dwordx4 v138, s[72:73]
	v_mfma_f32_16x16x32_bf16 v[76:79], v[128:131], v[216:219], v[76:79]
	ds_read_b128 v[224:227], v164 offset:49152
	v_mfma_f32_16x16x32_bf16 v[72:75], v[166:169], v[216:219], v[72:75]
	ds_read_b128 v[228:231], v164 offset:50176
	v_mfma_f32_16x16x32_bf16 v[124:127], v[132:135], v[196:199], v[124:127]
	ds_read_b128 v[232:235], v164 offset:51200
	v_mfma_f32_16x16x32_bf16 v[120:123], v[170:173], v[196:199], v[120:123]
	ds_read_b128 v[236:239], v164 offset:52224
	v_mfma_f32_16x16x32_bf16 v[108:111], v[132:135], v[204:207], v[108:111]
	s_add_i32 m0, s33, 0xa000
	v_mfma_f32_16x16x32_bf16 v[104:107], v[170:173], v[204:207], v[104:107]
	global_load_lds_dwordx4 v142, s[72:73]
	v_mfma_f32_16x16x32_bf16 v[92:95], v[132:135], v[212:215], v[92:95]
	ds_read_b128 v[240:243], v164 offset:53248
	v_mfma_f32_16x16x32_bf16 v[88:91], v[170:173], v[212:215], v[88:91]
	ds_read_b128 v[244:247], v164 offset:54272
	v_mfma_f32_16x16x32_bf16 v[76:79], v[132:135], v[220:223], v[76:79]
	ds_read_b128 v[250:253], v164 offset:55296
	v_mfma_f32_16x16x32_bf16 v[72:75], v[170:173], v[220:223], v[72:75]
	ds_read_b128 v[150:153], v164 offset:56320
	s_waitcnt lgkmcnt(8)
	v_mfma_f32_16x16x32_bf16 v[116:119], v[174:177], v[192:195], v[116:119]
	s_add_i32 m0, s33, 0x18000
	v_mfma_f32_16x16x32_bf16 v[112:115], v[182:185], v[192:195], v[112:115]
	global_load_lds_dwordx4 v140, s[76:77]
	v_mfma_f32_16x16x32_bf16 v[100:103], v[174:177], v[200:203], v[100:103]
	v_mfma_f32_16x16x32_bf16 v[96:99], v[182:185], v[200:203], v[96:99]
	v_mfma_f32_16x16x32_bf16 v[84:87], v[174:177], v[208:211], v[84:87]
	s_add_i32 m0, s33, 0x1a000
	v_mfma_f32_16x16x32_bf16 v[80:83], v[182:185], v[208:211], v[80:83]
	global_load_lds_dwordx4 v144, s[76:77]
	v_mfma_f32_16x16x32_bf16 v[68:71], v[174:177], v[216:219], v[68:71]
	v_mfma_f32_16x16x32_bf16 v[64:67], v[182:185], v[216:219], v[64:67]
	v_mfma_f32_16x16x32_bf16 v[116:119], v[178:181], v[196:199], v[116:119]
	s_add_u32 s74, s74, 0x80
	s_addc_u32 s75, s75, 0
	v_mfma_f32_16x16x32_bf16 v[112:115], v[188:191], v[196:199], v[112:115]
	s_add_u32 s78, s78, 0x80
	s_addc_u32 s79, s79, 0
	v_mfma_f32_16x16x32_bf16 v[100:103], v[178:181], v[204:207], v[100:103]
	v_mfma_f32_16x16x32_bf16 v[96:99], v[188:191], v[204:207], v[96:99]
	v_mfma_f32_16x16x32_bf16 v[84:87], v[178:181], v[212:215], v[84:87]
	v_mfma_f32_16x16x32_bf16 v[80:83], v[188:191], v[212:215], v[80:83]
	v_mfma_f32_16x16x32_bf16 v[68:71], v[178:181], v[220:223], v[68:71]
	v_mfma_f32_16x16x32_bf16 v[64:67], v[188:191], v[220:223], v[64:67]
	s_waitcnt vmcnt(8) lgkmcnt(0)
	s_barrier
; #define PG8_STAGE(bufoff, gbase, voff) do { _Pragma("unroll") for (int _i = 0; _i < 2; ++_i) \
;         __builtin_amdgcn_global_load_lds((const unsigned*)((const char*)(gbase) + (voff)[_i]), (LAS unsigned*)(lds + (bufoff) + ldsw + _i * 8192), 16, 0, 0); } while (0)
; #define PG8_LDA(dst, b, h) do { _Pragma("unroll") for (int m = 0; m < 4; ++m) _Pragma("unroll") for (int k = 0; k < 2; ++k) dst[m][k] = *(const LAS bf16x8*)(lds + PG8_SA(b, h) + aoff + m * 2048 + k * 1024); } while (0)
; #define PG8_MMA(ai, bj, At, Bt) do { __builtin_amdgcn_s_setprio(1); _Pragma("unroll") for (int m = 0; m < 4; ++m) _Pragma("unroll") for (int n = 0; n < 2; ++n) _Pragma("unroll") for (int k = 0; k < 2; ++k) \
;         acc[ai][bj][m][n] = __builtin_amdgcn_mfma_f32_16x16x32_bf16(Bt[n][k], At[m][k], acc[ai][bj][m][n], 0, 0, 0); __builtin_amdgcn_s_setprio(0); } while (0)
; #define PG8_WAIT_V(n) asm volatile("s_waitcnt vmcnt(" #n ")" ::: "memory")
; #define PG8_WAIT_L(n) asm volatile("s_waitcnt lgkmcnt(" #n ")" ::: "memory")
; #define PG8_BAR __builtin_amdgcn_s_barrier()
; #define PG8_SCHED __builtin_amdgcn_sched_barrier(0)
; template <class Epi, class Sched, int NSEG, bool ALIGN_EPI = true, bool AFTER_DRAIN = false>
; __device__ __forceinline__ void gemm_phase(LAS unsigned char* lds, const Gemm g, const Sched& S, const Epi& E) {
;     ...
;             PG8_WAIT_V(8); PG8_WAIT_L(0); PG8_BAR; PG8_MMA(0, 0, At, B0); PG8_MMA(0, 1, At, B1); PG8_BAR; PG8_SCHED;
;             PG8_LDA(At, 1, 1); PG8_STAGE(PG8_SB(1, 0), b3, voffB); PG8_STAGE(PG8_SB(1, 1), b3 + hstep, voffB); PG8_STAGE(PG8_SA(1, 0), a3, voffA);
;             PG8_WAIT_V(8); PG8_WAIT_L(0); PG8_BAR; PG8_MMA(1, 0, At, B0); PG8_MMA(1, 1, At, B1); PG8_BAR; PG8_SCHED;
	v_mfma_f32_16x16x32_bf16 v[60:63], v[128:131], v[224:227], v[60:63]
	ds_read_b128 v[192:195], v164 offset:0
	v_mfma_f32_16x16x32_bf16 v[56:59], v[166:169], v[224:227], v[56:59]
	ds_read_b128 v[196:199], v164 offset:1024
	v_mfma_f32_16x16x32_bf16 v[44:47], v[128:131], v[232:235], v[44:47]
	ds_read_b128 v[200:203], v164 offset:2048
	v_mfma_f32_16x16x32_bf16 v[40:43], v[166:169], v[232:235], v[40:43]
	ds_read_b128 v[204:207], v164 offset:3072
	v_mfma_f32_16x16x32_bf16 v[28:31], v[128:131], v[240:243], v[28:31]
	ds_read_b128 v[208:211], v164 offset:4096
	v_mfma_f32_16x16x32_bf16 v[24:27], v[166:169], v[240:243], v[24:27]
	ds_read_b128 v[212:215], v164 offset:5120
	v_mfma_f32_16x16x32_bf16 v[12:15], v[128:131], v[250:253], v[12:15]
	ds_read_b128 v[216:219], v164 offset:6144
	v_mfma_f32_16x16x32_bf16 v[8:11], v[166:169], v[250:253], v[8:11]
	ds_read_b128 v[220:223], v164 offset:7168
	v_mfma_f32_16x16x32_bf16 v[60:63], v[132:135], v[228:231], v[60:63]
	s_add_i32 m0, s33, 0xc000
	v_mfma_f32_16x16x32_bf16 v[56:59], v[170:173], v[228:231], v[56:59]
	global_load_lds_dwordx4 v138, s[74:75]
	v_mfma_f32_16x16x32_bf16 v[44:47], v[132:135], v[236:239], v[44:47]
	v_mfma_f32_16x16x32_bf16 v[40:43], v[170:173], v[236:239], v[40:43]
	v_mfma_f32_16x16x32_bf16 v[28:31], v[132:135], v[244:247], v[28:31]
	s_add_i32 m0, s33, 0xe000
	v_mfma_f32_16x16x32_bf16 v[24:27], v[170:173], v[244:247], v[24:27]
	global_load_lds_dwordx4 v142, s[74:75]
	v_mfma_f32_16x16x32_bf16 v[12:15], v[132:135], v[150:153], v[12:15]
	v_mfma_f32_16x16x32_bf16 v[8:11], v[170:173], v[150:153], v[8:11]
	v_mfma_f32_16x16x32_bf16 v[52:55], v[174:177], v[224:227], v[52:55]
	ds_read_b128 v[128:131], v162 offset:0
	v_mfma_f32_16x16x32_bf16 v[48:51], v[182:185], v[224:227], v[48:51]
	ds_read_b128 v[132:135], v162 offset:1024
	v_mfma_f32_16x16x32_bf16 v[36:39], v[174:177], v[232:235], v[36:39]
	ds_read_b128 v[166:169], v162 offset:2048
	v_mfma_f32_16x16x32_bf16 v[32:35], v[182:185], v[232:235], v[32:35]
	ds_read_b128 v[170:173], v162 offset:3072
	v_mfma_f32_16x16x32_bf16 v[20:23], v[174:177], v[240:243], v[20:23]
	s_add_i32 m0, s33, 0x1c000
	v_mfma_f32_16x16x32_bf16 v[16:19], v[182:185], v[240:243], v[16:19]
	global_load_lds_dwordx4 v140, s[78:79]
	v_mfma_f32_16x16x32_bf16 v[4:7], v[174:177], v[250:253], v[4:7]
	v_mfma_f32_16x16x32_bf16 v[0:3], v[182:185], v[250:253], v[0:3]
	v_mfma_f32_16x16x32_bf16 v[52:55], v[178:181], v[228:231], v[52:55]
	s_add_i32 m0, s33, 0x1e000
	v_mfma_f32_16x16x32_bf16 v[48:51], v[188:191], v[228:231], v[48:51]
	global_load_lds_dwordx4 v144, s[78:79]
	v_mfma_f32_16x16x32_bf16 v[36:39], v[178:181], v[236:239], v[36:39]
	v_mfma_f32_16x16x32_bf16 v[32:35], v[188:191], v[236:239], v[32:35]
	s_add_u32 s72, s72, 0x80
	s_addc_u32 s73, s73, 0
	v_mfma_f32_16x16x32_bf16 v[20:23], v[178:181], v[244:247], v[20:23]
	s_add_u32 s76, s76, 0x80
	s_addc_u32 s77, s77, 0
	v_mfma_f32_16x16x32_bf16 v[16:19], v[188:191], v[244:247], v[16:19]
	v_mfma_f32_16x16x32_bf16 v[4:7], v[178:181], v[150:153], v[4:7]
	v_mfma_f32_16x16x32_bf16 v[0:3], v[188:191], v[150:153], v[0:3]
	s_waitcnt vmcnt(8) lgkmcnt(0)
	s_barrier
	s_mov_b32 s80, 1
	.p2align 6

; #define LAS __attribute__((address_space(3)))
; __device__ __forceinline__ unsigned cvt_pk_bf16(float lo, float hi) { unsigned r; asm volatile("v_cvt_pk_bf16_f32 %0, %1, %2" : "=v"(r) : "v"(lo), "v"(hi)); return r; }
; __device__ __forceinline__ float bf_lo(unsigned w) { return __uint_as_float(w << 16); }
; __device__ __forceinline__ float bf_hi(unsigned w) { return __uint_as_float(w & 0xffff0000u); }
; __device__ __forceinline__ int crow(int r, int hi) { return (r & 3) + 8 * (r >> 2) + 4 * hi; }
; __device__ __forceinline__ void fox_block(const BlockRef& cur, const BlockRef& nxt, char* lds, Seam& S, const int tid) {
;     ...
;     if (hi == 0) li_l[r32] = l_reg; asm volatile("s_waitcnt lgkmcnt(0)" ::: "memory");
;     float rli[16];
; #pragma unroll
;     for (int r = 0; r < 16; ++r) rli[r] = __builtin_amdgcn_rcpf(li_l[crow(r, hi)]);
;     typedef __attribute__((address_space(1))) bf16_t gbf16; typedef __attribute__((address_space(1))) u32x4 gu32x4;
;     LAS float* stg = (LAS float*)(lds3 + SLOT + wid * 4096);
;     const int er = lane >> 2, eq = lane & 3;
;     gbf16* obase = (gbf16*)(cur.O + (size_t)(wid * QBLK + er) * LD + 8 * eq); const gbf16* zbase = (const gbf16*)(cur.Z + (size_t)(wid * QBLK + er) * LD + 8 * eq);
; #pragma unroll
;     for (int d0 = 0; d0 < 4; ++d0) {
; #pragma unroll
;         for (int r = 0; r < 16; ++r) stg[crow(r, hi) * 32 + r32] = o[d0][r] * rli[r];
;         asm volatile("s_waitcnt lgkmcnt(0)" ::: "memory");
;         gbf16* op = obase; const gbf16* zp = zbase;
; #pragma unroll
;         for (int i = 0; i < 2; ++i) {
;             asm volatile("" : "+v"(op), "+v"(zp));
;             const f32x4 v0 = *(const LAS f32x4*)(stg + (er + 16 * i) * 32 + 8 * eq), v1 = *(const LAS f32x4*)(stg + (er + 16 * i) * 32 + 8 * eq + 4);
;             const u32x4 z = __builtin_nontemporal_load((const gu32x4*)(zp + d0 * 32));
;             u32x4 w; w.x = cvt_pk_bf16(v0.x * bf_lo(z.x), v0.y * bf_hi(z.x)); w.y = cvt_pk_bf16(v0.z * bf_lo(z.y), v0.w * bf_hi(z.y));
;             w.z = cvt_pk_bf16(v1.x * bf_lo(z.z), v1.y * bf_hi(z.z)); w.w = cvt_pk_bf16(v1.z * bf_lo(z.w), v1.w * bf_hi(z.w));
;             *(gu32x4*)(op + d0 * 32) = w;
;             op += 16 * LD; zp += 16 * LD; }
;         asm volatile("s_waitcnt lgkmcnt(0)" ::: "memory"); }
.LBB0_485:
	s_or_b64 exec, exec, s[2:3]
	s_waitcnt lgkmcnt(0)
	ds_read_b128 v[64:67], v131
	ds_read_b128 v[68:71], v131 offset:32
	v_readlane_b32 s0, v248, 54
	s_add_u32 s0, s0, s68
	v_readlane_b32 s1, v248, 56
	s_waitcnt lgkmcnt(0)
	v_rcp_f32_e32 v72, v64
	v_rcp_f32_e32 v73, v65
	v_rcp_f32_e32 v74, v66
	v_rcp_f32_e32 v75, v67
	v_rcp_f32_e32 v76, v68
	ds_read_b128 v[64:67], v131 offset:64
	v_rcp_f32_e32 v77, v69
	v_rcp_f32_e32 v78, v70
	v_rcp_f32_e32 v79, v71
	ds_read_b128 v[68:71], v131 offset:96
	s_addc_u32 s1, s1, s69
	v_readlane_b32 s2, v248, 42
	s_add_u32 s2, s2, s68
	v_readlane_b32 s3, v248, 43
	s_addc_u32 s3, s3, s69
	s_lshl_b32 s4, s70, 12
	s_add_i32 s4, s4, 0
	s_waitcnt lgkmcnt(0)
	v_rcp_f32_e32 v84, v68
	v_add3_u32 v68, s4, v133, v170
	v_rcp_f32_e32 v80, v64
	v_rcp_f32_e32 v81, v65
	v_mul_f32_e32 v48, v48, v72
	v_mul_f32_e32 v49, v49, v73
	v_add_u32_e32 v88, 0x4000, v68
	v_rcp_f32_e32 v82, v66
	v_rcp_f32_e32 v83, v67
	ds_write2_b32 v88, v48, v49 offset1:32
	v_mul_f32_e32 v48, v50, v74
	v_mul_f32_e32 v49, v51, v75
	v_rcp_f32_e32 v85, v69
	ds_write2_b32 v88, v48, v49 offset0:64 offset1:96
	v_mul_f32_e32 v48, v52, v76
	v_mul_f32_e32 v49, v53, v77
	v_add_u32_e32 v89, 0x4400, v68
	v_rcp_f32_e32 v86, v70
	v_rcp_f32_e32 v87, v71
	v_or_b32_e32 v64, s71, v191
	ds_write2_b32 v89, v48, v49 offset1:32
	v_mul_f32_e32 v48, v54, v78
	v_mul_f32_e32 v49, v55, v79
	v_ashrrev_i32_e32 v65, 31, v64
	ds_write2_b32 v89, v48, v49 offset0:64 offset1:96
	v_mul_f32_e32 v48, v56, v80
	v_mul_f32_e32 v49, v57, v81
	v_add_u32_e32 v90, 0x4800, v68
	v_lshlrev_b64 v[66:67], 12, v[64:65]
	ds_write2_b32 v90, v48, v49 offset1:32
	v_mul_f32_e32 v48, v58, v82
	v_mul_f32_e32 v49, v59, v83
	v_lshl_add_u64 v[64:65], s[0:1], 0, v[66:67]
	v_lshlrev_b32_e32 v128, 1, v132
	v_lshl_add_u64 v[66:67], s[2:3], 0, v[66:67]
	ds_write2_b32 v90, v48, v49 offset0:64 offset1:96
	v_mul_f32_e32 v48, v60, v84
	v_mul_f32_e32 v49, v61, v85
	v_add_u32_e32 v91, 0x4c00, v68
	v_lshl_add_u64 v[64:65], v[64:65], 0, v[128:129]
	v_lshl_add_u64 v[66:67], v[66:67], 0, v[128:129]
	ds_write2_b32 v91, v48, v49 offset1:32
	v_mul_f32_e32 v48, v62, v86
	v_mul_f32_e32 v49, v63, v87
	ds_write2_b32 v91, v48, v49 offset0:64 offset1:96
	v_mov_b64_e32 v[62:63], v[64:65]
	v_mov_b64_e32 v[68:69], v[66:67]
	s_waitcnt lgkmcnt(0)
	global_load_dwordx4 v[50:53], v[68:69], off nt
	v_add_co_u32_e32 v250, vcc, 0x10000, v68
	s_nop 1
	v_addc_co_u32_e32 v251, vcc, 0, v69, vcc
	global_load_dwordx4 v[222:225], v[250:251], off nt
	global_load_dwordx4 v[226:229], v[68:69], off offset:64 nt
	global_load_dwordx4 v[230:233], v[250:251], off offset:64 nt
	global_load_dwordx4 v[234:237], v[68:69], off offset:128 nt
	global_load_dwordx4 v[238:241], v[250:251], off offset:128 nt
	global_load_dwordx4 v[242:245], v[68:69], off offset:192 nt
	v_lshlrev_b32_e32 v48, 2, v132
	v_add3_u32 v48, s4, v48, v145
	ds_read_b128 v[54:57], v48 offset:16384
	ds_read_b128 v[58:61], v48 offset:16400
	s_mov_b64 s[0:1], 0x10000
	v_lshl_add_u64 v[70:71], v[62:63], 0, s[0:1]
	v_lshl_add_u64 v[68:69], v[68:69], 0, s[0:1]
	v_mul_f32_e32 v40, v40, v80
	v_mul_f32_e32 v41, v41, v81
	v_mul_f32_e32 v42, v42, v82
	v_mul_f32_e32 v43, v43, v83
	v_mul_f32_e32 v44, v44, v84
	v_mul_f32_e32 v45, v45, v85
	v_mul_f32_e32 v46, v46, v86
	v_mul_f32_e32 v47, v47, v87
	v_mul_f32_e32 v24, v24, v80
	v_mul_f32_e32 v25, v25, v81
	v_mul_f32_e32 v26, v26, v82
	v_mul_f32_e32 v27, v27, v83
	v_mul_f32_e32 v28, v28, v84
	v_mul_f32_e32 v29, v29, v85
	v_mul_f32_e32 v30, v30, v86
	v_mul_f32_e32 v31, v31, v87
	v_mul_f32_e32 v8, v8, v80
	v_mul_f32_e32 v9, v9, v81
	v_mul_f32_e32 v10, v10, v82
	v_mul_f32_e32 v11, v11, v83
	v_mul_f32_e32 v12, v12, v84
	v_mul_f32_e32 v13, v13, v85
	v_mul_f32_e32 v14, v14, v86
	v_mul_f32_e32 v15, v15, v87
	v_readlane_b32 s60, v247, 11
	s_add_i32 s60, s60, s96
	v_readlane_b32 s66, v247, 4
	v_readlane_b32 s68, v247, 6
	s_movk_i32 s6, 0x1010
	v_readlane_b32 s67, v247, 5
	v_readlane_b32 s69, v247, 7
	s_waitcnt vmcnt(6)
	v_lshlrev_b32_e32 v49, 16, v50
	v_and_b32_e32 v50, 0xffff0000, v50
	v_lshlrev_b32_e32 v92, 16, v51
	v_and_b32_e32 v51, 0xffff0000, v51
	v_lshlrev_b32_e32 v93, 16, v52
	v_and_b32_e32 v52, 0xffff0000, v52
	v_lshlrev_b32_e32 v94, 16, v53
	v_and_b32_e32 v53, 0xffff0000, v53
	s_waitcnt lgkmcnt(1)
	v_mul_f32_e32 v50, v55, v50
	v_mul_f32_e32 v51, v57, v51
	s_waitcnt lgkmcnt(0)
	v_mul_f32_e32 v52, v59, v52
	v_mul_f32_e32 v53, v61, v53
	v_mul_f32_e32 v49, v54, v49
	v_mul_f32_e32 v54, v56, v92
	v_mul_f32_e32 v55, v58, v93
	v_mul_f32_e32 v56, v60, v94
	v_cvt_pk_bf16_f32 v50, v49, v50
	v_cvt_pk_bf16_f32 v51, v54, v51
	v_cvt_pk_bf16_f32 v52, v55, v52
	v_cvt_pk_bf16_f32 v53, v56, v53
	global_store_dwordx4 v[62:63], v[50:53], off
	v_mul_f32_e32 v49, v32, v72
	v_mul_f32_e32 v58, v33, v73
	v_mul_f32_e32 v59, v34, v74
	v_mul_f32_e32 v60, v35, v75
	v_mul_f32_e32 v61, v36, v76
	v_mul_f32_e32 v62, v37, v77
	v_mul_f32_e32 v63, v38, v78
	v_mul_f32_e32 v68, v39, v79
	ds_read_b128 v[32:35], v48 offset:18432
	ds_read_b128 v[36:39], v48 offset:18448
	v_mov_b64_e32 v[54:55], v[64:65]
	v_mov_b64_e32 v[56:57], v[66:67]
	s_waitcnt vmcnt(6)
	v_mov_b32_e32 v50, v222
	v_mov_b32_e32 v51, v223
	v_mov_b32_e32 v52, v224
	v_mov_b32_e32 v53, v225
	global_load_dwordx4 v[222:225], v[250:251], off offset:192 nt
	v_lshlrev_b32_e32 v69, 16, v50
	v_and_b32_e32 v50, 0xffff0000, v50
	v_lshlrev_b32_e32 v92, 16, v51
	v_and_b32_e32 v51, 0xffff0000, v51
	v_lshlrev_b32_e32 v93, 16, v52
	v_and_b32_e32 v52, 0xffff0000, v52
	v_lshlrev_b32_e32 v94, 16, v53
	v_and_b32_e32 v53, 0xffff0000, v53
	s_waitcnt lgkmcnt(1)
	v_mul_f32_e32 v32, v32, v69
	v_mul_f32_e32 v33, v33, v50
	v_mul_f32_e32 v34, v34, v92
	v_mul_f32_e32 v35, v35, v51
	s_waitcnt lgkmcnt(0)
; #define LAS __attribute__((address_space(3)))
; __device__ __forceinline__ unsigned cvt_pk_bf16(float lo, float hi) { unsigned r; asm volatile("v_cvt_pk_bf16_f32 %0, %1, %2" : "=v"(r) : "v"(lo), "v"(hi)); return r; }
; __device__ __forceinline__ float bf_lo(unsigned w) { return __uint_as_float(w << 16); }
; __device__ __forceinline__ float bf_hi(unsigned w) { return __uint_as_float(w & 0xffff0000u); }
; __device__ __forceinline__ int crow(int r, int hi) { return (r & 3) + 8 * (r >> 2) + 4 * hi; }
; __device__ __forceinline__ void fox_block(const BlockRef& cur, const BlockRef& nxt, char* lds, Seam& S, const int tid) {
;     ...
;     for (int d0 = 0; d0 < 4; ++d0) {
; #pragma unroll
;         for (int r = 0; r < 16; ++r) stg[crow(r, hi) * 32 + r32] = o[d0][r] * rli[r];
;         asm volatile("s_waitcnt lgkmcnt(0)" ::: "memory");
;         gbf16* op = obase; const gbf16* zp = zbase;
; #pragma unroll
;         for (int i = 0; i < 2; ++i) {
;             asm volatile("" : "+v"(op), "+v"(zp));
;             const f32x4 v0 = *(const LAS f32x4*)(stg + (er + 16 * i) * 32 + 8 * eq), v1 = *(const LAS f32x4*)(stg + (er + 16 * i) * 32 + 8 * eq + 4);
;             const u32x4 z = __builtin_nontemporal_load((const gu32x4*)(zp + d0 * 32));
;             u32x4 w; w.x = cvt_pk_bf16(v0.x * bf_lo(z.x), v0.y * bf_hi(z.x)); w.y = cvt_pk_bf16(v0.z * bf_lo(z.y), v0.w * bf_hi(z.y));
;             w.z = cvt_pk_bf16(v1.x * bf_lo(z.z), v1.y * bf_hi(z.z)); w.w = cvt_pk_bf16(v1.z * bf_lo(z.w), v1.w * bf_hi(z.w));
;             *(gu32x4*)(op + d0 * 32) = w;
;             op += 16 * LD; zp += 16 * LD; }
;         asm volatile("s_waitcnt lgkmcnt(0)" ::: "memory"); }
	v_mul_f32_e32 v36, v36, v93
	v_mul_f32_e32 v37, v37, v52
	v_mul_f32_e32 v38, v38, v94
	v_mul_f32_e32 v39, v39, v53
	v_cvt_pk_bf16_f32 v32, v32, v33
	v_cvt_pk_bf16_f32 v33, v34, v35
	v_cvt_pk_bf16_f32 v34, v36, v37
	v_cvt_pk_bf16_f32 v35, v38, v39
	global_store_dwordx4 v[70:71], v[32:35], off
	s_waitcnt lgkmcnt(0)
	ds_write2_b32 v88, v49, v58 offset1:32
	ds_write2_b32 v88, v59, v60 offset0:64 offset1:96
	ds_write2_b32 v89, v61, v62 offset1:32
	ds_write2_b32 v89, v63, v68 offset0:64 offset1:96
	ds_write2_b32 v90, v40, v41 offset1:32
	ds_write2_b32 v90, v42, v43 offset0:64 offset1:96
	ds_write2_b32 v91, v44, v45 offset1:32
	ds_write2_b32 v91, v46, v47 offset0:64 offset1:96
	s_waitcnt lgkmcnt(0)
	ds_read_b128 v[36:39], v48 offset:16384
	ds_read_b128 v[40:43], v48 offset:16400
	v_lshl_add_u64 v[44:45], v[54:55], 0, s[0:1]
	v_lshl_add_u64 v[46:47], v[56:57], 0, s[0:1]
	s_waitcnt vmcnt(7)
	v_mov_b32_e32 v32, v226
	v_mov_b32_e32 v33, v227
	v_mov_b32_e32 v34, v228
	v_mov_b32_e32 v35, v229
	v_lshlrev_b32_e32 v49, 16, v32
	v_and_b32_e32 v32, 0xffff0000, v32
	v_lshlrev_b32_e32 v50, 16, v33
	v_and_b32_e32 v33, 0xffff0000, v33
	v_lshlrev_b32_e32 v51, 16, v34
	v_and_b32_e32 v34, 0xffff0000, v34
	v_lshlrev_b32_e32 v52, 16, v35
	v_and_b32_e32 v35, 0xffff0000, v35
	s_waitcnt lgkmcnt(1)
	v_mul_f32_e32 v32, v37, v32
	v_mul_f32_e32 v33, v39, v33
	s_waitcnt lgkmcnt(0)
	v_mul_f32_e32 v34, v41, v34
	v_mul_f32_e32 v35, v43, v35
	v_mul_f32_e32 v36, v36, v49
	v_mul_f32_e32 v37, v38, v50
	v_mul_f32_e32 v38, v40, v51
	v_mul_f32_e32 v39, v42, v52
	v_cvt_pk_bf16_f32 v32, v36, v32
	v_cvt_pk_bf16_f32 v33, v37, v33
	v_cvt_pk_bf16_f32 v34, v38, v34
	v_cvt_pk_bf16_f32 v35, v39, v35
	global_store_dwordx4 v[54:55], v[32:35], off offset:64
	v_mul_f32_e32 v40, v16, v72
	v_mul_f32_e32 v41, v17, v73
	v_mul_f32_e32 v42, v18, v74
	v_mul_f32_e32 v43, v19, v75
	v_mul_f32_e32 v46, v20, v76
	v_mul_f32_e32 v47, v21, v77
	v_mul_f32_e32 v49, v22, v78
	v_mul_f32_e32 v50, v23, v79
	ds_read_b128 v[16:19], v48 offset:18432
	ds_read_b128 v[20:23], v48 offset:18448
	v_mov_b64_e32 v[36:37], v[64:65]
	v_mov_b64_e32 v[38:39], v[66:67]
	s_waitcnt vmcnt(7)
	v_mov_b32_e32 v32, v230
	v_mov_b32_e32 v33, v231
	v_mov_b32_e32 v34, v232
	v_mov_b32_e32 v35, v233
	v_lshlrev_b32_e32 v51, 16, v32
	v_and_b32_e32 v32, 0xffff0000, v32
	v_lshlrev_b32_e32 v52, 16, v33
	v_and_b32_e32 v33, 0xffff0000, v33
	v_lshlrev_b32_e32 v53, 16, v34
	v_and_b32_e32 v34, 0xffff0000, v34
	v_lshlrev_b32_e32 v54, 16, v35
	v_and_b32_e32 v35, 0xffff0000, v35
	s_waitcnt lgkmcnt(1)
	v_mul_f32_e32 v16, v16, v51
	v_mul_f32_e32 v17, v17, v32
	v_mul_f32_e32 v18, v18, v52
	v_mul_f32_e32 v19, v19, v33
	s_waitcnt lgkmcnt(0)
	v_mul_f32_e32 v20, v20, v53
	v_mul_f32_e32 v21, v21, v34
	v_mul_f32_e32 v22, v22, v54
	v_mul_f32_e32 v23, v23, v35
	v_cvt_pk_bf16_f32 v16, v16, v17
	v_cvt_pk_bf16_f32 v17, v18, v19
	v_cvt_pk_bf16_f32 v18, v20, v21
	v_cvt_pk_bf16_f32 v19, v22, v23
	global_store_dwordx4 v[44:45], v[16:19], off offset:64
	s_waitcnt lgkmcnt(0)
	ds_write2_b32 v88, v40, v41 offset1:32
	ds_write2_b32 v88, v42, v43 offset0:64 offset1:96
	ds_write2_b32 v89, v46, v47 offset1:32
	ds_write2_b32 v89, v49, v50 offset0:64 offset1:96
	ds_write2_b32 v90, v24, v25 offset1:32
	ds_write2_b32 v90, v26, v27 offset0:64 offset1:96
	ds_write2_b32 v91, v28, v29 offset1:32
	ds_write2_b32 v91, v30, v31 offset0:64 offset1:96
	s_waitcnt lgkmcnt(0)
	ds_read_b128 v[20:23], v48 offset:16384
	ds_read_b128 v[24:27], v48 offset:16400
	v_lshl_add_u64 v[28:29], v[36:37], 0, s[0:1]
	v_lshl_add_u64 v[30:31], v[38:39], 0, s[0:1]
	s_waitcnt vmcnt(7)
	v_mov_b32_e32 v16, v234
	v_mov_b32_e32 v17, v235
	v_mov_b32_e32 v18, v236
	v_mov_b32_e32 v19, v237
	v_lshlrev_b32_e32 v32, 16, v16
	v_and_b32_e32 v16, 0xffff0000, v16
	v_lshlrev_b32_e32 v33, 16, v17
	v_and_b32_e32 v17, 0xffff0000, v17
	v_lshlrev_b32_e32 v34, 16, v18
	v_and_b32_e32 v18, 0xffff0000, v18
	v_lshlrev_b32_e32 v35, 16, v19
	v_and_b32_e32 v19, 0xffff0000, v19
	s_waitcnt lgkmcnt(1)
	v_mul_f32_e32 v16, v21, v16
	v_mul_f32_e32 v17, v23, v17
	s_waitcnt lgkmcnt(0)
; #define LAS __attribute__((address_space(3)))
; __device__ __forceinline__ unsigned cvt_pk_bf16(float lo, float hi) { unsigned r; asm volatile("v_cvt_pk_bf16_f32 %0, %1, %2" : "=v"(r) : "v"(lo), "v"(hi)); return r; }
; __device__ __forceinline__ float bf_lo(unsigned w) { return __uint_as_float(w << 16); }
; __device__ __forceinline__ float bf_hi(unsigned w) { return __uint_as_float(w & 0xffff0000u); }
; __device__ __forceinline__ int crow(int r, int hi) { return (r & 3) + 8 * (r >> 2) + 4 * hi; }
; #define WAITV_BAR(N) asm volatile("s_waitcnt vmcnt(" #N ") lgkmcnt(0)\n\ts_barrier" ::: "memory")
; __device__ __forceinline__ void fox_block(const BlockRef& cur, const BlockRef& nxt, char* lds, Seam& S, const int tid) {
;     ...
;     for (int d0 = 0; d0 < 4; ++d0) {
; #pragma unroll
;         for (int r = 0; r < 16; ++r) stg[crow(r, hi) * 32 + r32] = o[d0][r] * rli[r];
;         asm volatile("s_waitcnt lgkmcnt(0)" ::: "memory");
;         gbf16* op = obase; const gbf16* zp = zbase;
; #pragma unroll
;         for (int i = 0; i < 2; ++i) {
;             asm volatile("" : "+v"(op), "+v"(zp));
;             const f32x4 v0 = *(const LAS f32x4*)(stg + (er + 16 * i) * 32 + 8 * eq), v1 = *(const LAS f32x4*)(stg + (er + 16 * i) * 32 + 8 * eq + 4);
;             const u32x4 z = __builtin_nontemporal_load((const gu32x4*)(zp + d0 * 32));
;             u32x4 w; w.x = cvt_pk_bf16(v0.x * bf_lo(z.x), v0.y * bf_hi(z.x)); w.y = cvt_pk_bf16(v0.z * bf_lo(z.y), v0.w * bf_hi(z.y));
;             w.z = cvt_pk_bf16(v1.x * bf_lo(z.z), v1.y * bf_hi(z.z)); w.w = cvt_pk_bf16(v1.z * bf_lo(z.w), v1.w * bf_hi(z.w));
;             *(gu32x4*)(op + d0 * 32) = w;
;             op += 16 * LD; zp += 16 * LD; }
;         asm volatile("s_waitcnt lgkmcnt(0)" ::: "memory"); }
;     WAITV_BAR(0);
; __device__ __forceinline__ void attn_phase(char* lds, const Tensors& T, int vcu, int G) {
;     for (int L = vcu; L < NB * NH * 8; L += G) {
	v_mul_f32_e32 v18, v25, v18
	v_mul_f32_e32 v19, v27, v19
	v_mul_f32_e32 v20, v20, v32
	v_mul_f32_e32 v21, v22, v33
	v_mul_f32_e32 v22, v24, v34
	v_mul_f32_e32 v23, v26, v35
	v_cvt_pk_bf16_f32 v16, v20, v16
	v_cvt_pk_bf16_f32 v17, v21, v17
	v_cvt_pk_bf16_f32 v18, v22, v18
	v_cvt_pk_bf16_f32 v19, v23, v19
	global_store_dwordx4 v[36:37], v[16:19], off offset:128
	v_mul_f32_e32 v20, v0, v72
	v_mul_f32_e32 v21, v1, v73
	v_mul_f32_e32 v22, v2, v74
	v_mul_f32_e32 v23, v3, v75
	v_mul_f32_e32 v24, v4, v76
	v_mul_f32_e32 v25, v5, v77
	v_mul_f32_e32 v26, v6, v78
	v_mul_f32_e32 v27, v7, v79
	ds_read_b128 v[0:3], v48 offset:18432
	ds_read_b128 v[4:7], v48 offset:18448
	s_waitcnt vmcnt(7)
	v_mov_b32_e32 v16, v238
	v_mov_b32_e32 v17, v239
	v_mov_b32_e32 v18, v240
	v_mov_b32_e32 v19, v241
	v_lshlrev_b32_e32 v30, 16, v16
	v_and_b32_e32 v16, 0xffff0000, v16
	v_lshlrev_b32_e32 v31, 16, v17
	v_and_b32_e32 v17, 0xffff0000, v17
	v_lshlrev_b32_e32 v32, 16, v18
	v_and_b32_e32 v18, 0xffff0000, v18
	v_lshlrev_b32_e32 v33, 16, v19
	v_and_b32_e32 v19, 0xffff0000, v19
	s_waitcnt lgkmcnt(1)
	v_mul_f32_e32 v0, v0, v30
	v_mul_f32_e32 v1, v1, v16
	v_mul_f32_e32 v2, v2, v31
	v_mul_f32_e32 v3, v3, v17
	s_waitcnt lgkmcnt(0)
	v_mul_f32_e32 v4, v4, v32
	v_mul_f32_e32 v5, v5, v18
	v_mul_f32_e32 v6, v6, v33
	v_mul_f32_e32 v7, v7, v19
	v_cvt_pk_bf16_f32 v0, v0, v1
	v_cvt_pk_bf16_f32 v1, v2, v3
	v_cvt_pk_bf16_f32 v2, v4, v5
	v_cvt_pk_bf16_f32 v3, v6, v7
	global_store_dwordx4 v[28:29], v[0:3], off offset:128
	s_waitcnt lgkmcnt(0)
	ds_write2_b32 v88, v20, v21 offset1:32
	ds_write2_b32 v88, v22, v23 offset0:64 offset1:96
	ds_write2_b32 v89, v24, v25 offset1:32
	ds_write2_b32 v89, v26, v27 offset0:64 offset1:96
	ds_write2_b32 v90, v8, v9 offset1:32
	ds_write2_b32 v90, v10, v11 offset0:64 offset1:96
	ds_write2_b32 v91, v12, v13 offset1:32
	ds_write2_b32 v91, v14, v15 offset0:64 offset1:96
	s_waitcnt lgkmcnt(0)
	ds_read_b128 v[4:7], v48 offset:16384
	ds_read_b128 v[8:11], v48 offset:16400
	v_lshl_add_u64 v[12:13], v[64:65], 0, s[0:1]
	v_lshl_add_u64 v[14:15], v[66:67], 0, s[0:1]
	v_readlane_b32 s0, v248, 61
	v_readlane_b32 s1, v248, 62
	s_add_i32 s0, s0, s1
	s_cmpk_lt_i32 s60, 0x100
	v_writelane_b32 v248, s0, 61
	s_waitcnt vmcnt(7)
	v_mov_b32_e32 v0, v242
	v_mov_b32_e32 v1, v243
	v_mov_b32_e32 v2, v244
	v_mov_b32_e32 v3, v245
	v_lshlrev_b32_e32 v16, 16, v0
	v_and_b32_e32 v0, 0xffff0000, v0
	v_lshlrev_b32_e32 v17, 16, v1
	v_and_b32_e32 v1, 0xffff0000, v1
	v_lshlrev_b32_e32 v18, 16, v2
	v_and_b32_e32 v2, 0xffff0000, v2
	v_lshlrev_b32_e32 v19, 16, v3
	v_and_b32_e32 v3, 0xffff0000, v3
	s_waitcnt lgkmcnt(1)
	v_mul_f32_e32 v0, v5, v0
	v_mul_f32_e32 v1, v7, v1
	s_waitcnt lgkmcnt(0)
	v_mul_f32_e32 v2, v9, v2
	v_mul_f32_e32 v3, v11, v3
	v_mul_f32_e32 v4, v4, v16
	v_mul_f32_e32 v5, v6, v17
	v_mul_f32_e32 v6, v8, v18
	v_mul_f32_e32 v7, v10, v19
	v_cvt_pk_bf16_f32 v0, v4, v0
	v_cvt_pk_bf16_f32 v1, v5, v1
	v_cvt_pk_bf16_f32 v2, v6, v2
	v_cvt_pk_bf16_f32 v3, v7, v3
	global_store_dwordx4 v[64:65], v[0:3], off offset:192
	ds_read_b128 v[4:7], v48 offset:18432
	ds_read_b128 v[8:11], v48 offset:18448
	s_waitcnt vmcnt(6)
	v_mov_b32_e32 v0, v222
	v_mov_b32_e32 v1, v223
	v_mov_b32_e32 v2, v224
	v_mov_b32_e32 v3, v225
	v_lshlrev_b32_e32 v14, 16, v0
	v_and_b32_e32 v0, 0xffff0000, v0
	v_lshlrev_b32_e32 v15, 16, v1
	v_and_b32_e32 v1, 0xffff0000, v1
	v_lshlrev_b32_e32 v16, 16, v2
	v_and_b32_e32 v2, 0xffff0000, v2
	v_lshlrev_b32_e32 v17, 16, v3
	v_and_b32_e32 v3, 0xffff0000, v3
	s_waitcnt lgkmcnt(1)
	v_mul_f32_e32 v0, v5, v0
	v_mul_f32_e32 v1, v7, v1
	s_waitcnt lgkmcnt(0)
	v_mul_f32_e32 v2, v9, v2
	v_mul_f32_e32 v3, v11, v3
	v_mul_f32_e32 v4, v4, v14
	v_mul_f32_e32 v5, v6, v15
	v_mul_f32_e32 v6, v8, v16
	v_mul_f32_e32 v7, v10, v17
	v_cvt_pk_bf16_f32 v0, v4, v0
	v_cvt_pk_bf16_f32 v1, v5, v1
	v_cvt_pk_bf16_f32 v2, v6, v2
	v_cvt_pk_bf16_f32 v3, v7, v3
	global_store_dwordx4 v[12:13], v[0:3], off offset:192
	s_waitcnt lgkmcnt(0)
	s_waitcnt vmcnt(0) lgkmcnt(0)
	s_barrier
	s_cbranch_scc0 .LBB0_590

; #define LAS __attribute__((address_space(3)))
; __device__ __forceinline__ void finishSM(f32x16& p0, f32x16& p1, float alpha, float& l_reg, bf16x8& pa0, bf16x8& pa1, bf16x8& pa2, bf16x8& pa3) {
; #pragma unroll
;     for (int r = 0; r < 16; ++r) p1[r] = __builtin_amdgcn_exp2f(p1[r]);
;     float ps = 0;
; #pragma unroll
;     for (int r = 0; r < 16; ++r) ps += p0[r];
; #pragma unroll
;     for (int r = 0; r < 16; ++r) ps += p1[r];
;     { auto rr = __builtin_amdgcn_permlane32_swap(__float_as_uint(ps), __float_as_uint(ps), false, false);
;       ps = __uint_as_float(rr[0]) + __uint_as_float(rr[1]); }
;     l_reg = l_reg * alpha + ps;
;     ...
;     PK4(p0, 0, pa0); PK4(p0, 8, pa1); PK4(p1, 0, pa2); PK4(p1, 8, pa3);
;     ...
; }
; __device__ __forceinline__ void qkt(f32x16& p0, f32x16& p1, const char* Kslot, int r32, int hi, const bf16x8* qr, const LAS f32x4* cp) {
; #pragma unroll
;     for (int g = 0; g < 4; ++g) { const f32x4 c0 = cp[2 * g], c1 = cp[8 + 2 * g];
; #pragma unroll
;         for (int j = 0; j < 4; ++j) { p0[4 * g + j] = c0[j]; p1[4 * g + j] = c1[j]; } }
;     const char* kb[4];
; #pragma unroll
;     for (int dd = 0; dd < 4; ++dd) kb[dd] = Kslot + KSWZ(r32, (dd * 16 + hi * 8) * 2);
; #pragma unroll
;     for (int d0 = 0; d0 < 8; ++d0) { const char* a = kb[d0 & 3] + (d0 >> 2) * 128;
;         bf16x8 b0 = *reinterpret_cast<const bf16x8*>(a);
;         bf16x8 b1 = *reinterpret_cast<const bf16x8*>(a + 32 * 256);
;         p0 = __builtin_amdgcn_mfma_f32_32x32x16_bf16(b0, qr[d0], p0, 0, 0, 0);
;         p1 = __builtin_amdgcn_mfma_f32_32x32x16_bf16(b1, qr[d0], p1, 0, 0, 0); }
.LBB0_523:
	s_add_i32 s3, s70, s76
	v_lshl_add_u64 v[160:161], s[68:69], 0, v[150:151]
	v_lshl_add_u64 v[64:65], v[160:161], 0, s[84:85]
	s_mov_b32 m0, s3
	v_lshl_add_u64 v[162:163], s[68:69], 0, v[152:153]
	global_load_lds_dwordx4 v[64:65], off
	v_lshl_add_u64 v[64:65], v[162:163], 0, s[84:85]
	s_add_i32 m0, s3, 0x400
	s_nop 0
	global_load_lds_dwordx4 v[64:65], off
	s_add_i32 s3, s73, 0
	v_add_u32_e32 v218, s3, v193
	ds_read_b128 v[80:83], v217
	ds_read_b128 v[84:87], v217 offset:32
	ds_read_b128 v[64:67], v217 offset:128
	ds_read_b128 v[68:71], v217 offset:160
	ds_read_b128 v[88:91], v217 offset:64
	ds_read_b128 v[72:75], v217 offset:192
	ds_read_b128 v[92:95], v217 offset:96
	ds_read_b128 v[76:79], v217 offset:224
	ds_read_b128 v[238:241], v218 offset:49152
	ds_read_b128 v[242:245], v218 offset:57344
	v_add_u32_e32 v219, s3, v194
	v_add_u32_e32 v220, s3, v195
	s_waitcnt lgkmcnt(0)
	v_mfma_f32_32x32x16_bf16 v[80:95], v[238:241], v[96:99], v[80:95]
	v_add_u32_e32 v237, s3, v196
	v_exp_f32_e32 v173, v173
	v_exp_f32_e32 v176, v176
	v_exp_f32_e32 v177, v177
	v_exp_f32_e32 v178, v178
	v_exp_f32_e32 v179, v179
	v_exp_f32_e32 v246, v165
	v_mfma_f32_32x32x16_bf16 v[64:79], v[242:245], v[96:99], v[64:79]
	ds_read_b128 v[238:241], v219 offset:49152
	ds_read_b128 v[242:245], v219 offset:57344
	s_waitcnt lgkmcnt(0)
	v_mfma_f32_32x32x16_bf16 v[64:79], v[242:245], v[100:103], v[64:79]
	v_mfma_f32_32x32x16_bf16 v[80:95], v[238:241], v[100:103], v[80:95]
	ds_read_b128 v[238:241], v220 offset:49152
	ds_read_b128 v[242:245], v220 offset:57344
	s_waitcnt lgkmcnt(0)
	v_mfma_f32_32x32x16_bf16 v[64:79], v[242:245], v[104:107], v[64:79]
	v_mfma_f32_32x32x16_bf16 v[80:95], v[238:241], v[104:107], v[80:95]
	ds_read_b128 v[238:241], v237 offset:49152
	ds_read_b128 v[242:245], v237 offset:57344
	s_waitcnt lgkmcnt(0)
	v_mfma_f32_32x32x16_bf16 v[64:79], v[242:245], v[108:111], v[64:79]
	v_mfma_f32_32x32x16_bf16 v[80:95], v[238:241], v[108:111], v[80:95]
	v_xor_b32_e32 v249, 0x80, v218
	v_xor_b32_e32 v250, 0x80, v219
	v_xor_b32_e32 v251, 0x80, v220
	v_xor_b32_e32 v252, 0x80, v237
	ds_read_b128 v[238:241], v249 offset:49152
	ds_read_b128 v[242:245], v249 offset:57344
	s_waitcnt lgkmcnt(0)
	v_mfma_f32_32x32x16_bf16 v[64:79], v[242:245], v[112:115], v[64:79]
	v_mfma_f32_32x32x16_bf16 v[80:95], v[238:241], v[112:115], v[80:95]
	ds_read_b128 v[238:241], v250 offset:49152
	ds_read_b128 v[242:245], v250 offset:57344
	s_waitcnt lgkmcnt(0)
	v_mfma_f32_32x32x16_bf16 v[64:79], v[242:245], v[116:119], v[64:79]
	v_mfma_f32_32x32x16_bf16 v[80:95], v[238:241], v[116:119], v[80:95]
	ds_read_b128 v[238:241], v251 offset:49152
	ds_read_b128 v[242:245], v251 offset:57344
	v_exp_f32_e32 v220, v168
	s_waitcnt lgkmcnt(0)
	v_mfma_f32_32x32x16_bf16 v[64:79], v[242:245], v[120:123], v[64:79]
	v_mfma_f32_32x32x16_bf16 v[80:95], v[238:241], v[120:123], v[80:95]
	ds_read_b128 v[238:241], v252 offset:49152
	ds_read_b128 v[242:245], v252 offset:57344
	v_exp_f32_e32 v237, v169
	s_waitcnt lgkmcnt(0)
	v_mfma_f32_32x32x16_bf16 v[64:79], v[242:245], v[124:127], v[64:79]
	v_exp_f32_e32 v245, v164
	v_add_f32_e32 v164, 0, v221
	v_add_f32_e32 v164, v236, v164
	v_add_f32_e32 v164, v233, v164
	v_add_f32_e32 v164, v235, v164
	v_add_f32_e32 v164, v231, v164
	v_add_f32_e32 v164, v234, v164
	v_add_f32_e32 v164, v230, v164
	v_add_f32_e32 v164, v232, v164
	v_add_f32_e32 v164, v227, v164
	v_add_f32_e32 v164, v229, v164
	v_add_f32_e32 v164, v225, v164
	v_add_f32_e32 v164, v228, v164
	v_add_f32_e32 v164, v223, v164
	v_add_f32_e32 v164, v226, v164
	v_mfma_f32_32x32x16_bf16 v[80:95], v[238:241], v[124:127], v[80:95]
	v_exp_f32_e32 v238, v172
	v_add_f32_e32 v164, v222, v164
	v_add_f32_e32 v164, v224, v164
	v_add_f32_e32 v164, v220, v164
	v_add_f32_e32 v164, v237, v164
	v_exp_f32_e32 v239, v166
	v_add_f32_e32 v164, v238, v164
	v_exp_f32_e32 v240, v167
	v_add_f32_e32 v164, v173, v164
	v_exp_f32_e32 v241, v170
	v_add_f32_e32 v164, v176, v164
	v_exp_f32_e32 v242, v171
	v_add_f32_e32 v164, v177, v164
	v_exp_f32_e32 v243, v174
	v_add_f32_e32 v164, v239, v164
	v_exp_f32_e32 v244, v175
	v_add_f32_e32 v164, v240, v164
	v_add_f32_e32 v164, v241, v164
	v_add_f32_e32 v164, v242, v164
	v_add_f32_e32 v164, v243, v164
	v_add_f32_e32 v164, v244, v164
	v_add_f32_e32 v164, v178, v164
	v_add_f32_e32 v164, v179, v164
	v_add_f32_e32 v164, v245, v164
	v_add_f32_e32 v218, v246, v164
	v_mov_b32_e32 v219, v218
	s_nop 1
	v_permlane32_swap_b32_e32 v218, v219
	v_cvt_pk_bf16_f32 v164, v221, v236
	v_cvt_pk_bf16_f32 v165, v233, v235
	v_cvt_pk_bf16_f32 v166, v231, v234
	v_cvt_pk_bf16_f32 v167, v230, v232
	v_cvt_pk_bf16_f32 v168, v227, v229
	v_cvt_pk_bf16_f32 v169, v225, v228
	v_cvt_pk_bf16_f32 v170, v223, v226
	v_cvt_pk_bf16_f32 v171, v222, v224
	v_cvt_pk_bf16_f32 v172, v220, v237
	v_cvt_pk_bf16_f32 v173, v238, v173
	v_cvt_pk_bf16_f32 v174, v176, v177
	v_cvt_pk_bf16_f32 v175, v239, v240
	v_cvt_pk_bf16_f32 v176, v241, v242
	v_cvt_pk_bf16_f32 v177, v243, v244
	v_cvt_pk_bf16_f32 v178, v178, v179
	v_cvt_pk_bf16_f32 v179, v245, v246
	s_nop 0
	v_permlane32_swap_b32_e32 v164, v166
	v_permlane32_swap_b32_e32 v165, v167
	v_permlane32_swap_b32_e32 v168, v170
	v_permlane32_swap_b32_e32 v169, v171
	v_permlane32_swap_b32_e32 v172, v174
	v_permlane32_swap_b32_e32 v173, v175
	v_permlane32_swap_b32_e32 v176, v178
	v_permlane32_swap_b32_e32 v177, v179
	v_add_u32_e32 v236, s2, v192
	s_sub_i32 s2, s92, 64
	s_cmp_le_i32 s2, s91
	s_cbranch_scc0 .Lband_0
; #define SBAR() __builtin_amdgcn_sched_barrier(0)
; #define PV_RD(d0, kh, X) do { constexpr int b_ = v_rd_off(d0, 2 * (kh), 0); TRRD(X##l0, b_); TRRD(X##h0, b_ + 2048); TRRD(X##l1, b_ + 4096); TRRD(X##h1, b_ + 6144); } while (0)
; #define PV_MM(d0, X, PA, PB) do { \
;         o[d0] = __builtin_amdgcn_mfma_f32_32x32x16_bf16(PA, (bf16x8){X##l0[0], X##l0[1], X##l0[2], X##l0[3], X##h0[0], X##h0[1], X##h0[2], X##h0[3]}, o[d0], 0, 0, 0);   \
;         o[d0] = __builtin_amdgcn_mfma_f32_32x32x16_bf16(PB, (bf16x8){X##l1[0], X##l1[1], X##l1[2], X##l1[3], X##h1[0], X##h1[1], X##h1[2], X##h1[3]}, o[d0], 0, 0, 0); } while (0)
; #define PV_W4() do { asm volatile("s_waitcnt lgkmcnt(4)" ::: "memory"); SBAR(); } while (0)
; #define PV_W0() do { asm volatile("s_waitcnt lgkmcnt(0)" ::: "memory"); SBAR(); } while (0)
; __device__ __forceinline__ void partialSM(f32x16& p0, f32x16& p1, float& m_reg, float& mn, float& alpha) {
;     float pmax = p0[0];
; #pragma unroll
;     for (int r = 1; r < 16; ++r) pmax = fmaxf(pmax, p0[r]);
; #pragma unroll
;     for (int r = 0; r < 16; ++r) pmax = fmaxf(pmax, p1[r]);
;     { auto rr = __builtin_amdgcn_permlane32_swap(__float_as_uint(pmax), __float_as_uint(pmax), false, false);
;       pmax = fmaxf(__uint_as_float(rr[0]), __uint_as_float(rr[1])); }
;     if (__builtin_expect(__all((pmax - m_reg) <= THR2), 1)) { mn = m_reg; alpha = 1.f; }
;     else { mn = fmaxf(m_reg, pmax); alpha = __builtin_amdgcn_exp2f(m_reg - mn); m_reg = mn; }
; __device__ __forceinline__ void pv_tile(f32x16* o, int vb0, bf16x8 pa0, bf16x8 pa1, bf16x8 pa2, bf16x8 pa3) {
;     ...
;     s16x4 al0, al1, ah0, ah1, bl0, bl1, bh0, bh1;
;     PV_RD(0, 0, a);
;     PV_RD(0, 1, b); PV_W4(); PV_MM(0, a, pa0, pa1); SBAR();
;     PV_RD(1, 0, a); PV_W4(); PV_MM(0, b, pa2, pa3); SBAR();
;     PV_RD(1, 1, b); PV_W4(); PV_MM(1, a, pa0, pa1); SBAR();
;     PV_RD(2, 0, a); PV_W4(); PV_MM(1, b, pa2, pa3); SBAR();
;     PV_RD(2, 1, b); PV_W4(); PV_MM(2, a, pa0, pa1); SBAR();
;     PV_RD(3, 0, a); PV_W4(); PV_MM(2, b, pa2, pa3); SBAR();
;     PV_RD(3, 1, b); PV_W4(); PV_MM(3, a, pa0, pa1); SBAR();
;     PV_W0(); PV_MM(3, b, pa2, pa3);
	ds_read_b64_tr_b16 v[220:221], v236 offset:0
	ds_read_b64_tr_b16 v[222:223], v236 offset:0x800
	ds_read_b64_tr_b16 v[224:225], v236 offset:0x1000
	ds_read_b64_tr_b16 v[226:227], v236 offset:0x1800
	ds_read_b64_tr_b16 v[228:229], v236 offset:0x2000
	ds_read_b64_tr_b16 v[230:231], v236 offset:0x2800
	ds_read_b64_tr_b16 v[232:233], v236 offset:0x3000
	ds_read_b64_tr_b16 v[234:235], v236 offset:0x3800
	s_waitcnt lgkmcnt(4)
	s_nop 0
	v_mfma_f32_32x32x16_bf16 v[48:63], v[164:167], v[220:223], v[48:63]
	v_max_f32_e32 v253, v81, v81
	v_max_f32_e32 v254, v80, v80
	v_mfma_f32_32x32x16_bf16 v[48:63], v[168:171], v[224:227], v[48:63]
	v_max_f32_e32 v253, v254, v253
	v_max3_f32 v253, v253, v82, v83
	ds_read_b64_tr_b16 v[220:221], v236 offset:0x200
	ds_read_b64_tr_b16 v[222:223], v236 offset:0xa00
	ds_read_b64_tr_b16 v[224:225], v236 offset:0x1200
	ds_read_b64_tr_b16 v[226:227], v236 offset:0x1a00
	s_waitcnt lgkmcnt(4)
	v_mfma_f32_32x32x16_bf16 v[48:63], v[172:175], v[228:231], v[48:63]
	v_max3_f32 v253, v253, v84, v85
	v_max3_f32 v253, v253, v86, v87
	v_mfma_f32_32x32x16_bf16 v[48:63], v[176:179], v[232:235], v[48:63]
	v_max3_f32 v253, v253, v88, v89
	v_max3_f32 v253, v253, v90, v91
	ds_read_b64_tr_b16 v[228:229], v236 offset:0x2200
	ds_read_b64_tr_b16 v[230:231], v236 offset:0x2a00
	ds_read_b64_tr_b16 v[232:233], v236 offset:0x3200
	ds_read_b64_tr_b16 v[234:235], v236 offset:0x3a00
	s_waitcnt lgkmcnt(4)
	v_mfma_f32_32x32x16_bf16 v[32:47], v[164:167], v[220:223], v[32:47]
	v_max3_f32 v253, v253, v92, v93
	v_max3_f32 v253, v253, v94, v95
	v_mfma_f32_32x32x16_bf16 v[32:47], v[168:171], v[224:227], v[32:47]
	v_max3_f32 v253, v253, v64, v65
	v_max3_f32 v253, v253, v66, v67
	ds_read_b64_tr_b16 v[220:221], v236 offset:0x400
	ds_read_b64_tr_b16 v[222:223], v236 offset:0xc00
	ds_read_b64_tr_b16 v[224:225], v236 offset:0x1400
	ds_read_b64_tr_b16 v[226:227], v236 offset:0x1c00
	s_waitcnt lgkmcnt(4)
	v_mfma_f32_32x32x16_bf16 v[32:47], v[172:175], v[228:231], v[32:47]
	v_max3_f32 v253, v253, v68, v69
	v_max3_f32 v253, v253, v70, v71
	v_mfma_f32_32x32x16_bf16 v[32:47], v[176:179], v[232:235], v[32:47]
	v_max3_f32 v253, v253, v72, v73
	v_max3_f32 v253, v253, v74, v75
	ds_read_b64_tr_b16 v[228:229], v236 offset:0x2400
	ds_read_b64_tr_b16 v[230:231], v236 offset:0x2c00
	ds_read_b64_tr_b16 v[232:233], v236 offset:0x3400
	ds_read_b64_tr_b16 v[234:235], v236 offset:0x3c00
	s_waitcnt lgkmcnt(4)
	v_mfma_f32_32x32x16_bf16 v[16:31], v[164:167], v[220:223], v[16:31]
	v_max3_f32 v253, v253, v76, v77
	v_max3_f32 v253, v253, v78, v79
	v_mfma_f32_32x32x16_bf16 v[16:31], v[168:171], v[224:227], v[16:31]
	v_mov_b32_e32 v254, v253
	s_nop 1
	ds_read_b64_tr_b16 v[220:221], v236 offset:0x600
	ds_read_b64_tr_b16 v[222:223], v236 offset:0xe00
	ds_read_b64_tr_b16 v[224:225], v236 offset:0x1600
	ds_read_b64_tr_b16 v[226:227], v236 offset:0x1e00
	s_waitcnt lgkmcnt(4)
	v_mfma_f32_32x32x16_bf16 v[16:31], v[172:175], v[228:231], v[16:31]
	v_permlane32_swap_b32_e32 v253, v254
	v_max_f32_e32 v254, v254, v254
	v_mfma_f32_32x32x16_bf16 v[16:31], v[176:179], v[232:235], v[16:31]
	v_max_f32_e32 v253, v253, v253
	v_max_f32_e32 v253, v253, v254
	ds_read_b64_tr_b16 v[228:229], v236 offset:0x2600
	ds_read_b64_tr_b16 v[230:231], v236 offset:0x2e00
	ds_read_b64_tr_b16 v[232:233], v236 offset:0x3600
	ds_read_b64_tr_b16 v[234:235], v236 offset:0x3e00
	s_waitcnt lgkmcnt(4)
	v_mfma_f32_32x32x16_bf16 v[0:15], v[164:167], v[220:223], v[0:15]
	v_sub_f32_e32 v254, v253, v154
	v_cmp_ge_f32_e32 vcc, s33, v254
	v_mfma_f32_32x32x16_bf16 v[0:15], v[168:171], v[224:227], v[0:15]
	v_max_f32_e32 v254, v154, v154
	v_max_f32_e32 v253, v254, v253
	s_waitcnt lgkmcnt(0)
	v_mfma_f32_32x32x16_bf16 v[0:15], v[172:175], v[228:231], v[0:15]
	v_sub_f32_e32 v254, v154, v253
	v_exp_f32_e32 v254, v254
	v_mfma_f32_32x32x16_bf16 v[0:15], v[176:179], v[232:235], v[0:15]
	v_mov_b32_e32 v164, v253
	v_mov_b32_e32 v165, v254
	s_branch .Lmaxtail_0
; #define SBAR() __builtin_amdgcn_sched_barrier(0)
; #define PV_RD(d0, kh, X) do { constexpr int b_ = v_rd_off(d0, 2 * (kh), 0); TRRD(X##l0, b_); TRRD(X##h0, b_ + 2048); TRRD(X##l1, b_ + 4096); TRRD(X##h1, b_ + 6144); } while (0)
; #define PV_MM(d0, X, PA, PB) do { \
;         o[d0] = __builtin_amdgcn_mfma_f32_32x32x16_bf16(PA, (bf16x8){X##l0[0], X##l0[1], X##l0[2], X##l0[3], X##h0[0], X##h0[1], X##h0[2], X##h0[3]}, o[d0], 0, 0, 0);   \
;         o[d0] = __builtin_amdgcn_mfma_f32_32x32x16_bf16(PB, (bf16x8){X##l1[0], X##l1[1], X##l1[2], X##l1[3], X##h1[0], X##h1[1], X##h1[2], X##h1[3]}, o[d0], 0, 0, 0); } while (0)
; #define PV_W4() do { asm volatile("s_waitcnt lgkmcnt(4)" ::: "memory"); SBAR(); } while (0)
; #define PV_W0() do { asm volatile("s_waitcnt lgkmcnt(0)" ::: "memory"); SBAR(); } while (0)
; __device__ __forceinline__ void mask_tile(f32x16& p0, f32x16& p1, int dq) {
;     const float NEG = -__builtin_inff();
; #pragma unroll
;     for (int r = 0; r < 16; ++r) { const int c = (r & 3) + 8 * (r >> 2); if (dq - c < 0) p0[r] = NEG; if (dq - c - 32 < 0) p1[r] = NEG; }
; }
; __device__ __forceinline__ void pv_tile(f32x16* o, int vb0, bf16x8 pa0, bf16x8 pa1, bf16x8 pa2, bf16x8 pa3) {
;     ...
;     s16x4 al0, al1, ah0, ah1, bl0, bl1, bh0, bh1;
;     PV_RD(0, 0, a);
;     PV_RD(0, 1, b); PV_W4(); PV_MM(0, a, pa0, pa1); SBAR();
;     PV_RD(1, 0, a); PV_W4(); PV_MM(0, b, pa2, pa3); SBAR();
;     PV_RD(1, 1, b); PV_W4(); PV_MM(1, a, pa0, pa1); SBAR();
;     PV_RD(2, 0, a); PV_W4(); PV_MM(1, b, pa2, pa3); SBAR();
;     PV_RD(2, 1, b); PV_W4(); PV_MM(2, a, pa0, pa1); SBAR();
;     PV_RD(3, 0, a); PV_W4(); PV_MM(2, b, pa2, pa3); SBAR();
;     PV_RD(3, 1, b); PV_W4(); PV_MM(3, a, pa0, pa1); SBAR();
;     PV_W0(); PV_MM(3, b, pa2, pa3);
.Lband_0:
	ds_read_b64_tr_b16 v[220:221], v236 offset:0
	ds_read_b64_tr_b16 v[222:223], v236 offset:0x800
	ds_read_b64_tr_b16 v[224:225], v236 offset:0x1000
	ds_read_b64_tr_b16 v[226:227], v236 offset:0x1800
	ds_read_b64_tr_b16 v[228:229], v236 offset:0x2000
	ds_read_b64_tr_b16 v[230:231], v236 offset:0x2800
	ds_read_b64_tr_b16 v[232:233], v236 offset:0x3000
	ds_read_b64_tr_b16 v[234:235], v236 offset:0x3800
	s_waitcnt lgkmcnt(4)
	s_nop 0
	v_mfma_f32_32x32x16_bf16 v[48:63], v[164:167], v[220:223], v[48:63]
	v_mfma_f32_32x32x16_bf16 v[48:63], v[168:171], v[224:227], v[48:63]
	ds_read_b64_tr_b16 v[220:221], v236 offset:0x200
	ds_read_b64_tr_b16 v[222:223], v236 offset:0xa00
	ds_read_b64_tr_b16 v[224:225], v236 offset:0x1200
	ds_read_b64_tr_b16 v[226:227], v236 offset:0x1a00
	s_waitcnt lgkmcnt(4)
	v_mfma_f32_32x32x16_bf16 v[48:63], v[172:175], v[228:231], v[48:63]
	v_mfma_f32_32x32x16_bf16 v[48:63], v[176:179], v[232:235], v[48:63]
	ds_read_b64_tr_b16 v[228:229], v236 offset:0x2200
	ds_read_b64_tr_b16 v[230:231], v236 offset:0x2a00
	ds_read_b64_tr_b16 v[232:233], v236 offset:0x3200
	ds_read_b64_tr_b16 v[234:235], v236 offset:0x3a00
	s_waitcnt lgkmcnt(4)
	v_mfma_f32_32x32x16_bf16 v[32:47], v[164:167], v[220:223], v[32:47]
	v_mfma_f32_32x32x16_bf16 v[32:47], v[168:171], v[224:227], v[32:47]
	ds_read_b64_tr_b16 v[220:221], v236 offset:0x400
	ds_read_b64_tr_b16 v[222:223], v236 offset:0xc00
	ds_read_b64_tr_b16 v[224:225], v236 offset:0x1400
	ds_read_b64_tr_b16 v[226:227], v236 offset:0x1c00
	s_waitcnt lgkmcnt(4)
	v_mfma_f32_32x32x16_bf16 v[32:47], v[172:175], v[228:231], v[32:47]
	v_mfma_f32_32x32x16_bf16 v[32:47], v[176:179], v[232:235], v[32:47]
	ds_read_b64_tr_b16 v[228:229], v236 offset:0x2400
	ds_read_b64_tr_b16 v[230:231], v236 offset:0x2c00
	ds_read_b64_tr_b16 v[232:233], v236 offset:0x3400
	ds_read_b64_tr_b16 v[234:235], v236 offset:0x3c00
	s_waitcnt lgkmcnt(4)
	v_mfma_f32_32x32x16_bf16 v[16:31], v[164:167], v[220:223], v[16:31]
	v_mfma_f32_32x32x16_bf16 v[16:31], v[168:171], v[224:227], v[16:31]
	ds_read_b64_tr_b16 v[220:221], v236 offset:0x600
	ds_read_b64_tr_b16 v[222:223], v236 offset:0xe00
	ds_read_b64_tr_b16 v[224:225], v236 offset:0x1600
	ds_read_b64_tr_b16 v[226:227], v236 offset:0x1e00
	s_waitcnt lgkmcnt(4)
	v_mfma_f32_32x32x16_bf16 v[16:31], v[172:175], v[228:231], v[16:31]
	v_mfma_f32_32x32x16_bf16 v[16:31], v[176:179], v[232:235], v[16:31]
	ds_read_b64_tr_b16 v[228:229], v236 offset:0x2600
	ds_read_b64_tr_b16 v[230:231], v236 offset:0x2e00
	ds_read_b64_tr_b16 v[232:233], v236 offset:0x3600
	ds_read_b64_tr_b16 v[234:235], v236 offset:0x3e00
	s_waitcnt lgkmcnt(4)
	v_mfma_f32_32x32x16_bf16 v[0:15], v[164:167], v[220:223], v[0:15]
	v_mfma_f32_32x32x16_bf16 v[0:15], v[168:171], v[224:227], v[0:15]
	s_waitcnt lgkmcnt(0)
	v_mfma_f32_32x32x16_bf16 v[0:15], v[172:175], v[228:231], v[0:15]
	s_sub_i32 s2, s92, 64
	s_cmp_le_i32 s2, s91
	v_mfma_f32_32x32x16_bf16 v[0:15], v[176:179], v[232:235], v[0:15]
	s_cbranch_scc1 .LBB0_525
	v_cmp_gt_i32_e64 s[62:63], 26, v216
	v_cmp_gt_i32_e64 s[64:65], 27, v216
	v_cmp_gt_i32_e64 s[60:61], 25, v216
	s_and_b64 s[62:63], s[64:65], s[62:63]
	v_cmp_gt_i32_e64 s[58:59], 24, v216
	s_and_b64 s[60:61], s[62:63], s[60:61]
	v_cmp_gt_i32_e64 s[56:57], 19, v216
	s_and_b64 s[58:59], s[60:61], s[58:59]
	v_cmp_gt_i32_e64 s[54:55], 18, v216
	s_and_b64 s[56:57], s[58:59], s[56:57]
	v_cmp_gt_i32_e64 s[52:53], 17, v216
	s_and_b64 s[54:55], s[56:57], s[54:55]
	v_cmp_gt_i32_e64 s[50:51], 16, v216
	s_and_b64 s[52:53], s[54:55], s[52:53]
	v_cmp_gt_i32_e64 s[48:49], 11, v216
	s_and_b64 s[50:51], s[52:53], s[50:51]
	v_cmp_gt_i32_e64 s[46:47], 10, v216
	s_and_b64 s[48:49], s[50:51], s[48:49]
	v_cmp_gt_i32_e64 s[44:45], 9, v216
	s_and_b64 s[46:47], s[48:49], s[46:47]
	v_cmp_gt_i32_e64 s[42:43], 8, v216
	s_and_b64 s[44:45], s[46:47], s[44:45]
	v_cmp_gt_i32_e64 s[40:41], 3, v216
	s_and_b64 s[42:43], s[44:45], s[42:43]
	v_cmp_gt_i32_e64 s[38:39], 2, v216
	s_and_b64 s[40:41], s[42:43], s[40:41]
	v_cmp_gt_i32_e64 s[36:37], 1, v216
	s_and_b64 s[38:39], s[40:41], s[38:39]
	v_cmp_gt_i32_e64 s[34:35], 0, v216
	s_and_b64 s[36:37], s[38:39], s[36:37]
	s_and_b64 s[34:35], s[36:37], s[34:35]
	v_cmp_gt_i32_e64 s[28:29], 58, v216
	v_cndmask_b32_e64 v80, v80, v130, s[34:35]
	v_cmp_gt_i32_e64 s[34:35], 59, v216
	v_cmp_gt_i32_e64 s[26:27], 57, v216
	s_and_b64 s[28:29], s[34:35], s[28:29]
	v_cmp_gt_i32_e64 s[24:25], 56, v216
	s_and_b64 s[26:27], s[28:29], s[26:27]
	v_cmp_gt_i32_e64 s[22:23], 51, v216
	s_and_b64 s[24:25], s[26:27], s[24:25]
	v_cmp_gt_i32_e64 s[20:21], 50, v216
	s_and_b64 s[22:23], s[24:25], s[22:23]
	v_cmp_gt_i32_e64 s[18:19], 49, v216
	s_and_b64 s[20:21], s[22:23], s[20:21]
	v_cmp_gt_i32_e64 s[16:17], 48, v216
	s_and_b64 s[18:19], s[20:21], s[18:19]
	v_cmp_gt_i32_e64 s[14:15], 43, v216
	s_and_b64 s[16:17], s[18:19], s[16:17]
	v_cmp_gt_i32_e64 s[12:13], 42, v216
	s_and_b64 s[14:15], s[16:17], s[14:15]
	v_cmp_gt_i32_e64 s[10:11], 41, v216
	s_and_b64 s[12:13], s[14:15], s[12:13]
	v_cmp_gt_i32_e64 s[8:9], 40, v216
	s_and_b64 s[10:11], s[12:13], s[10:11]
	v_cmp_gt_i32_e64 s[6:7], 35, v216
	s_and_b64 s[8:9], s[10:11], s[8:9]
	v_cmp_gt_i32_e64 s[4:5], 34, v216
	s_and_b64 s[6:7], s[8:9], s[6:7]
	v_cmp_gt_i32_e64 s[2:3], 33, v216
	s_and_b64 s[4:5], s[6:7], s[4:5]
	v_cmp_gt_i32_e32 vcc, 32, v216
	s_and_b64 s[2:3], s[4:5], s[2:3]
	s_and_b64 vcc, s[2:3], vcc
	v_cndmask_b32_e64 v95, v95, v130, s[64:65]
	v_cndmask_b32_e64 v94, v94, v130, s[62:63]
	v_cndmask_b32_e64 v93, v93, v130, s[60:61]
	v_cndmask_b32_e64 v92, v92, v130, s[58:59]
	v_cndmask_b32_e64 v91, v91, v130, s[56:57]
	v_cndmask_b32_e64 v90, v90, v130, s[54:55]
	v_cndmask_b32_e64 v89, v89, v130, s[52:53]
	v_cndmask_b32_e64 v88, v88, v130, s[50:51]
	v_cndmask_b32_e64 v87, v87, v130, s[48:49]
	v_cndmask_b32_e64 v86, v86, v130, s[46:47]
	v_cndmask_b32_e64 v85, v85, v130, s[44:45]
	v_cndmask_b32_e64 v84, v84, v130, s[42:43]
	v_cndmask_b32_e64 v83, v83, v130, s[40:41]
	v_cndmask_b32_e64 v82, v82, v130, s[38:39]
	v_cndmask_b32_e64 v81, v81, v130, s[36:37]
	v_cndmask_b32_e64 v79, v79, v130, s[34:35]
	v_cndmask_b32_e64 v78, v78, v130, s[28:29]
	v_cndmask_b32_e64 v77, v77, v130, s[26:27]
	v_cndmask_b32_e64 v76, v76, v130, s[24:25]
	v_cndmask_b32_e64 v75, v75, v130, s[22:23]
	v_cndmask_b32_e64 v74, v74, v130, s[20:21]
	v_cndmask_b32_e64 v73, v73, v130, s[18:19]
	v_cndmask_b32_e64 v72, v72, v130, s[16:17]
	v_cndmask_b32_e64 v71, v71, v130, s[14:15]
	v_cndmask_b32_e64 v70, v70, v130, s[12:13]
	v_cndmask_b32_e64 v69, v69, v130, s[10:11]
	v_cndmask_b32_e64 v68, v68, v130, s[8:9]
	v_cndmask_b32_e64 v67, v67, v130, s[6:7]
	v_cndmask_b32_e64 v66, v66, v130, s[4:5]
	v_cndmask_b32_e64 v65, v65, v130, s[2:3]
	v_cndmask_b32_e32 v64, v64, v130, vcc

; __device__ __forceinline__ void partialSM(f32x16& p0, f32x16& p1, float& m_reg, float& mn, float& alpha) {
;     ...
;     if (__builtin_expect(__all((pmax - m_reg) <= THR2), 1)) { mn = m_reg; alpha = 1.f; }
;     else { mn = fmaxf(m_reg, pmax); alpha = __builtin_amdgcn_exp2f(m_reg - mn); m_reg = mn; }
.Lmaxtail_0:
	s_cmp_eq_u64 vcc, exec
	s_cselect_b64 s[2:3], -1, 0
	v_cndmask_b32_e64 v220, v165, 1.0, s[2:3]
	v_cmp_gt_f32_e32 vcc, 1.0, v220
	s_cbranch_vccz .LBB0_529
	s_and_saveexec_b64 s[4:5], s[0:1]
	ds_write_b32 v214, v220 offset:128
	s_or_b64 exec, exec, s[4:5]
	s_waitcnt lgkmcnt(0)
	ds_read_b128 v[166:169], v131 offset:224
	ds_read_b128 v[170:173], v131 offset:192
	ds_read_b128 v[174:177], v131 offset:160
	ds_read_b128 v[222:225], v131 offset:128
	s_waitcnt lgkmcnt(0)
	v_pk_mul_f32 v[62:63], v[62:63], v[168:169]
	v_pk_mul_f32 v[58:59], v[58:59], v[172:173]
	v_pk_mul_f32 v[54:55], v[54:55], v[176:177]
	v_pk_mul_f32 v[50:51], v[50:51], v[224:225]
	v_pk_mul_f32 v[60:61], v[60:61], v[166:167]
	v_pk_mul_f32 v[56:57], v[56:57], v[170:171]
	v_pk_mul_f32 v[52:53], v[52:53], v[174:175]
	v_pk_mul_f32 v[48:49], v[48:49], v[222:223]
	v_pk_mul_f32 v[46:47], v[46:47], v[168:169]
	v_pk_mul_f32 v[42:43], v[42:43], v[172:173]
	v_pk_mul_f32 v[38:39], v[38:39], v[176:177]
	v_pk_mul_f32 v[34:35], v[34:35], v[224:225]
	v_pk_mul_f32 v[44:45], v[44:45], v[166:167]
	v_pk_mul_f32 v[40:41], v[40:41], v[170:171]
	v_pk_mul_f32 v[36:37], v[36:37], v[174:175]
	v_pk_mul_f32 v[32:33], v[32:33], v[222:223]
	v_pk_mul_f32 v[30:31], v[30:31], v[168:169]
	v_pk_mul_f32 v[26:27], v[26:27], v[172:173]
	v_pk_mul_f32 v[22:23], v[22:23], v[176:177]
	v_pk_mul_f32 v[18:19], v[18:19], v[224:225]
	v_pk_mul_f32 v[28:29], v[28:29], v[166:167]
	v_pk_mul_f32 v[24:25], v[24:25], v[170:171]
	v_pk_mul_f32 v[20:21], v[20:21], v[174:175]
	v_pk_mul_f32 v[16:17], v[16:17], v[222:223]
	v_pk_mul_f32 v[14:15], v[14:15], v[168:169]
	v_pk_mul_f32 v[10:11], v[10:11], v[172:173]
	v_pk_mul_f32 v[6:7], v[6:7], v[176:177]
	v_pk_mul_f32 v[2:3], v[2:3], v[224:225]
	v_pk_mul_f32 v[12:13], v[12:13], v[166:167]
	v_pk_mul_f32 v[8:9], v[8:9], v[170:171]
	v_pk_mul_f32 v[4:5], v[4:5], v[174:175]
	v_pk_mul_f32 v[0:1], v[0:1], v[222:223]

; #define LAS __attribute__((address_space(3)))
; __device__ __forceinline__ void partialSM(f32x16& p0, f32x16& p1, float& m_reg, float& mn, float& alpha) {
;     ...
; #pragma unroll
;     for (int r = 0; r < 16; ++r) p0[r] = p0[r] - mn;
; #pragma unroll
;     for (int r = 0; r < 16; ++r) p1[r] = p1[r] - mn;
; #pragma unroll
;     for (int r = 0; r < 16; ++r) p0[r] = __builtin_amdgcn_exp2f(p0[r]);
; }
; __device__ __forceinline__ void finishSM(f32x16& p0, f32x16& p1, float alpha, float& l_reg, bf16x8& pa0, bf16x8& pa1, bf16x8& pa2, bf16x8& pa3) {
; #pragma unroll
;     for (int r = 0; r < 16; ++r) p1[r] = __builtin_amdgcn_exp2f(p1[r]);
;     float ps = 0;
; #pragma unroll
;     for (int r = 0; r < 16; ++r) ps += p0[r];
; #pragma unroll
;     for (int r = 0; r < 16; ++r) ps += p1[r];
;     { auto rr = __builtin_amdgcn_permlane32_swap(__float_as_uint(ps), __float_as_uint(ps), false, false);
;       ps = __uint_as_float(rr[0]) + __uint_as_float(rr[1]); }
;     l_reg = l_reg * alpha + ps;
;     ...
;     PK4(p0, 0, pa0); PK4(p0, 8, pa1); PK4(p1, 0, pa2); PK4(p1, 8, pa3);
;     ...
; }
; __device__ __forceinline__ void qkt(f32x16& p0, f32x16& p1, const char* Kslot, int r32, int hi, const bf16x8* qr, const LAS f32x4* cp) {
; #pragma unroll
;     for (int g = 0; g < 4; ++g) { const f32x4 c0 = cp[2 * g], c1 = cp[8 + 2 * g];
; #pragma unroll
;         for (int j = 0; j < 4; ++j) { p0[4 * g + j] = c0[j]; p1[4 * g + j] = c1[j]; } }
;     const char* kb[4];
; #pragma unroll
;     for (int dd = 0; dd < 4; ++dd) kb[dd] = Kslot + KSWZ(r32, (dd * 16 + hi * 8) * 2);
; #pragma unroll
;     for (int d0 = 0; d0 < 8; ++d0) { const char* a = kb[d0 & 3] + (d0 >> 2) * 128;
;         bf16x8 b0 = *reinterpret_cast<const bf16x8*>(a);
;         bf16x8 b1 = *reinterpret_cast<const bf16x8*>(a + 32 * 256);
;         p0 = __builtin_amdgcn_mfma_f32_32x32x16_bf16(b0, qr[d0], p0, 0, 0, 0);
;         p1 = __builtin_amdgcn_mfma_f32_32x32x16_bf16(b1, qr[d0], p1, 0, 0, 0); }
.LBB0_537:
	v_cndmask_b32_e64 v154, v164, v154, s[2:3]
	v_sub_f32_e32 v80, v80, v154
	v_sub_f32_e32 v81, v81, v154
	v_sub_f32_e32 v82, v82, v154
	v_sub_f32_e32 v83, v83, v154
	v_sub_f32_e32 v84, v84, v154
	v_sub_f32_e32 v85, v85, v154
	v_sub_f32_e32 v86, v86, v154
	v_sub_f32_e32 v87, v87, v154
	v_sub_f32_e32 v88, v88, v154
	v_sub_f32_e32 v89, v89, v154
	v_sub_f32_e32 v90, v90, v154
	v_sub_f32_e32 v91, v91, v154
	v_sub_f32_e32 v92, v92, v154
	v_sub_f32_e32 v93, v93, v154
	v_sub_f32_e32 v94, v94, v154
	v_sub_f32_e32 v95, v95, v154
	v_sub_f32_e32 v164, v64, v154
	v_sub_f32_e32 v165, v65, v154
	v_sub_f32_e32 v166, v66, v154
	v_sub_f32_e32 v167, v67, v154
	v_sub_f32_e32 v168, v68, v154
	v_sub_f32_e32 v169, v69, v154
	v_sub_f32_e32 v170, v70, v154
	v_sub_f32_e32 v171, v71, v154
	v_sub_f32_e32 v172, v72, v154
	v_sub_f32_e32 v173, v73, v154
	v_sub_f32_e32 v174, v74, v154
	v_sub_f32_e32 v175, v75, v154
	v_sub_f32_e32 v176, v76, v154
	v_exp_f32_e32 v177, v80
	v_exp_f32_e32 v178, v81
	v_exp_f32_e32 v179, v82
	v_exp_f32_e32 v221, v83
	v_exp_f32_e32 v222, v84
	v_exp_f32_e32 v223, v85
	v_exp_f32_e32 v224, v86
	v_exp_f32_e32 v225, v87
	v_exp_f32_e32 v226, v88
	v_exp_f32_e32 v227, v89
	v_exp_f32_e32 v228, v90
	v_exp_f32_e32 v229, v91
	v_exp_f32_e32 v230, v92
	v_exp_f32_e32 v231, v93
	v_exp_f32_e32 v232, v94
	v_exp_f32_e32 v233, v95
	v_sub_f32_e32 v234, v77, v154
	v_sub_f32_e32 v235, v78, v154
	v_sub_f32_e32 v236, v79, v154
	s_add_i32 s2, s76, 0
	v_add_u32_e32 v237, s2, v193
	ds_read_b128 v[80:83], v217 offset:256
	ds_read_b128 v[84:87], v217 offset:288
	ds_read_b128 v[64:67], v217 offset:384
	ds_read_b128 v[68:71], v217 offset:416
	ds_read_b128 v[88:91], v217 offset:320
	ds_read_b128 v[72:75], v217 offset:448
	ds_read_b128 v[92:95], v217 offset:352
	ds_read_b128 v[76:79], v217 offset:480
	ds_read_b128 v[156:159], v237 offset:49152
	ds_read_b128 v[160:163], v237 offset:57344
	v_add_u32_e32 v238, s2, v194
	v_add_u32_e32 v239, s2, v195
	s_waitcnt lgkmcnt(0)
	v_mfma_f32_32x32x16_bf16 v[80:95], v[156:159], v[96:99], v[80:95]
	v_add_u32_e32 v240, s2, v196
	v_exp_f32_e32 v167, v167
	v_exp_f32_e32 v168, v168
	v_exp_f32_e32 v169, v169
	v_exp_f32_e32 v170, v170
	v_exp_f32_e32 v171, v171
	v_exp_f32_e32 v172, v172
	v_mfma_f32_32x32x16_bf16 v[64:79], v[160:163], v[96:99], v[64:79]
	ds_read_b128 v[156:159], v238 offset:49152
	ds_read_b128 v[160:163], v238 offset:57344
	v_exp_f32_e32 v173, v173
	v_exp_f32_e32 v174, v174
	v_exp_f32_e32 v175, v175
	v_exp_f32_e32 v176, v176
	v_exp_f32_e32 v234, v234
	v_exp_f32_e32 v235, v235
	s_waitcnt lgkmcnt(0)
	v_mfma_f32_32x32x16_bf16 v[80:95], v[156:159], v[100:103], v[80:95]
	v_exp_f32_e32 v236, v236
	v_mfma_f32_32x32x16_bf16 v[64:79], v[160:163], v[100:103], v[64:79]
	ds_read_b128 v[156:159], v239 offset:49152
	ds_read_b128 v[160:163], v239 offset:57344
	s_waitcnt lgkmcnt(0)
	v_mfma_f32_32x32x16_bf16 v[80:95], v[156:159], v[104:107], v[80:95]
	v_mfma_f32_32x32x16_bf16 v[64:79], v[160:163], v[104:107], v[64:79]
	ds_read_b128 v[156:159], v240 offset:49152
	ds_read_b128 v[160:163], v240 offset:57344
	s_waitcnt lgkmcnt(0)
	v_mfma_f32_32x32x16_bf16 v[80:95], v[156:159], v[108:111], v[80:95]
	v_mfma_f32_32x32x16_bf16 v[64:79], v[160:163], v[108:111], v[64:79]
	v_xor_b32_e32 v249, 0x80, v237
	v_xor_b32_e32 v250, 0x80, v238
	v_xor_b32_e32 v251, 0x80, v239
	v_xor_b32_e32 v252, 0x80, v240
	ds_read_b128 v[156:159], v249 offset:49152
	ds_read_b128 v[160:163], v249 offset:57344
	v_exp_f32_e32 v237, v164
	s_waitcnt lgkmcnt(0)
	v_mfma_f32_32x32x16_bf16 v[80:95], v[156:159], v[112:115], v[80:95]
	v_mfma_f32_32x32x16_bf16 v[64:79], v[160:163], v[112:115], v[64:79]
	ds_read_b128 v[156:159], v250 offset:49152
	ds_read_b128 v[160:163], v250 offset:57344
	v_exp_f32_e32 v238, v165
	s_waitcnt lgkmcnt(0)
	v_mfma_f32_32x32x16_bf16 v[80:95], v[156:159], v[116:119], v[80:95]
	v_mfma_f32_32x32x16_bf16 v[64:79], v[160:163], v[116:119], v[64:79]
	ds_read_b128 v[156:159], v251 offset:49152
	ds_read_b128 v[160:163], v251 offset:57344
	v_exp_f32_e32 v239, v166
	s_waitcnt lgkmcnt(0)
	v_mfma_f32_32x32x16_bf16 v[80:95], v[156:159], v[120:123], v[80:95]
	v_mfma_f32_32x32x16_bf16 v[64:79], v[160:163], v[120:123], v[64:79]
	ds_read_b128 v[156:159], v252 offset:49152
	ds_read_b128 v[160:163], v252 offset:57344
	s_waitcnt lgkmcnt(0)
	v_mfma_f32_32x32x16_bf16 v[80:95], v[156:159], v[124:127], v[80:95]
	v_add_f32_e32 v156, 0, v177
	v_add_f32_e32 v156, v178, v156
	v_add_f32_e32 v156, v179, v156
	v_add_f32_e32 v156, v221, v156
	v_add_f32_e32 v156, v222, v156
	v_add_f32_e32 v156, v223, v156
	v_add_f32_e32 v156, v224, v156
	v_add_f32_e32 v156, v225, v156
	v_add_f32_e32 v156, v226, v156
	v_add_f32_e32 v156, v227, v156
	v_add_f32_e32 v156, v228, v156
	v_add_f32_e32 v156, v229, v156
	v_add_f32_e32 v156, v230, v156
	v_add_f32_e32 v156, v231, v156
	v_add_f32_e32 v156, v232, v156
	v_add_f32_e32 v156, v233, v156
	v_add_f32_e32 v156, v237, v156
	v_add_f32_e32 v156, v238, v156
	v_add_f32_e32 v156, v239, v156
	v_add_f32_e32 v156, v167, v156
	v_add_f32_e32 v156, v168, v156
	v_add_f32_e32 v156, v169, v156
	v_add_f32_e32 v156, v170, v156
	v_add_f32_e32 v156, v171, v156
	v_add_f32_e32 v156, v172, v156
	v_add_f32_e32 v156, v173, v156
	v_mfma_f32_32x32x16_bf16 v[64:79], v[160:163], v[124:127], v[64:79]
	v_add_f32_e32 v156, v174, v156
	v_add_f32_e32 v156, v175, v156
	v_add_f32_e32 v156, v176, v156
	v_add_f32_e32 v156, v234, v156
	v_add_f32_e32 v156, v235, v156
	v_add_f32_e32 v156, v236, v156
	v_mov_b32_e32 v157, v156
	s_nop 1
	v_permlane32_swap_b32_e32 v156, v157
	v_cvt_pk_bf16_f32 v158, v177, v178
	v_cvt_pk_bf16_f32 v159, v179, v221
	v_cvt_pk_bf16_f32 v160, v222, v223
	v_cvt_pk_bf16_f32 v161, v224, v225
	v_cvt_pk_bf16_f32 v162, v226, v227
	v_cvt_pk_bf16_f32 v163, v228, v229
	v_cvt_pk_bf16_f32 v164, v230, v231
	v_cvt_pk_bf16_f32 v165, v232, v233
	v_cvt_pk_bf16_f32 v166, v237, v238
	v_cvt_pk_bf16_f32 v167, v239, v167
	v_cvt_pk_bf16_f32 v168, v168, v169
	v_cvt_pk_bf16_f32 v169, v170, v171
	v_cvt_pk_bf16_f32 v170, v172, v173
	v_cvt_pk_bf16_f32 v171, v174, v175
	v_cvt_pk_bf16_f32 v172, v176, v234
	v_cvt_pk_bf16_f32 v173, v235, v236
	s_nop 0
	v_permlane32_swap_b32_e32 v158, v160
	v_permlane32_swap_b32_e32 v159, v161
	v_permlane32_swap_b32_e32 v162, v164
	v_permlane32_swap_b32_e32 v163, v165
	v_permlane32_swap_b32_e32 v166, v168
	v_permlane32_swap_b32_e32 v167, v169
	v_permlane32_swap_b32_e32 v170, v172
	v_permlane32_swap_b32_e32 v171, v173
	v_add_u32_e32 v178, s73, v192
	s_cmp_le_i32 s92, s91
	s_cbranch_scc0 .Lband_1
; #define SBAR() __builtin_amdgcn_sched_barrier(0)
; #define PV_RD(d0, kh, X) do { constexpr int b_ = v_rd_off(d0, 2 * (kh), 0); TRRD(X##l0, b_); TRRD(X##h0, b_ + 2048); TRRD(X##l1, b_ + 4096); TRRD(X##h1, b_ + 6144); } while (0)
; #define PV_MM(d0, X, PA, PB) do { \
;         o[d0] = __builtin_amdgcn_mfma_f32_32x32x16_bf16(PA, (bf16x8){X##l0[0], X##l0[1], X##l0[2], X##l0[3], X##h0[0], X##h0[1], X##h0[2], X##h0[3]}, o[d0], 0, 0, 0);   \
;         o[d0] = __builtin_amdgcn_mfma_f32_32x32x16_bf16(PB, (bf16x8){X##l1[0], X##l1[1], X##l1[2], X##l1[3], X##h1[0], X##h1[1], X##h1[2], X##h1[3]}, o[d0], 0, 0, 0); } while (0)
; #define PV_W4() do { asm volatile("s_waitcnt lgkmcnt(4)" ::: "memory"); SBAR(); } while (0)
; #define PV_W0() do { asm volatile("s_waitcnt lgkmcnt(0)" ::: "memory"); SBAR(); } while (0)
; __device__ __forceinline__ void partialSM(f32x16& p0, f32x16& p1, float& m_reg, float& mn, float& alpha) {
;     float pmax = p0[0];
; #pragma unroll
;     for (int r = 1; r < 16; ++r) pmax = fmaxf(pmax, p0[r]);
; #pragma unroll
;     for (int r = 0; r < 16; ++r) pmax = fmaxf(pmax, p1[r]);
;     { auto rr = __builtin_amdgcn_permlane32_swap(__float_as_uint(pmax), __float_as_uint(pmax), false, false);
;       pmax = fmaxf(__uint_as_float(rr[0]), __uint_as_float(rr[1])); }
;     if (__builtin_expect(__all((pmax - m_reg) <= THR2), 1)) { mn = m_reg; alpha = 1.f; }
;     else { mn = fmaxf(m_reg, pmax); alpha = __builtin_amdgcn_exp2f(m_reg - mn); m_reg = mn; }
; __device__ __forceinline__ void pv_tile(f32x16* o, int vb0, bf16x8 pa0, bf16x8 pa1, bf16x8 pa2, bf16x8 pa3) {
;     ...
;     s16x4 al0, al1, ah0, ah1, bl0, bl1, bh0, bh1;
;     PV_RD(0, 0, a);
;     PV_RD(0, 1, b); PV_W4(); PV_MM(0, a, pa0, pa1); SBAR();
;     PV_RD(1, 0, a); PV_W4(); PV_MM(0, b, pa2, pa3); SBAR();
;     PV_RD(1, 1, b); PV_W4(); PV_MM(1, a, pa0, pa1); SBAR();
;     PV_RD(2, 0, a); PV_W4(); PV_MM(1, b, pa2, pa3); SBAR();
;     PV_RD(2, 1, b); PV_W4(); PV_MM(2, a, pa0, pa1); SBAR();
;     PV_RD(3, 0, a); PV_W4(); PV_MM(2, b, pa2, pa3); SBAR();
;     PV_RD(3, 1, b); PV_W4(); PV_MM(3, a, pa0, pa1); SBAR();
;     PV_W0(); PV_MM(3, b, pa2, pa3);
	ds_read_b64_tr_b16 v[174:175], v178 offset:0
	ds_read_b64_tr_b16 v[176:177], v178 offset:0x800
	ds_read_b64_tr_b16 v[222:223], v178 offset:0x1000
	ds_read_b64_tr_b16 v[224:225], v178 offset:0x1800
	ds_read_b64_tr_b16 v[226:227], v178 offset:0x2000
	ds_read_b64_tr_b16 v[228:229], v178 offset:0x2800
	ds_read_b64_tr_b16 v[230:231], v178 offset:0x3000
	ds_read_b64_tr_b16 v[232:233], v178 offset:0x3800
	s_waitcnt lgkmcnt(4)
	s_nop 0
	v_mfma_f32_32x32x16_bf16 v[48:63], v[158:161], v[174:177], v[48:63]
	v_max_f32_e32 v253, v81, v81
	v_max_f32_e32 v254, v80, v80
	v_mfma_f32_32x32x16_bf16 v[48:63], v[162:165], v[222:225], v[48:63]
	v_max_f32_e32 v253, v254, v253
	v_max3_f32 v253, v253, v82, v83
	ds_read_b64_tr_b16 v[174:175], v178 offset:0x200
	ds_read_b64_tr_b16 v[176:177], v178 offset:0xa00
	ds_read_b64_tr_b16 v[222:223], v178 offset:0x1200
	ds_read_b64_tr_b16 v[224:225], v178 offset:0x1a00
	s_waitcnt lgkmcnt(4)
	v_mfma_f32_32x32x16_bf16 v[48:63], v[166:169], v[226:229], v[48:63]
	v_max3_f32 v253, v253, v84, v85
	v_max3_f32 v253, v253, v86, v87
	v_mfma_f32_32x32x16_bf16 v[48:63], v[170:173], v[230:233], v[48:63]
	v_max3_f32 v253, v253, v88, v89
	v_max3_f32 v253, v253, v90, v91
	ds_read_b64_tr_b16 v[226:227], v178 offset:0x2200
	ds_read_b64_tr_b16 v[228:229], v178 offset:0x2a00
	ds_read_b64_tr_b16 v[230:231], v178 offset:0x3200
	ds_read_b64_tr_b16 v[232:233], v178 offset:0x3a00
	s_waitcnt lgkmcnt(4)
	v_mfma_f32_32x32x16_bf16 v[32:47], v[158:161], v[174:177], v[32:47]
	v_max3_f32 v253, v253, v92, v93
	v_max3_f32 v253, v253, v94, v95
	v_mfma_f32_32x32x16_bf16 v[32:47], v[162:165], v[222:225], v[32:47]
	v_max3_f32 v253, v253, v64, v65
	v_max3_f32 v253, v253, v66, v67
	ds_read_b64_tr_b16 v[174:175], v178 offset:0x400
	ds_read_b64_tr_b16 v[176:177], v178 offset:0xc00
	ds_read_b64_tr_b16 v[222:223], v178 offset:0x1400
	ds_read_b64_tr_b16 v[224:225], v178 offset:0x1c00
	s_waitcnt lgkmcnt(4)
	v_mfma_f32_32x32x16_bf16 v[32:47], v[166:169], v[226:229], v[32:47]
	v_max3_f32 v253, v253, v68, v69
	v_max3_f32 v253, v253, v70, v71
	v_mfma_f32_32x32x16_bf16 v[32:47], v[170:173], v[230:233], v[32:47]
	v_max3_f32 v253, v253, v72, v73
	v_max3_f32 v253, v253, v74, v75
	ds_read_b64_tr_b16 v[226:227], v178 offset:0x2400
	ds_read_b64_tr_b16 v[228:229], v178 offset:0x2c00
	ds_read_b64_tr_b16 v[230:231], v178 offset:0x3400
	ds_read_b64_tr_b16 v[232:233], v178 offset:0x3c00
	s_waitcnt lgkmcnt(4)
	v_mfma_f32_32x32x16_bf16 v[16:31], v[158:161], v[174:177], v[16:31]
	v_max3_f32 v253, v253, v76, v77
	v_max3_f32 v253, v253, v78, v79
	v_mfma_f32_32x32x16_bf16 v[16:31], v[162:165], v[222:225], v[16:31]
	v_mov_b32_e32 v254, v253
	s_nop 1
	ds_read_b64_tr_b16 v[174:175], v178 offset:0x600
	ds_read_b64_tr_b16 v[176:177], v178 offset:0xe00
	ds_read_b64_tr_b16 v[222:223], v178 offset:0x1600
	ds_read_b64_tr_b16 v[224:225], v178 offset:0x1e00
	s_waitcnt lgkmcnt(4)
	v_mfma_f32_32x32x16_bf16 v[16:31], v[166:169], v[226:229], v[16:31]
	v_permlane32_swap_b32_e32 v253, v254
	v_max_f32_e32 v254, v254, v254
	v_mfma_f32_32x32x16_bf16 v[16:31], v[170:173], v[230:233], v[16:31]
	v_max_f32_e32 v253, v253, v253
	v_max_f32_e32 v253, v253, v254
	ds_read_b64_tr_b16 v[226:227], v178 offset:0x2600
	ds_read_b64_tr_b16 v[228:229], v178 offset:0x2e00
	ds_read_b64_tr_b16 v[230:231], v178 offset:0x3600
	ds_read_b64_tr_b16 v[232:233], v178 offset:0x3e00
	s_waitcnt lgkmcnt(4)
	v_mfma_f32_32x32x16_bf16 v[0:15], v[158:161], v[174:177], v[0:15]
	v_sub_f32_e32 v254, v253, v154
	v_cmp_ge_f32_e32 vcc, s33, v254
	v_mfma_f32_32x32x16_bf16 v[0:15], v[162:165], v[222:225], v[0:15]
	v_max_f32_e32 v254, v154, v154
	v_max_f32_e32 v254, v254, v253
	s_waitcnt lgkmcnt(0)
	v_mfma_f32_32x32x16_bf16 v[0:15], v[166:169], v[226:229], v[0:15]
	v_sub_f32_e32 v253, v154, v254
	v_exp_f32_e32 v253, v253
	v_mfma_f32_32x32x16_bf16 v[0:15], v[170:173], v[230:233], v[0:15]
	v_mov_b32_e32 v158, v253
	v_mov_b32_e32 v159, v254
	s_branch .Lmaxtail_1
; #define SBAR() __builtin_amdgcn_sched_barrier(0)
; #define PV_RD(d0, kh, X) do { constexpr int b_ = v_rd_off(d0, 2 * (kh), 0); TRRD(X##l0, b_); TRRD(X##h0, b_ + 2048); TRRD(X##l1, b_ + 4096); TRRD(X##h1, b_ + 6144); } while (0)
; #define PV_MM(d0, X, PA, PB) do { \
;         o[d0] = __builtin_amdgcn_mfma_f32_32x32x16_bf16(PA, (bf16x8){X##l0[0], X##l0[1], X##l0[2], X##l0[3], X##h0[0], X##h0[1], X##h0[2], X##h0[3]}, o[d0], 0, 0, 0);   \
;         o[d0] = __builtin_amdgcn_mfma_f32_32x32x16_bf16(PB, (bf16x8){X##l1[0], X##l1[1], X##l1[2], X##l1[3], X##h1[0], X##h1[1], X##h1[2], X##h1[3]}, o[d0], 0, 0, 0); } while (0)
; #define PV_W4() do { asm volatile("s_waitcnt lgkmcnt(4)" ::: "memory"); SBAR(); } while (0)
; #define PV_W0() do { asm volatile("s_waitcnt lgkmcnt(0)" ::: "memory"); SBAR(); } while (0)
; __device__ __forceinline__ void mask_tile(f32x16& p0, f32x16& p1, int dq) {
;     const float NEG = -__builtin_inff();
; #pragma unroll
;     for (int r = 0; r < 16; ++r) { const int c = (r & 3) + 8 * (r >> 2); if (dq - c < 0) p0[r] = NEG; if (dq - c - 32 < 0) p1[r] = NEG; }
; }
; __device__ __forceinline__ void pv_tile(f32x16* o, int vb0, bf16x8 pa0, bf16x8 pa1, bf16x8 pa2, bf16x8 pa3) {
;     ...
;     s16x4 al0, al1, ah0, ah1, bl0, bl1, bh0, bh1;
;     PV_RD(0, 0, a);
;     PV_RD(0, 1, b); PV_W4(); PV_MM(0, a, pa0, pa1); SBAR();
;     PV_RD(1, 0, a); PV_W4(); PV_MM(0, b, pa2, pa3); SBAR();
;     PV_RD(1, 1, b); PV_W4(); PV_MM(1, a, pa0, pa1); SBAR();
;     PV_RD(2, 0, a); PV_W4(); PV_MM(1, b, pa2, pa3); SBAR();
;     PV_RD(2, 1, b); PV_W4(); PV_MM(2, a, pa0, pa1); SBAR();
;     PV_RD(3, 0, a); PV_W4(); PV_MM(2, b, pa2, pa3); SBAR();
;     PV_RD(3, 1, b); PV_W4(); PV_MM(3, a, pa0, pa1); SBAR();
;     PV_W0(); PV_MM(3, b, pa2, pa3);
.Lband_1:
	ds_read_b64_tr_b16 v[174:175], v178 offset:0
	ds_read_b64_tr_b16 v[176:177], v178 offset:0x800
	ds_read_b64_tr_b16 v[222:223], v178 offset:0x1000
	ds_read_b64_tr_b16 v[224:225], v178 offset:0x1800
	ds_read_b64_tr_b16 v[226:227], v178 offset:0x2000
	ds_read_b64_tr_b16 v[228:229], v178 offset:0x2800
	ds_read_b64_tr_b16 v[230:231], v178 offset:0x3000
	ds_read_b64_tr_b16 v[232:233], v178 offset:0x3800
	s_waitcnt lgkmcnt(4)
	s_nop 0
	v_mfma_f32_32x32x16_bf16 v[48:63], v[158:161], v[174:177], v[48:63]
	v_mfma_f32_32x32x16_bf16 v[48:63], v[162:165], v[222:225], v[48:63]
	ds_read_b64_tr_b16 v[174:175], v178 offset:0x200
	ds_read_b64_tr_b16 v[176:177], v178 offset:0xa00
	ds_read_b64_tr_b16 v[222:223], v178 offset:0x1200
	ds_read_b64_tr_b16 v[224:225], v178 offset:0x1a00
	s_waitcnt lgkmcnt(4)
	v_mfma_f32_32x32x16_bf16 v[48:63], v[166:169], v[226:229], v[48:63]
	v_mfma_f32_32x32x16_bf16 v[48:63], v[170:173], v[230:233], v[48:63]
	ds_read_b64_tr_b16 v[226:227], v178 offset:0x2200
	ds_read_b64_tr_b16 v[228:229], v178 offset:0x2a00
	ds_read_b64_tr_b16 v[230:231], v178 offset:0x3200
	ds_read_b64_tr_b16 v[232:233], v178 offset:0x3a00
	s_waitcnt lgkmcnt(4)
	v_mfma_f32_32x32x16_bf16 v[32:47], v[158:161], v[174:177], v[32:47]
	v_mfma_f32_32x32x16_bf16 v[32:47], v[162:165], v[222:225], v[32:47]
	ds_read_b64_tr_b16 v[174:175], v178 offset:0x400
	ds_read_b64_tr_b16 v[176:177], v178 offset:0xc00
	ds_read_b64_tr_b16 v[222:223], v178 offset:0x1400
	ds_read_b64_tr_b16 v[224:225], v178 offset:0x1c00
	s_waitcnt lgkmcnt(4)
	v_mfma_f32_32x32x16_bf16 v[32:47], v[166:169], v[226:229], v[32:47]
	v_mfma_f32_32x32x16_bf16 v[32:47], v[170:173], v[230:233], v[32:47]
	ds_read_b64_tr_b16 v[226:227], v178 offset:0x2400
	ds_read_b64_tr_b16 v[228:229], v178 offset:0x2c00
	ds_read_b64_tr_b16 v[230:231], v178 offset:0x3400
	ds_read_b64_tr_b16 v[232:233], v178 offset:0x3c00
	s_waitcnt lgkmcnt(4)
	v_mfma_f32_32x32x16_bf16 v[16:31], v[158:161], v[174:177], v[16:31]
	v_mfma_f32_32x32x16_bf16 v[16:31], v[162:165], v[222:225], v[16:31]
	ds_read_b64_tr_b16 v[174:175], v178 offset:0x600
	ds_read_b64_tr_b16 v[176:177], v178 offset:0xe00
	ds_read_b64_tr_b16 v[222:223], v178 offset:0x1600
	ds_read_b64_tr_b16 v[224:225], v178 offset:0x1e00
	s_waitcnt lgkmcnt(4)
	v_mfma_f32_32x32x16_bf16 v[16:31], v[166:169], v[226:229], v[16:31]
	v_mfma_f32_32x32x16_bf16 v[16:31], v[170:173], v[230:233], v[16:31]
	ds_read_b64_tr_b16 v[226:227], v178 offset:0x2600
	ds_read_b64_tr_b16 v[228:229], v178 offset:0x2e00
	ds_read_b64_tr_b16 v[230:231], v178 offset:0x3600
	ds_read_b64_tr_b16 v[232:233], v178 offset:0x3e00
	s_waitcnt lgkmcnt(4)
	v_mfma_f32_32x32x16_bf16 v[0:15], v[158:161], v[174:177], v[0:15]
	v_mfma_f32_32x32x16_bf16 v[0:15], v[162:165], v[222:225], v[0:15]
	s_waitcnt lgkmcnt(0)
	v_mfma_f32_32x32x16_bf16 v[0:15], v[166:169], v[226:229], v[0:15]
	s_cmp_le_i32 s92, s91
	v_mfma_f32_32x32x16_bf16 v[0:15], v[170:173], v[230:233], v[0:15]
	s_cbranch_scc1 .LBB0_539
	v_subrev_u32_e32 v158, 64, v216
	v_cmp_gt_i32_e64 s[62:63], 26, v158
	v_cmp_gt_i32_e64 s[64:65], 27, v158
	v_cmp_gt_i32_e64 s[60:61], 25, v158
	s_and_b64 s[62:63], s[64:65], s[62:63]
	v_cmp_gt_i32_e64 s[58:59], 24, v158
	s_and_b64 s[60:61], s[62:63], s[60:61]
	v_cmp_gt_i32_e64 s[56:57], 19, v158
	s_and_b64 s[58:59], s[60:61], s[58:59]
	v_cmp_gt_i32_e64 s[54:55], 18, v158
	s_and_b64 s[56:57], s[58:59], s[56:57]
	v_cmp_gt_i32_e64 s[52:53], 17, v158
	s_and_b64 s[54:55], s[56:57], s[54:55]
	v_cmp_gt_i32_e64 s[50:51], 16, v158
	s_and_b64 s[52:53], s[54:55], s[52:53]
	v_cmp_gt_i32_e64 s[48:49], 11, v158
	s_and_b64 s[50:51], s[52:53], s[50:51]
	v_cmp_gt_i32_e64 s[46:47], 10, v158
	s_and_b64 s[48:49], s[50:51], s[48:49]
	v_cmp_gt_i32_e64 s[44:45], 9, v158
	s_and_b64 s[46:47], s[48:49], s[46:47]
	v_cmp_gt_i32_e64 s[42:43], 8, v158
	s_and_b64 s[44:45], s[46:47], s[44:45]
	v_cmp_gt_i32_e64 s[40:41], 3, v158
	s_and_b64 s[42:43], s[44:45], s[42:43]
	v_cmp_gt_i32_e64 s[38:39], 2, v158
	s_and_b64 s[40:41], s[42:43], s[40:41]
	v_cmp_gt_i32_e64 s[36:37], 1, v158
	s_and_b64 s[38:39], s[40:41], s[38:39]
	v_cmp_gt_i32_e64 s[34:35], 0, v158
	s_and_b64 s[36:37], s[38:39], s[36:37]
	s_and_b64 s[34:35], s[36:37], s[34:35]
	v_cmp_gt_i32_e64 s[28:29], 58, v158
	v_cndmask_b32_e64 v80, v80, v130, s[34:35]
	v_cmp_gt_i32_e64 s[34:35], 59, v158
	v_cmp_gt_i32_e64 s[26:27], 57, v158
	s_and_b64 s[28:29], s[34:35], s[28:29]
	v_cmp_gt_i32_e64 s[24:25], 56, v158
	s_and_b64 s[26:27], s[28:29], s[26:27]
	v_cmp_gt_i32_e64 s[22:23], 51, v158
	s_and_b64 s[24:25], s[26:27], s[24:25]
	v_cmp_gt_i32_e64 s[20:21], 50, v158
	s_and_b64 s[22:23], s[24:25], s[22:23]
	v_cmp_gt_i32_e64 s[18:19], 49, v158
	s_and_b64 s[20:21], s[22:23], s[20:21]
	v_cmp_gt_i32_e64 s[16:17], 48, v158
	s_and_b64 s[18:19], s[20:21], s[18:19]
	v_cmp_gt_i32_e64 s[14:15], 43, v158
	s_and_b64 s[16:17], s[18:19], s[16:17]
	v_cmp_gt_i32_e64 s[12:13], 42, v158
	s_and_b64 s[14:15], s[16:17], s[14:15]
	v_cmp_gt_i32_e64 s[10:11], 41, v158
	s_and_b64 s[12:13], s[14:15], s[12:13]
	v_cmp_gt_i32_e64 s[8:9], 40, v158
	s_and_b64 s[10:11], s[12:13], s[10:11]
	v_cmp_gt_i32_e64 s[6:7], 35, v158
	s_and_b64 s[8:9], s[10:11], s[8:9]
	v_cmp_gt_i32_e64 s[4:5], 34, v158
	s_and_b64 s[6:7], s[8:9], s[6:7]
	v_cmp_gt_i32_e64 s[2:3], 33, v158
	s_and_b64 s[4:5], s[6:7], s[4:5]
	v_cmp_gt_i32_e32 vcc, 32, v158
	s_and_b64 s[2:3], s[4:5], s[2:3]
	s_and_b64 vcc, s[2:3], vcc
	v_cndmask_b32_e64 v95, v95, v130, s[64:65]
	v_cndmask_b32_e64 v94, v94, v130, s[62:63]
	v_cndmask_b32_e64 v93, v93, v130, s[60:61]
	v_cndmask_b32_e64 v92, v92, v130, s[58:59]
	v_cndmask_b32_e64 v91, v91, v130, s[56:57]
	v_cndmask_b32_e64 v90, v90, v130, s[54:55]
	v_cndmask_b32_e64 v89, v89, v130, s[52:53]
	v_cndmask_b32_e64 v88, v88, v130, s[50:51]
	v_cndmask_b32_e64 v87, v87, v130, s[48:49]
	v_cndmask_b32_e64 v86, v86, v130, s[46:47]
	v_cndmask_b32_e64 v85, v85, v130, s[44:45]
	v_cndmask_b32_e64 v84, v84, v130, s[42:43]
	v_cndmask_b32_e64 v83, v83, v130, s[40:41]
	v_cndmask_b32_e64 v82, v82, v130, s[38:39]
	v_cndmask_b32_e64 v81, v81, v130, s[36:37]
	v_cndmask_b32_e64 v79, v79, v130, s[34:35]
	v_cndmask_b32_e64 v78, v78, v130, s[28:29]
	v_cndmask_b32_e64 v77, v77, v130, s[26:27]
	v_cndmask_b32_e64 v76, v76, v130, s[24:25]
	v_cndmask_b32_e64 v75, v75, v130, s[22:23]
	v_cndmask_b32_e64 v74, v74, v130, s[20:21]
	v_cndmask_b32_e64 v73, v73, v130, s[18:19]
	v_cndmask_b32_e64 v72, v72, v130, s[16:17]
	v_cndmask_b32_e64 v71, v71, v130, s[14:15]
	v_cndmask_b32_e64 v70, v70, v130, s[12:13]
	v_cndmask_b32_e64 v69, v69, v130, s[10:11]
	v_cndmask_b32_e64 v68, v68, v130, s[8:9]
	v_cndmask_b32_e64 v67, v67, v130, s[6:7]
	v_cndmask_b32_e64 v66, v66, v130, s[4:5]
	v_cndmask_b32_e64 v65, v65, v130, s[2:3]
	v_cndmask_b32_e32 v64, v64, v130, vcc

; __device__ __forceinline__ void partialSM(f32x16& p0, f32x16& p1, float& m_reg, float& mn, float& alpha) {
;     ...
;     if (__builtin_expect(__all((pmax - m_reg) <= THR2), 1)) { mn = m_reg; alpha = 1.f; }
;     else { mn = fmaxf(m_reg, pmax); alpha = __builtin_amdgcn_exp2f(m_reg - mn); m_reg = mn; }
.Lmaxtail_1:
	s_cmp_eq_u64 vcc, exec
	s_cselect_b64 s[2:3], -1, 0
	v_cndmask_b32_e64 v158, v158, 1.0, s[2:3]
	v_cmp_gt_f32_e32 vcc, 1.0, v158
	s_cbranch_vccz .LBB0_543
	s_and_saveexec_b64 s[4:5], s[0:1]
	ds_write_b32 v214, v158 offset:128
	s_or_b64 exec, exec, s[4:5]
	s_waitcnt lgkmcnt(0)
	ds_read_b128 v[160:163], v131 offset:224
	ds_read_b128 v[164:167], v131 offset:192
	ds_read_b128 v[168:171], v131 offset:160
	ds_read_b128 v[172:175], v131 offset:128
	s_waitcnt lgkmcnt(0)
	v_pk_mul_f32 v[62:63], v[62:63], v[162:163]
	v_pk_mul_f32 v[58:59], v[58:59], v[166:167]
	v_pk_mul_f32 v[54:55], v[54:55], v[170:171]
	v_pk_mul_f32 v[50:51], v[50:51], v[174:175]
	v_pk_mul_f32 v[60:61], v[60:61], v[160:161]
	v_pk_mul_f32 v[56:57], v[56:57], v[164:165]
	v_pk_mul_f32 v[52:53], v[52:53], v[168:169]
	v_pk_mul_f32 v[48:49], v[48:49], v[172:173]
	v_pk_mul_f32 v[46:47], v[46:47], v[162:163]
	v_pk_mul_f32 v[42:43], v[42:43], v[166:167]
	v_pk_mul_f32 v[38:39], v[38:39], v[170:171]
	v_pk_mul_f32 v[34:35], v[34:35], v[174:175]
	v_pk_mul_f32 v[44:45], v[44:45], v[160:161]
	v_pk_mul_f32 v[40:41], v[40:41], v[164:165]
	v_pk_mul_f32 v[36:37], v[36:37], v[168:169]
	v_pk_mul_f32 v[32:33], v[32:33], v[172:173]
	v_pk_mul_f32 v[30:31], v[30:31], v[162:163]
	v_pk_mul_f32 v[26:27], v[26:27], v[166:167]
	v_pk_mul_f32 v[22:23], v[22:23], v[170:171]
	v_pk_mul_f32 v[18:19], v[18:19], v[174:175]
	v_pk_mul_f32 v[28:29], v[28:29], v[160:161]
	v_pk_mul_f32 v[24:25], v[24:25], v[164:165]
	v_pk_mul_f32 v[20:21], v[20:21], v[168:169]
	v_pk_mul_f32 v[16:17], v[16:17], v[172:173]
	v_pk_mul_f32 v[14:15], v[14:15], v[162:163]
	v_pk_mul_f32 v[10:11], v[10:11], v[166:167]
	v_pk_mul_f32 v[6:7], v[6:7], v[170:171]
	v_pk_mul_f32 v[2:3], v[2:3], v[174:175]
	v_pk_mul_f32 v[12:13], v[12:13], v[160:161]
	v_pk_mul_f32 v[8:9], v[8:9], v[164:165]
	v_pk_mul_f32 v[4:5], v[4:5], v[168:169]
	v_pk_mul_f32 v[0:1], v[0:1], v[172:173]

; #define SBAR() __builtin_amdgcn_sched_barrier(0)
; #define PV_RD(d0, kh, X) do { constexpr int b_ = v_rd_off(d0, 2 * (kh), 0); TRRD(X##l0, b_); TRRD(X##h0, b_ + 2048); TRRD(X##l1, b_ + 4096); TRRD(X##h1, b_ + 6144); } while (0)
; #define PV_MM(d0, X, PA, PB) do { \
;         o[d0] = __builtin_amdgcn_mfma_f32_32x32x16_bf16(PA, (bf16x8){X##l0[0], X##l0[1], X##l0[2], X##l0[3], X##h0[0], X##h0[1], X##h0[2], X##h0[3]}, o[d0], 0, 0, 0);   \
;         o[d0] = __builtin_amdgcn_mfma_f32_32x32x16_bf16(PB, (bf16x8){X##l1[0], X##l1[1], X##l1[2], X##l1[3], X##h1[0], X##h1[1], X##h1[2], X##h1[3]}, o[d0], 0, 0, 0); } while (0)
; #define PV_W4() do { asm volatile("s_waitcnt lgkmcnt(4)" ::: "memory"); SBAR(); } while (0)
; #define PV_W0() do { asm volatile("s_waitcnt lgkmcnt(0)" ::: "memory"); SBAR(); } while (0)
; __device__ __forceinline__ void finishSM(f32x16& p0, f32x16& p1, float alpha, float& l_reg, bf16x8& pa0, bf16x8& pa1, bf16x8& pa2, bf16x8& pa3) {
; #pragma unroll
;     for (int r = 0; r < 16; ++r) p1[r] = __builtin_amdgcn_exp2f(p1[r]);
;     float ps = 0;
; #pragma unroll
;     for (int r = 0; r < 16; ++r) ps += p0[r];
; #pragma unroll
;     for (int r = 0; r < 16; ++r) ps += p1[r];
;     { auto rr = __builtin_amdgcn_permlane32_swap(__float_as_uint(ps), __float_as_uint(ps), false, false);
;       ps = __uint_as_float(rr[0]) + __uint_as_float(rr[1]); }
;     l_reg = l_reg * alpha + ps;
;     ...
;     PK4(p0, 0, pa0); PK4(p0, 8, pa1); PK4(p1, 0, pa2); PK4(p1, 8, pa3);
; __device__ __forceinline__ void pv_tile(f32x16* o, int vb0, bf16x8 pa0, bf16x8 pa1, bf16x8 pa2, bf16x8 pa3) {
;     ...
;     s16x4 al0, al1, ah0, ah1, bl0, bl1, bh0, bh1;
;     PV_RD(0, 0, a);
;     PV_RD(0, 1, b); PV_W4(); PV_MM(0, a, pa0, pa1); SBAR();
;     PV_RD(1, 0, a); PV_W4(); PV_MM(0, b, pa2, pa3); SBAR();
;     PV_RD(1, 1, b); PV_W4(); PV_MM(1, a, pa0, pa1); SBAR();
;     PV_RD(2, 0, a); PV_W4(); PV_MM(1, b, pa2, pa3); SBAR();
;     PV_RD(2, 1, b); PV_W4(); PV_MM(2, a, pa0, pa1); SBAR();
;     PV_RD(3, 0, a); PV_W4(); PV_MM(2, b, pa2, pa3); SBAR();
;     PV_RD(3, 1, b); PV_W4(); PV_MM(3, a, pa0, pa1); SBAR();
;     PV_W0(); PV_MM(3, b, pa2, pa3);
.LBB0_553:
	v_add_f32_e32 v64, 0, v221
	v_add_f32_e32 v64, v236, v64
	v_add_f32_e32 v64, v233, v64
	v_add_f32_e32 v64, v235, v64
	v_add_f32_e32 v64, v231, v64
	v_add_f32_e32 v64, v234, v64
	v_add_f32_e32 v64, v230, v64
	v_add_f32_e32 v64, v232, v64
	v_add_f32_e32 v64, v227, v64
	v_add_f32_e32 v64, v229, v64
	v_add_f32_e32 v64, v225, v64
	v_add_f32_e32 v64, v228, v64
	v_exp_f32_e32 v74, v168
	v_add_f32_e32 v64, v223, v64
	v_exp_f32_e32 v75, v169
	v_add_f32_e32 v64, v226, v64
	v_exp_f32_e32 v76, v172
	v_add_f32_e32 v64, v222, v64
	v_exp_f32_e32 v77, v173
	v_add_f32_e32 v64, v224, v64
	v_exp_f32_e32 v78, v176
	v_add_f32_e32 v64, v74, v64
	v_exp_f32_e32 v79, v177
	v_add_f32_e32 v64, v75, v64
	v_exp_f32_e32 v80, v166
	v_add_f32_e32 v64, v76, v64
	v_exp_f32_e32 v81, v167
	v_add_f32_e32 v64, v77, v64
	v_exp_f32_e32 v82, v170
	v_add_f32_e32 v64, v78, v64
	v_exp_f32_e32 v83, v171
	v_add_f32_e32 v64, v79, v64
	v_exp_f32_e32 v84, v174
	v_add_f32_e32 v64, v80, v64
	v_exp_f32_e32 v85, v175
	v_add_f32_e32 v64, v81, v64
	v_exp_f32_e32 v86, v178
	v_add_f32_e32 v64, v82, v64
	v_exp_f32_e32 v87, v179
	v_add_f32_e32 v64, v83, v64
	v_readlane_b32 s7, v247, 12
	v_readlane_b32 s2, v247, 13
	v_exp_f32_e32 v88, v164
	v_add_f32_e32 v64, v84, v64
	s_or_b32 s2, s7, s2
	v_exp_f32_e32 v89, v165
	v_add_f32_e32 v64, v85, v64
	s_ashr_i32 s3, s2, 31
	v_readlane_b32 s4, v248, 63
	v_add_f32_e32 v64, v86, v64
	s_lshl_b64 s[2:3], s[2:3], 11
	v_readlane_b32 s5, v247, 0
	v_add_f32_e32 v64, v87, v64
	s_or_b64 s[2:3], s[2:3], s[4:5]
	v_add_f32_e32 v64, v88, v64
	s_lshl_b64 s[68:69], s[2:3], 1
	v_readlane_b32 s93, v247, 10
	v_add_f32_e32 v64, v89, v64
	s_add_u32 s2, s93, s68
	v_readlane_b32 s3, v248, 37
	v_mov_b32_e32 v65, v64
	s_addc_u32 s3, s3, s69
	s_nop 0
	v_permlane32_swap_b32_e32 v64, v65
	v_cvt_pk_bf16_f32 v66, v221, v236
	v_cvt_pk_bf16_f32 v67, v233, v235
	v_cvt_pk_bf16_f32 v68, v231, v234
	v_cvt_pk_bf16_f32 v69, v230, v232
	v_cvt_pk_bf16_f32 v70, v227, v229
	v_cvt_pk_bf16_f32 v71, v225, v228
	v_cvt_pk_bf16_f32 v72, v223, v226
	v_cvt_pk_bf16_f32 v73, v222, v224
	v_cvt_pk_bf16_f32 v74, v74, v75
	v_cvt_pk_bf16_f32 v75, v76, v77
	v_cvt_pk_bf16_f32 v76, v78, v79
	v_cvt_pk_bf16_f32 v77, v80, v81
	v_cvt_pk_bf16_f32 v78, v82, v83
	v_cvt_pk_bf16_f32 v79, v84, v85
	v_cvt_pk_bf16_f32 v80, v86, v87
	v_cvt_pk_bf16_f32 v81, v88, v89
	s_nop 0
	v_permlane32_swap_b32_e32 v66, v68
	v_permlane32_swap_b32_e32 v67, v69
	v_permlane32_swap_b32_e32 v70, v72
	v_permlane32_swap_b32_e32 v71, v73
	v_permlane32_swap_b32_e32 v74, v76
	v_permlane32_swap_b32_e32 v75, v77
	v_permlane32_swap_b32_e32 v78, v80
	v_permlane32_swap_b32_e32 v79, v81
	v_add_u32_e32 v98, s76, v192
	ds_read_b64_tr_b16 v[82:83], v98 offset:0
	ds_read_b64_tr_b16 v[84:85], v98 offset:0x800
	ds_read_b64_tr_b16 v[86:87], v98 offset:0x1000
	ds_read_b64_tr_b16 v[88:89], v98 offset:0x1800
	ds_read_b64_tr_b16 v[90:91], v98 offset:0x2000
	ds_read_b64_tr_b16 v[92:93], v98 offset:0x2800
	ds_read_b64_tr_b16 v[94:95], v98 offset:0x3000
	ds_read_b64_tr_b16 v[96:97], v98 offset:0x3800
	s_waitcnt lgkmcnt(4)
	s_nop 0
	v_mfma_f32_32x32x16_bf16 v[48:63], v[66:69], v[82:85], v[48:63]
	v_mfma_f32_32x32x16_bf16 v[48:63], v[70:73], v[86:89], v[48:63]
	ds_read_b64_tr_b16 v[82:83], v98 offset:0x200
	ds_read_b64_tr_b16 v[84:85], v98 offset:0xa00
	ds_read_b64_tr_b16 v[86:87], v98 offset:0x1200
	ds_read_b64_tr_b16 v[88:89], v98 offset:0x1a00
	s_waitcnt lgkmcnt(4)
	v_mfma_f32_32x32x16_bf16 v[48:63], v[74:77], v[90:93], v[48:63]
	v_mfma_f32_32x32x16_bf16 v[48:63], v[78:81], v[94:97], v[48:63]
	ds_read_b64_tr_b16 v[90:91], v98 offset:0x2200
	ds_read_b64_tr_b16 v[92:93], v98 offset:0x2a00
	ds_read_b64_tr_b16 v[94:95], v98 offset:0x3200
	ds_read_b64_tr_b16 v[96:97], v98 offset:0x3a00
	s_waitcnt lgkmcnt(4)
	v_mfma_f32_32x32x16_bf16 v[32:47], v[66:69], v[82:85], v[32:47]
	v_mfma_f32_32x32x16_bf16 v[32:47], v[70:73], v[86:89], v[32:47]
	ds_read_b64_tr_b16 v[82:83], v98 offset:0x400
	ds_read_b64_tr_b16 v[84:85], v98 offset:0xc00
	ds_read_b64_tr_b16 v[86:87], v98 offset:0x1400
	ds_read_b64_tr_b16 v[88:89], v98 offset:0x1c00
	s_waitcnt lgkmcnt(4)
	v_mfma_f32_32x32x16_bf16 v[32:47], v[74:77], v[90:93], v[32:47]
	v_mfma_f32_32x32x16_bf16 v[32:47], v[78:81], v[94:97], v[32:47]
	ds_read_b64_tr_b16 v[90:91], v98 offset:0x2400
	ds_read_b64_tr_b16 v[92:93], v98 offset:0x2c00
	ds_read_b64_tr_b16 v[94:95], v98 offset:0x3400
	ds_read_b64_tr_b16 v[96:97], v98 offset:0x3c00
	s_waitcnt lgkmcnt(4)
	v_mfma_f32_32x32x16_bf16 v[16:31], v[66:69], v[82:85], v[16:31]
	v_mfma_f32_32x32x16_bf16 v[16:31], v[70:73], v[86:89], v[16:31]
	ds_read_b64_tr_b16 v[82:83], v98 offset:0x600
	ds_read_b64_tr_b16 v[84:85], v98 offset:0xe00
	ds_read_b64_tr_b16 v[86:87], v98 offset:0x1600
	ds_read_b64_tr_b16 v[88:89], v98 offset:0x1e00
	s_waitcnt lgkmcnt(4)
	v_mfma_f32_32x32x16_bf16 v[16:31], v[74:77], v[90:93], v[16:31]
	v_mfma_f32_32x32x16_bf16 v[16:31], v[78:81], v[94:97], v[16:31]
	ds_read_b64_tr_b16 v[90:91], v98 offset:0x2600
	ds_read_b64_tr_b16 v[92:93], v98 offset:0x2e00
	ds_read_b64_tr_b16 v[94:95], v98 offset:0x3600
	ds_read_b64_tr_b16 v[96:97], v98 offset:0x3e00
	s_waitcnt lgkmcnt(4)
	v_mfma_f32_32x32x16_bf16 v[0:15], v[66:69], v[82:85], v[0:15]
	v_mfma_f32_32x32x16_bf16 v[0:15], v[70:73], v[86:89], v[0:15]
	s_waitcnt lgkmcnt(0)
	v_mfma_f32_32x32x16_bf16 v[0:15], v[74:77], v[90:93], v[0:15]
	v_mfma_f32_32x32x16_bf16 v[0:15], v[78:81], v[94:97], v[0:15]
	v_lshl_add_u64 v[66:67], s[2:3], 0, v[132:133]
	v_mov_b32_e32 v147, v129
	s_waitcnt vmcnt(0) lgkmcnt(0)
	s_barrier
; #define LAS __attribute__((address_space(3)))
; __device__ __forceinline__ unsigned cvt_pk_bf16(float lo, float hi) { unsigned r; asm volatile("v_cvt_pk_bf16_f32 %0, %1, %2" : "=v"(r) : "v"(lo), "v"(hi)); return r; }
; __device__ __forceinline__ float bf_lo(unsigned w) { return __uint_as_float(w << 16); }
; #define SBAR() __builtin_amdgcn_sched_barrier(0)
; __device__ __forceinline__ void fox_block(const BlockRef& cur, const BlockRef& nxt, char* lds, Seam& S, const int tid) {
;     ...
;     { const bf16_t* Kh = nxt.K; const bf16_t* Vh = nxt.V;
; #pragma unroll
;       for (int d0 = 0; d0 < 8; ++d0) S.qr[d0] = load8(nxt.Q + (size_t)(wid * QBLK + r32) * LD + d0 * 16 + hi * 8);
;       SBAR(); DMA_K(0, 0); DMA_K(1, SLOT); DMA_V(0, 0); SBAR(); }
;     if (hi == 0) li_l[r32] = l_reg; asm volatile("s_waitcnt lgkmcnt(0)" ::: "memory");
;     float rli[16];
; #pragma unroll
;     for (int r = 0; r < 16; ++r) rli[r] = __builtin_amdgcn_rcpf(li_l[crow(r, hi)]);
;     typedef __attribute__((address_space(1))) bf16_t gbf16; typedef __attribute__((address_space(1))) u32x4 gu32x4;
;     LAS float* stg = (LAS float*)(lds3 + SLOT + wid * 4096);
;     const int er = lane >> 2, eq = lane & 3;
;     gbf16* obase = (gbf16*)(cur.O + (size_t)(wid * QBLK + er) * LD + 8 * eq); const gbf16* zbase = (const gbf16*)(cur.Z + (size_t)(wid * QBLK + er) * LD + 8 * eq);
; #pragma unroll
;     for (int d0 = 0; d0 < 4; ++d0) {
; #pragma unroll
;         for (int r = 0; r < 16; ++r) stg[crow(r, hi) * 32 + r32] = o[d0][r] * rli[r];
;         asm volatile("s_waitcnt lgkmcnt(0)" ::: "memory");
;         gbf16* op = obase; const gbf16* zp = zbase;
; #pragma unroll
;         for (int i = 0; i < 2; ++i) {
;             asm volatile("" : "+v"(op), "+v"(zp));
;             const f32x4 v0 = *(const LAS f32x4*)(stg + (er + 16 * i) * 32 + 8 * eq), v1 = *(const LAS f32x4*)(stg + (er + 16 * i) * 32 + 8 * eq + 4);
;             const u32x4 z = __builtin_nontemporal_load((const gu32x4*)(zp + d0 * 32));
;             u32x4 w; w.x = cvt_pk_bf16(v0.x * bf_lo(z.x), v0.y * bf_hi(z.x)); w.y = cvt_pk_bf16(v0.z * bf_lo(z.y), v0.w * bf_hi(z.y));
;             w.z = cvt_pk_bf16(v1.x * bf_lo(z.z), v1.y * bf_hi(z.z)); w.w = cvt_pk_bf16(v1.z * bf_lo(z.w), v1.w * bf_hi(z.w));
;             *(gu32x4*)(op + d0 * 32) = w;
;             op += 16 * LD; zp += 16 * LD; }
;         asm volatile("s_waitcnt lgkmcnt(0)" ::: "memory"); }
	v_lshl_add_u64 v[66:67], v[66:67], 0, v[146:147]
	global_load_dwordx4 v[96:99], v[66:67], off
	global_load_dwordx4 v[100:103], v[66:67], off offset:32
	global_load_dwordx4 v[104:107], v[66:67], off offset:64
	global_load_dwordx4 v[108:111], v[66:67], off offset:96
	global_load_dwordx4 v[112:115], v[66:67], off offset:128
	global_load_dwordx4 v[116:119], v[66:67], off offset:160
	global_load_dwordx4 v[120:123], v[66:67], off offset:192
	global_load_dwordx4 v[124:127], v[66:67], off offset:224
	v_readlane_b32 s2, v247, 15
	s_mov_b32 m0, s2
	v_readlane_b32 s2, v247, 16
	global_load_lds_dwordx4 v[144:145], off
	s_mov_b32 m0, s2
	v_readlane_b32 s2, v247, 17
	global_load_lds_dwordx4 v[142:143], off
	s_mov_b32 m0, s2
	v_readlane_b32 s2, v247, 18
	global_load_lds_dwordx4 v[136:137], off
	s_mov_b32 m0, s2
	v_readlane_b32 s2, v247, 19
	global_load_lds_dwordx4 v[138:139], off
	s_mov_b32 m0, s70
	s_nop 0
	global_load_lds_dwordx4 v[140:141], off
	s_mov_b32 m0, s2
	s_nop 0
	global_load_lds_dwordx4 v[134:135], off
	s_and_saveexec_b64 s[2:3], s[0:1]
	v_add_f32_e32 v64, v64, v65
	v_fmac_f32_e32 v64, v215, v158
	ds_write_b32 v214, v64
	s_or_b64 exec, exec, s[2:3]
	s_waitcnt lgkmcnt(0)
	ds_read_b128 v[64:67], v131
	ds_read_b128 v[68:71], v131 offset:32
	v_readlane_b32 s2, v248, 42
	s_add_u32 s2, s2, s78
	v_readlane_b32 s3, v248, 43
	s_waitcnt lgkmcnt(0)
	v_rcp_f32_e32 v72, v64
	v_rcp_f32_e32 v73, v65
	v_rcp_f32_e32 v74, v66
	v_rcp_f32_e32 v75, v67
	v_rcp_f32_e32 v76, v68
	ds_read_b128 v[64:67], v131 offset:64
	v_rcp_f32_e32 v77, v69
	v_rcp_f32_e32 v78, v70
	v_rcp_f32_e32 v79, v71
	ds_read_b128 v[68:71], v131 offset:96
	s_addc_u32 s3, s3, s79
	v_readlane_b32 s4, v248, 54
	s_add_u32 s4, s4, s78
	v_readlane_b32 s5, v248, 56
	v_readlane_b32 s6, v247, 14
	s_addc_u32 s5, s5, s79
	s_lshl_b32 s6, s6, 12
	s_waitcnt lgkmcnt(0)
	v_rcp_f32_e32 v84, v68
	s_add_i32 s6, s6, 0
	v_lshlrev_b32_e32 v68, 3, v155
	v_lshlrev_b32_e32 v133, 2, v199
	v_lshlrev_b32_e32 v170, 9, v213
	v_and_b32_e32 v132, 24, v68
	v_add3_u32 v68, s6, v133, v170
	v_rcp_f32_e32 v80, v64
	v_rcp_f32_e32 v81, v65
	v_mul_f32_e32 v48, v48, v72
	v_mul_f32_e32 v49, v49, v73
	v_add_u32_e32 v86, 0x4000, v68
	v_rcp_f32_e32 v82, v66
	v_rcp_f32_e32 v83, v67
	ds_write2_b32 v86, v48, v49 offset1:32
	v_mul_f32_e32 v48, v50, v74
	v_mul_f32_e32 v49, v51, v75
	v_rcp_f32_e32 v85, v69
	ds_write2_b32 v86, v48, v49 offset0:64 offset1:96
	v_mul_f32_e32 v48, v52, v76
	v_mul_f32_e32 v49, v53, v77
	v_add_u32_e32 v87, 0x4400, v68
	v_rcp_f32_e32 v70, v70
	v_rcp_f32_e32 v71, v71
	v_or_b32_e32 v64, s77, v191
	ds_write2_b32 v87, v48, v49 offset1:32
	v_mul_f32_e32 v48, v54, v78
	v_mul_f32_e32 v49, v55, v79
	v_ashrrev_i32_e32 v65, 31, v64
	ds_write2_b32 v87, v48, v49 offset0:64 offset1:96
	v_mul_f32_e32 v48, v56, v80
	v_mul_f32_e32 v49, v57, v81
	v_add_u32_e32 v88, 0x4800, v68
	v_lshlrev_b64 v[66:67], 12, v[64:65]
	ds_write2_b32 v88, v48, v49 offset1:32
	v_mul_f32_e32 v48, v58, v82
	v_mul_f32_e32 v49, v59, v83
	v_lshl_add_u64 v[64:65], s[4:5], 0, v[66:67]
	v_lshlrev_b32_e32 v128, 1, v132
	v_lshl_add_u64 v[66:67], s[2:3], 0, v[66:67]
	ds_write2_b32 v88, v48, v49 offset0:64 offset1:96
	v_mul_f32_e32 v48, v60, v84
	v_mul_f32_e32 v49, v61, v85
	v_add_u32_e32 v89, 0x4c00, v68
	v_lshl_add_u64 v[64:65], v[64:65], 0, v[128:129]
	v_lshl_add_u64 v[66:67], v[66:67], 0, v[128:129]
	ds_write2_b32 v89, v48, v49 offset1:32
	v_mul_f32_e32 v48, v62, v70
	v_mul_f32_e32 v49, v63, v71
	ds_write2_b32 v89, v48, v49 offset0:64 offset1:96
	v_mov_b64_e32 v[62:63], v[64:65]
	v_mov_b64_e32 v[68:69], v[66:67]
	s_waitcnt lgkmcnt(0)
	global_load_dwordx4 v[50:53], v[68:69], off nt
	v_add_co_u32_e32 v250, vcc, 0x10000, v68
	s_nop 1
	v_addc_co_u32_e32 v251, vcc, 0, v69, vcc
	global_load_dwordx4 v[222:225], v[250:251], off nt
	global_load_dwordx4 v[226:229], v[68:69], off offset:64 nt
	global_load_dwordx4 v[230:233], v[250:251], off offset:64 nt
	global_load_dwordx4 v[234:237], v[68:69], off offset:128 nt
	global_load_dwordx4 v[238:241], v[250:251], off offset:128 nt
	global_load_dwordx4 v[242:245], v[68:69], off offset:192 nt
	v_lshlrev_b32_e32 v145, 7, v191
	v_lshlrev_b32_e32 v48, 2, v132
	v_add3_u32 v48, s6, v48, v145
	ds_read_b128 v[54:57], v48 offset:16384
	ds_read_b128 v[58:61], v48 offset:16400
	s_mov_b64 s[2:3], 0x10000
	v_mul_f32_e32 v40, v40, v80
	v_mul_f32_e32 v41, v41, v81
	v_mul_f32_e32 v42, v42, v82
	v_mul_f32_e32 v43, v43, v83
	v_mul_f32_e32 v44, v44, v84
	v_mul_f32_e32 v45, v45, v85
	v_mul_f32_e32 v46, v46, v70
	v_mul_f32_e32 v47, v47, v71
	v_mul_f32_e32 v24, v24, v80
	v_mul_f32_e32 v25, v25, v81
	v_mul_f32_e32 v26, v26, v82
	v_mul_f32_e32 v27, v27, v83
	v_mul_f32_e32 v28, v28, v84
	v_mul_f32_e32 v29, v29, v85
	v_mul_f32_e32 v30, v30, v70
	v_mul_f32_e32 v31, v31, v71
	v_mul_f32_e32 v8, v8, v80
	v_mul_f32_e32 v9, v9, v81
	v_mul_f32_e32 v10, v10, v82
	v_mul_f32_e32 v11, v11, v83
	v_mul_f32_e32 v12, v12, v84
	v_mul_f32_e32 v13, v13, v85
	v_mul_f32_e32 v14, v14, v70
	v_mul_f32_e32 v15, v15, v71
	s_movk_i32 s6, 0x60
	s_or_b32 s4, s7, 64
	s_mov_b32 s87, 4
	s_lshr_b32 s89, s4, 6
	s_waitcnt vmcnt(6)
	v_lshlrev_b32_e32 v49, 16, v50
	v_and_b32_e32 v50, 0xffff0000, v50
	v_lshlrev_b32_e32 v90, 16, v51
	v_and_b32_e32 v51, 0xffff0000, v51
	v_lshlrev_b32_e32 v91, 16, v52
	v_and_b32_e32 v52, 0xffff0000, v52
	s_waitcnt lgkmcnt(1)
	v_mul_f32_e32 v50, v55, v50
	v_mul_f32_e32 v51, v57, v51
	v_lshlrev_b32_e32 v92, 16, v53
	v_and_b32_e32 v53, 0xffff0000, v53
	v_mul_f32_e32 v49, v54, v49
	v_mul_f32_e32 v54, v56, v90
	s_waitcnt lgkmcnt(0)
; #define LAS __attribute__((address_space(3)))
; __device__ __forceinline__ unsigned cvt_pk_bf16(float lo, float hi) { unsigned r; asm volatile("v_cvt_pk_bf16_f32 %0, %1, %2" : "=v"(r) : "v"(lo), "v"(hi)); return r; }
; __device__ __forceinline__ float bf_lo(unsigned w) { return __uint_as_float(w << 16); }
; __device__ __forceinline__ float bf_hi(unsigned w) { return __uint_as_float(w & 0xffff0000u); }
; __device__ __forceinline__ int crow(int r, int hi) { return (r & 3) + 8 * (r >> 2) + 4 * hi; }
; __device__ __forceinline__ void fox_block(const BlockRef& cur, const BlockRef& nxt, char* lds, Seam& S, const int tid) {
;     ...
;     for (int d0 = 0; d0 < 4; ++d0) {
; #pragma unroll
;         for (int r = 0; r < 16; ++r) stg[crow(r, hi) * 32 + r32] = o[d0][r] * rli[r];
;         asm volatile("s_waitcnt lgkmcnt(0)" ::: "memory");
;         gbf16* op = obase; const gbf16* zp = zbase;
; #pragma unroll
;         for (int i = 0; i < 2; ++i) {
;             asm volatile("" : "+v"(op), "+v"(zp));
;             const f32x4 v0 = *(const LAS f32x4*)(stg + (er + 16 * i) * 32 + 8 * eq), v1 = *(const LAS f32x4*)(stg + (er + 16 * i) * 32 + 8 * eq + 4);
;             const u32x4 z = __builtin_nontemporal_load((const gu32x4*)(zp + d0 * 32));
;             u32x4 w; w.x = cvt_pk_bf16(v0.x * bf_lo(z.x), v0.y * bf_hi(z.x)); w.y = cvt_pk_bf16(v0.z * bf_lo(z.y), v0.w * bf_hi(z.y));
;             w.z = cvt_pk_bf16(v1.x * bf_lo(z.z), v1.y * bf_hi(z.z)); w.w = cvt_pk_bf16(v1.z * bf_lo(z.w), v1.w * bf_hi(z.w));
;             *(gu32x4*)(op + d0 * 32) = w;
;             op += 16 * LD; zp += 16 * LD; }
;         asm volatile("s_waitcnt lgkmcnt(0)" ::: "memory"); }
	v_mul_f32_e32 v55, v58, v91
	v_mul_f32_e32 v52, v59, v52
	v_cvt_pk_bf16_f32 v50, v49, v50
	v_cvt_pk_bf16_f32 v51, v54, v51
	v_mul_f32_e32 v56, v60, v92
	v_cvt_pk_bf16_f32 v52, v55, v52
	v_mul_f32_e32 v49, v61, v53
	v_cvt_pk_bf16_f32 v53, v56, v49
	global_store_dwordx4 v[62:63], v[50:53], off
	v_lshl_add_u64 v[54:55], v[62:63], 0, s[2:3]
	v_mul_f32_e32 v49, v32, v72
	v_lshl_add_u64 v[50:51], v[68:69], 0, s[2:3]
	v_mul_f32_e32 v60, v33, v73
	v_mul_f32_e32 v61, v34, v74
	v_mul_f32_e32 v62, v35, v75
	v_mul_f32_e32 v63, v36, v76
	v_mul_f32_e32 v68, v37, v77
	v_mul_f32_e32 v69, v38, v78
	v_mul_f32_e32 v90, v39, v79
	ds_read_b128 v[32:35], v48 offset:18432
	ds_read_b128 v[36:39], v48 offset:18448
	v_mov_b64_e32 v[56:57], v[66:67]
	v_mov_b64_e32 v[58:59], v[64:65]
	s_waitcnt vmcnt(6)
	v_mov_b32_e32 v50, v222
	v_mov_b32_e32 v51, v223
	v_mov_b32_e32 v52, v224
	v_mov_b32_e32 v53, v225
	global_load_dwordx4 v[222:225], v[250:251], off offset:192 nt
	v_lshlrev_b32_e32 v91, 16, v50
	v_and_b32_e32 v50, 0xffff0000, v50
	v_lshlrev_b32_e32 v92, 16, v51
	v_and_b32_e32 v51, 0xffff0000, v51
	v_lshlrev_b32_e32 v93, 16, v52
	v_and_b32_e32 v52, 0xffff0000, v52
	v_lshlrev_b32_e32 v94, 16, v53
	v_and_b32_e32 v53, 0xffff0000, v53
	s_waitcnt lgkmcnt(1)
	v_mul_f32_e32 v32, v32, v91
	v_mul_f32_e32 v33, v33, v50
	v_mul_f32_e32 v34, v34, v92
	v_mul_f32_e32 v35, v35, v51
	s_waitcnt lgkmcnt(0)
	v_mul_f32_e32 v36, v36, v93
	v_mul_f32_e32 v37, v37, v52
	v_mul_f32_e32 v38, v38, v94
	v_mul_f32_e32 v39, v39, v53
	v_cvt_pk_bf16_f32 v32, v32, v33
	v_cvt_pk_bf16_f32 v33, v34, v35
	v_cvt_pk_bf16_f32 v34, v36, v37
	v_cvt_pk_bf16_f32 v35, v38, v39
	global_store_dwordx4 v[54:55], v[32:35], off
	s_waitcnt lgkmcnt(0)
	ds_write2_b32 v86, v49, v60 offset1:32
	ds_write2_b32 v86, v61, v62 offset0:64 offset1:96
	ds_write2_b32 v87, v63, v68 offset1:32
	ds_write2_b32 v87, v69, v90 offset0:64 offset1:96
	ds_write2_b32 v88, v40, v41 offset1:32
	ds_write2_b32 v88, v42, v43 offset0:64 offset1:96
	ds_write2_b32 v89, v44, v45 offset1:32
	ds_write2_b32 v89, v46, v47 offset0:64 offset1:96
	s_waitcnt lgkmcnt(0)
	ds_read_b128 v[36:39], v48 offset:16384
	ds_read_b128 v[40:43], v48 offset:16400
	v_lshl_add_u64 v[44:45], v[58:59], 0, s[2:3]
	v_lshl_add_u64 v[46:47], v[56:57], 0, s[2:3]
	s_waitcnt vmcnt(7)
	v_mov_b32_e32 v32, v226
	v_mov_b32_e32 v33, v227
	v_mov_b32_e32 v34, v228
	v_mov_b32_e32 v35, v229
	v_lshlrev_b32_e32 v49, 16, v32
	v_and_b32_e32 v32, 0xffff0000, v32
	v_lshlrev_b32_e32 v50, 16, v33
	v_and_b32_e32 v33, 0xffff0000, v33
	v_lshlrev_b32_e32 v51, 16, v34
	v_and_b32_e32 v34, 0xffff0000, v34
	v_lshlrev_b32_e32 v52, 16, v35
	v_and_b32_e32 v35, 0xffff0000, v35
	s_waitcnt lgkmcnt(1)
	v_mul_f32_e32 v32, v37, v32
	v_mul_f32_e32 v33, v39, v33
	s_waitcnt lgkmcnt(0)
	v_mul_f32_e32 v34, v41, v34
	v_mul_f32_e32 v35, v43, v35
	v_mul_f32_e32 v36, v36, v49
	v_mul_f32_e32 v37, v38, v50
	v_mul_f32_e32 v38, v40, v51
	v_mul_f32_e32 v39, v42, v52
	v_cvt_pk_bf16_f32 v32, v36, v32
	v_cvt_pk_bf16_f32 v33, v37, v33
	v_cvt_pk_bf16_f32 v34, v38, v34
	v_cvt_pk_bf16_f32 v35, v39, v35
	global_store_dwordx4 v[58:59], v[32:35], off offset:64
	v_mul_f32_e32 v40, v16, v72
	v_mul_f32_e32 v41, v17, v73
	v_mul_f32_e32 v42, v18, v74
	v_mul_f32_e32 v43, v19, v75
	v_mul_f32_e32 v46, v20, v76
	v_mul_f32_e32 v47, v21, v77
	v_mul_f32_e32 v49, v22, v78
	v_mul_f32_e32 v50, v23, v79
	ds_read_b128 v[16:19], v48 offset:18432
	ds_read_b128 v[20:23], v48 offset:18448
	v_mov_b64_e32 v[36:37], v[66:67]
	v_mov_b64_e32 v[38:39], v[64:65]
	s_waitcnt vmcnt(7)
	v_mov_b32_e32 v32, v230
	v_mov_b32_e32 v33, v231
	v_mov_b32_e32 v34, v232
	v_mov_b32_e32 v35, v233
	v_lshlrev_b32_e32 v51, 16, v32
	v_and_b32_e32 v32, 0xffff0000, v32
	v_lshlrev_b32_e32 v52, 16, v33
	v_and_b32_e32 v33, 0xffff0000, v33
	v_lshlrev_b32_e32 v53, 16, v34
	v_and_b32_e32 v34, 0xffff0000, v34
	v_lshlrev_b32_e32 v54, 16, v35
	v_and_b32_e32 v35, 0xffff0000, v35
	s_waitcnt lgkmcnt(1)
	v_mul_f32_e32 v16, v16, v51
	v_mul_f32_e32 v17, v17, v32
	v_mul_f32_e32 v18, v18, v52
	v_mul_f32_e32 v19, v19, v33
	s_waitcnt lgkmcnt(0)
	v_mul_f32_e32 v20, v20, v53
	v_mul_f32_e32 v21, v21, v34
	v_mul_f32_e32 v22, v22, v54
	v_mul_f32_e32 v23, v23, v35
	v_cvt_pk_bf16_f32 v16, v16, v17
	v_cvt_pk_bf16_f32 v17, v18, v19
	v_cvt_pk_bf16_f32 v18, v20, v21
	v_cvt_pk_bf16_f32 v19, v22, v23
	global_store_dwordx4 v[44:45], v[16:19], off offset:64
	s_waitcnt lgkmcnt(0)
	ds_write2_b32 v86, v40, v41 offset1:32
	ds_write2_b32 v86, v42, v43 offset0:64 offset1:96
	ds_write2_b32 v87, v46, v47 offset1:32
	ds_write2_b32 v87, v49, v50 offset0:64 offset1:96
	ds_write2_b32 v88, v24, v25 offset1:32
	ds_write2_b32 v88, v26, v27 offset0:64 offset1:96
	ds_write2_b32 v89, v28, v29 offset1:32
	ds_write2_b32 v89, v30, v31 offset0:64 offset1:96
	s_waitcnt lgkmcnt(0)
	ds_read_b128 v[20:23], v48 offset:16384
	ds_read_b128 v[24:27], v48 offset:16400
	v_lshl_add_u64 v[28:29], v[38:39], 0, s[2:3]
	v_lshl_add_u64 v[30:31], v[36:37], 0, s[2:3]
	s_waitcnt vmcnt(7)
	v_mov_b32_e32 v16, v234
	v_mov_b32_e32 v17, v235
	v_mov_b32_e32 v18, v236
	v_mov_b32_e32 v19, v237
	v_lshlrev_b32_e32 v32, 16, v16
	v_and_b32_e32 v16, 0xffff0000, v16
	v_lshlrev_b32_e32 v33, 16, v17
	v_and_b32_e32 v17, 0xffff0000, v17
	v_lshlrev_b32_e32 v34, 16, v18
	v_and_b32_e32 v18, 0xffff0000, v18
	v_lshlrev_b32_e32 v35, 16, v19
	v_and_b32_e32 v19, 0xffff0000, v19
	s_waitcnt lgkmcnt(1)
	v_mul_f32_e32 v16, v21, v16
	v_mul_f32_e32 v17, v23, v17
	s_waitcnt lgkmcnt(0)
; #define LAS __attribute__((address_space(3)))
; __device__ __forceinline__ unsigned cvt_pk_bf16(float lo, float hi) { unsigned r; asm volatile("v_cvt_pk_bf16_f32 %0, %1, %2" : "=v"(r) : "v"(lo), "v"(hi)); return r; }
; __device__ __forceinline__ float bf_lo(unsigned w) { return __uint_as_float(w << 16); }
; __device__ __forceinline__ float bf_hi(unsigned w) { return __uint_as_float(w & 0xffff0000u); }
; __device__ __forceinline__ int crow(int r, int hi) { return (r & 3) + 8 * (r >> 2) + 4 * hi; }
; #define WAITV_BAR(N) asm volatile("s_waitcnt vmcnt(" #N ") lgkmcnt(0)\n\ts_barrier" ::: "memory")
; __device__ __forceinline__ void fox_block(const BlockRef& cur, const BlockRef& nxt, char* lds, Seam& S, const int tid) {
;     ...
;     for (int d0 = 0; d0 < 4; ++d0) {
; #pragma unroll
;         for (int r = 0; r < 16; ++r) stg[crow(r, hi) * 32 + r32] = o[d0][r] * rli[r];
;         asm volatile("s_waitcnt lgkmcnt(0)" ::: "memory");
;         gbf16* op = obase; const gbf16* zp = zbase;
; #pragma unroll
;         for (int i = 0; i < 2; ++i) {
;             asm volatile("" : "+v"(op), "+v"(zp));
;             const f32x4 v0 = *(const LAS f32x4*)(stg + (er + 16 * i) * 32 + 8 * eq), v1 = *(const LAS f32x4*)(stg + (er + 16 * i) * 32 + 8 * eq + 4);
;             const u32x4 z = __builtin_nontemporal_load((const gu32x4*)(zp + d0 * 32));
;             u32x4 w; w.x = cvt_pk_bf16(v0.x * bf_lo(z.x), v0.y * bf_hi(z.x)); w.y = cvt_pk_bf16(v0.z * bf_lo(z.y), v0.w * bf_hi(z.y));
;             w.z = cvt_pk_bf16(v1.x * bf_lo(z.z), v1.y * bf_hi(z.z)); w.w = cvt_pk_bf16(v1.z * bf_lo(z.w), v1.w * bf_hi(z.w));
;             *(gu32x4*)(op + d0 * 32) = w;
;             op += 16 * LD; zp += 16 * LD; }
;         asm volatile("s_waitcnt lgkmcnt(0)" ::: "memory"); }
;     WAITV_BAR(0);
	v_mul_f32_e32 v18, v25, v18
	v_mul_f32_e32 v19, v27, v19
	v_mul_f32_e32 v20, v20, v32
	v_mul_f32_e32 v21, v22, v33
	v_mul_f32_e32 v22, v24, v34
	v_mul_f32_e32 v23, v26, v35
	v_cvt_pk_bf16_f32 v16, v20, v16
	v_cvt_pk_bf16_f32 v17, v21, v17
	v_cvt_pk_bf16_f32 v18, v22, v18
	v_cvt_pk_bf16_f32 v19, v23, v19
	global_store_dwordx4 v[38:39], v[16:19], off offset:128
	v_mul_f32_e32 v20, v0, v72
	v_mul_f32_e32 v21, v1, v73
	v_mul_f32_e32 v22, v2, v74
	v_mul_f32_e32 v23, v3, v75
	v_mul_f32_e32 v24, v4, v76
	v_mul_f32_e32 v25, v5, v77
	v_mul_f32_e32 v26, v6, v78
	v_mul_f32_e32 v27, v7, v79
	ds_read_b128 v[0:3], v48 offset:18432
	ds_read_b128 v[4:7], v48 offset:18448
	s_waitcnt vmcnt(7)
	v_mov_b32_e32 v16, v238
	v_mov_b32_e32 v17, v239
	v_mov_b32_e32 v18, v240
	v_mov_b32_e32 v19, v241
	v_lshlrev_b32_e32 v30, 16, v16
	v_and_b32_e32 v16, 0xffff0000, v16
	v_lshlrev_b32_e32 v31, 16, v17
	v_and_b32_e32 v17, 0xffff0000, v17
	v_lshlrev_b32_e32 v32, 16, v18
	v_and_b32_e32 v18, 0xffff0000, v18
	v_lshlrev_b32_e32 v33, 16, v19
	v_and_b32_e32 v19, 0xffff0000, v19
	s_waitcnt lgkmcnt(1)
	v_mul_f32_e32 v0, v0, v30
	v_mul_f32_e32 v1, v1, v16
	v_mul_f32_e32 v2, v2, v31
	v_mul_f32_e32 v3, v3, v17
	s_waitcnt lgkmcnt(0)
	v_mul_f32_e32 v4, v4, v32
	v_mul_f32_e32 v5, v5, v18
	v_mul_f32_e32 v6, v6, v33
	v_mul_f32_e32 v7, v7, v19
	v_cvt_pk_bf16_f32 v0, v0, v1
	v_cvt_pk_bf16_f32 v1, v2, v3
	v_cvt_pk_bf16_f32 v2, v4, v5
	v_cvt_pk_bf16_f32 v3, v6, v7
	global_store_dwordx4 v[28:29], v[0:3], off offset:128
	s_waitcnt lgkmcnt(0)
	ds_write2_b32 v86, v20, v21 offset1:32
	ds_write2_b32 v86, v22, v23 offset0:64 offset1:96
	ds_write2_b32 v87, v24, v25 offset1:32
	ds_write2_b32 v87, v26, v27 offset0:64 offset1:96
	ds_write2_b32 v88, v8, v9 offset1:32
	ds_write2_b32 v88, v10, v11 offset0:64 offset1:96
	ds_write2_b32 v89, v12, v13 offset1:32
	ds_write2_b32 v89, v14, v15 offset0:64 offset1:96
	s_waitcnt lgkmcnt(0)
	ds_read_b128 v[4:7], v48 offset:16384
	ds_read_b128 v[8:11], v48 offset:16400
	v_lshl_add_u64 v[12:13], v[64:65], 0, s[2:3]
	v_lshl_add_u64 v[14:15], v[66:67], 0, s[2:3]
	v_readfirstlane_b32 s3, v155
	s_ashr_i32 s70, s3, 6
	s_lshl_b32 s5, s70, 7
	s_and_b32 s3, s3, 0x3fffffc0
	v_readlane_b32 s2, v248, 61
	s_lshl_b32 s3, s3, 2
	s_and_b32 s2, s2, 0x700
	s_lshl_b32 s71, s70, 5
	s_add_i32 s3, s3, 0
	s_add_i32 s3, s3, 0x18000
	s_waitcnt vmcnt(7)
	v_mov_b32_e32 v0, v242
	v_mov_b32_e32 v1, v243
	v_mov_b32_e32 v2, v244
	v_mov_b32_e32 v3, v245
	v_lshlrev_b32_e32 v16, 16, v0
	v_and_b32_e32 v0, 0xffff0000, v0
	v_lshlrev_b32_e32 v17, 16, v1
	v_and_b32_e32 v1, 0xffff0000, v1
	v_lshlrev_b32_e32 v18, 16, v2
	v_and_b32_e32 v2, 0xffff0000, v2
	v_lshlrev_b32_e32 v19, 16, v3
	v_and_b32_e32 v3, 0xffff0000, v3
	s_waitcnt lgkmcnt(1)
	v_mul_f32_e32 v0, v5, v0
	v_mul_f32_e32 v1, v7, v1
	s_waitcnt lgkmcnt(0)
	v_mul_f32_e32 v2, v9, v2
	v_mul_f32_e32 v3, v11, v3
	v_mul_f32_e32 v4, v4, v16
	v_mul_f32_e32 v5, v6, v17
	v_mul_f32_e32 v6, v8, v18
	v_mul_f32_e32 v7, v10, v19
	v_cvt_pk_bf16_f32 v0, v4, v0
	v_cvt_pk_bf16_f32 v1, v5, v1
	v_cvt_pk_bf16_f32 v2, v6, v2
	v_cvt_pk_bf16_f32 v3, v7, v3
	global_store_dwordx4 v[64:65], v[0:3], off offset:192
	v_or_b32_e32 v4, s5, v198
	s_ashr_i32 s5, s5, 4
	v_bitop3_b32 v36, s5, -13, v191 bitop3:0xc8
	s_lshr_b32 s5, s5, 1
	v_ashrrev_i32_e32 v5, 4, v4
	s_and_b32 s5, s5, 4
	v_or_b32_e32 v14, 64, v4
	v_bitop3_b32 v4, v5, v203, 15 bitop3:0x6c
	v_lshlrev_b32_e32 v5, 8, v5
	v_or3_b32 v6, v36, s5, v200
	v_lshl_or_b32 v128, v4, 4, v5
	v_lshlrev_b32_e32 v17, 8, v6
	ds_read_b128 v[4:7], v48 offset:18432
	ds_read_b128 v[8:11], v48 offset:18448
	v_ashrrev_i32_e32 v15, 4, v14
	v_bitop3_b32 v16, v15, v203, 15 bitop3:0x6c
	v_or_b32_e32 v134, v17, v204
	s_waitcnt vmcnt(6)
	v_mov_b32_e32 v0, v222
	v_mov_b32_e32 v1, v223
	v_mov_b32_e32 v2, v224
	v_mov_b32_e32 v3, v225
	v_lshlrev_b32_e32 v18, 16, v0
	v_and_b32_e32 v0, 0xffff0000, v0
	v_lshlrev_b32_e32 v19, 16, v1
	v_and_b32_e32 v1, 0xffff0000, v1
	v_lshlrev_b32_e32 v20, 16, v2
	v_and_b32_e32 v2, 0xffff0000, v2
	v_lshlrev_b32_e32 v21, 16, v3
	v_and_b32_e32 v3, 0xffff0000, v3
	s_waitcnt lgkmcnt(1)
	v_mul_f32_e32 v0, v5, v0
	v_mul_f32_e32 v1, v7, v1
	s_waitcnt lgkmcnt(0)
	v_mul_f32_e32 v2, v9, v2
	v_mul_f32_e32 v3, v11, v3
	v_mul_f32_e32 v4, v4, v18
	v_mul_f32_e32 v5, v6, v19
	v_mul_f32_e32 v6, v8, v20
	v_mul_f32_e32 v7, v10, v21
	v_cvt_pk_bf16_f32 v0, v4, v0
	v_cvt_pk_bf16_f32 v1, v5, v1
	v_cvt_pk_bf16_f32 v2, v6, v2
	v_cvt_pk_bf16_f32 v3, v7, v3
	global_store_dwordx4 v[12:13], v[0:3], off offset:192
	s_waitcnt lgkmcnt(0)
	s_waitcnt vmcnt(0) lgkmcnt(0)
	s_barrier
; #define LAS __attribute__((address_space(3)))
; #define SBAR() __builtin_amdgcn_sched_barrier(0)
; __device__ __forceinline__ int v_rd_base(int lane) { return ((lane & 3) << 3) | (((lane >> 2) & 3) << 6) | (((lane >> 4) & 1) << 5) | (((lane >> 5) & 1) << 8); }
; #define WAITV_BAR(N) asm volatile("s_waitcnt vmcnt(" #N ") lgkmcnt(0)\n\ts_barrier" ::: "memory")
; #define DMA_K(t, slot) do { _Pragma("unroll") for (int i_ = 0; i_ < 2; ++i_) __builtin_amdgcn_global_load_lds((const unsigned*)((const char*)Kh + (size_t)(t) * (KVBLK * D * 2) + dof.k[i_]), \
;         (LAS unsigned*)((LAS unsigned char*)lds3 + OFF_K + (slot) + (wid * 2 + i_) * 1024), 16, 0, 0); } while (0)
; #define DMA_V(t, slot) do { _Pragma("unroll") for (int i_ = 0; i_ < 2; ++i_) __builtin_amdgcn_global_load_lds((const unsigned*)((const char*)Vh + (size_t)(t) * (KVBLK * D * 2) + dof.v[i_]), \
;         (LAS unsigned*)((LAS unsigned char*)lds3 + (slot) + (wid * 2 + i_) * 1024), 16, 0, 0); } while (0)
; #define ROT() do { s_prev = s_cur; s_cur = s_next; s_next = s_nn; s_nn = (s_nn == (NSLOT - 1) * SLOT) ? 0 : s_nn + SLOT; } while (0)
; __device__ __forceinline__ void fox_block(const BlockRef& cur, const BlockRef& nxt, char* lds, Seam& S, const int tid) {
;     const int wid = __builtin_amdgcn_readfirstlane(tid >> 6), lane = tid & 63, r32 = lane & 31, hi = lane >> 5;
;     const int NT = cur.P0 / KVBLK + 4;
;     const int qlo = cur.P0 + wid * QBLK, qm = qlo + r32 - 4 * hi;
;     char* V_lds = lds; char* K_lds = lds + OFF_K; LAS unsigned char* lds3 = (LAS unsigned char*)lds;
;     float* ws = (float*)(lds + OFF_WS) + wid * 64; float* li_l = ws, * al_l = ws + 32;
;     const LAS float* ctab = (const LAS float*)(LAS char*)(lds + OFF_C);
;     float m_reg = -1e30f, l_reg = 0; f32x16 o[4] = {};
;     const DmaOff dof = dma_offsets(wid, lane);
;     const int vb0 = (int)(uintptr_t)V_lds + v_rd_base(lane);
;     const bf16_t* Kh = cur.K; const bf16_t* Vh = cur.V;
;     ...
;     f32x16 pA0, pA1, pB0, pB1; float mnA, mnB, alA, alB; bf16x8 pa0, pa1, pa2, pa3;
;     int s_prev = 0, s_cur = 0, s_next = SLOT, s_nn = 2 * SLOT;
;     SBAR(); DMA_K(2, s_nn); DMA_V(1, s_next); SBAR();
;     qkt(pA0, pA1, K_lds + s_cur, r32, hi, S.qr, CTP(0));
;     mask_meta(pA0, pA1); partialSM(pA0, pA1, m_reg, mnA, alA);
;     SBAR(); WAITV_BAR(4);
;     ROT();
	s_nop 1
	v_lshlrev_b32_e32 v0, 8, v15
	v_lshl_or_b32 v138, v16, 4, v0
	v_and_or_b32 v0, v14, s6, v202
	v_lshl_or_b32 v136, v0, 1, v17
	s_lshl_b32 s6, s70, 11
	s_add_i32 s86, s6, 0
	s_add_i32 m0, s86, 0x14000
	v_readlane_b32 s6, v247, 24
	global_load_lds_dwordx4 v128, s[66:67]
	s_add_i32 m0, s86, 0x14400
	v_readlane_b32 s7, v247, 25
	global_load_lds_dwordx4 v138, s[66:67]
	s_add_i32 m0, s86, 0x4000
	v_mov_b32_e32 v139, v129
	s_add_i32 s88, s71, s4
	s_nop 0
	global_load_lds_dwordx4 v134, s[6:7]
	s_add_i32 m0, s86, 0x4400
	s_movk_i32 s73, 0x4000
	global_load_lds_dwordx4 v136, s[6:7]
	v_mov_b32_e32 v135, v129
	v_mov_b32_e32 v137, v129
	s_add_i32 s89, s89, 4
	ds_read_b128 v[16:19], v209 offset:57344
	ds_read_b128 v[0:3], v205 offset:128
	ds_read_b128 v[4:7], v205 offset:160
	ds_read_b128 v[8:11], v205 offset:192
	ds_read_b128 v[12:15], v205 offset:224
	v_xor_b32_e32 v249, 0x80, v209
	v_xor_b32_e32 v250, 0x80, v208
	v_xor_b32_e32 v251, 0x80, v207
	v_xor_b32_e32 v252, 0x80, v206
	ds_read_b128 v[20:23], v249 offset:57344
	s_mov_b32 s4, 0xff800000
	s_waitcnt lgkmcnt(0)
	v_mfma_f32_32x32x16_bf16 v[0:15], v[16:19], v[96:99], v[0:15]
	ds_read_b128 v[16:19], v208 offset:57344
	ds_read_b128 v[24:27], v250 offset:57344
	s_waitcnt lgkmcnt(0)
	v_mfma_f32_32x32x16_bf16 v[0:15], v[16:19], v[100:103], v[0:15]
	ds_read_b128 v[16:19], v207 offset:57344
	ds_read_b128 v[28:31], v251 offset:57344
	s_waitcnt lgkmcnt(0)
	v_mfma_f32_32x32x16_bf16 v[0:15], v[16:19], v[104:107], v[0:15]
	ds_read_b128 v[16:19], v206 offset:57344
	ds_read_b128 v[32:35], v252 offset:57344
	s_waitcnt lgkmcnt(0)
	v_mfma_f32_32x32x16_bf16 v[0:15], v[16:19], v[108:111], v[0:15]
	v_mfma_f32_32x32x16_bf16 v[0:15], v[20:23], v[112:115], v[0:15]
	v_mfma_f32_32x32x16_bf16 v[0:15], v[24:27], v[116:119], v[0:15]
	v_mfma_f32_32x32x16_bf16 v[0:15], v[28:31], v[120:123], v[0:15]
	v_mfma_f32_32x32x16_bf16 v[0:15], v[32:35], v[124:127], v[0:15]
	s_nop 11
	v_max3_f32 v0, v8, s4, v9
	v_max3_f32 v0, v0, v10, v11
	v_max3_f32 v0, v0, v12, v13
	v_max3_f32 v0, v0, v14, v15
	v_mov_b32_e32 v1, v0
	s_nop 1
	v_permlane32_swap_b32_e32 v0, v1
	v_max_f32_e32 v1, v1, v1
	v_max_f32_e32 v0, v0, v0
	v_max_f32_e32 v0, v0, v1
	v_add_f32_e32 v1, 0x7149f2ca, v0
	v_cmp_ge_f32_e32 vcc, s33, v1
	s_cmp_eq_u64 vcc, exec
	v_max_f32_e32 v2, 0xf149f2ca, v0
	s_cselect_b64 vcc, -1, 0
	v_cndmask_b32_e32 v144, v2, v189, vcc
	v_mov_b32_e32 v0, v9
	v_mov_b32_e32 v1, v10
	v_pk_add_f32 v[66:67], v[0:1], v[144:145] op_sel_hi:[1,0] neg_lo:[0,1] neg_hi:[0,1]
	v_mov_b32_e32 v0, v11
	v_mov_b32_e32 v1, v12
	v_pk_add_f32 v[68:69], v[0:1], v[144:145] op_sel_hi:[1,0] neg_lo:[0,1] neg_hi:[0,1]
	v_sub_f32_e32 v1, 0xf149f2ca, v2
	v_mov_b32_e32 v131, v8
	v_mov_b32_e32 v0, v13
	v_exp_f32_e32 v2, v1
	v_mov_b32_e32 v1, v14
	s_add_i32 s2, s2, s71
	v_pk_add_f32 v[64:65], v[130:131], v[144:145] op_sel_hi:[1,0] neg_lo:[0,1] neg_hi:[0,1]
	v_pk_add_f32 v[70:71], v[0:1], v[144:145] op_sel_hi:[1,0] neg_lo:[0,1] neg_hi:[0,1]
	v_or_b32_e32 v0, s2, v199
	v_exp_f32_e32 v178, v64
	v_sub_u32_e32 v173, v0, v201
	v_add_u32_e32 v0, v36, v200
	v_add_lshl_u32 v0, v0, s5, 8
	s_waitcnt vmcnt(4) lgkmcnt(0)
	s_barrier
	v_or_b32_e32 v1, v0, v211
	v_mov_b32_e32 v48, v129
	v_mov_b32_e32 v49, v129
	v_sub_f32_e32 v155, v15, v144
	v_cndmask_b32_e64 v174, v2, 1.0, vcc
	v_add_u32_e32 v140, v1, v210
	v_or3_b32 v142, v0, v212, v210
	v_mov_b32_e32 v50, v129
	v_mov_b32_e32 v51, v129
	v_mov_b32_e32 v52, v129
	v_mov_b32_e32 v53, v129
	v_mov_b32_e32 v54, v129
	v_mov_b32_e32 v55, v129
	v_mov_b32_e32 v56, v129
	v_mov_b32_e32 v57, v129
	v_mov_b32_e32 v58, v129
	v_mov_b32_e32 v59, v129
	v_mov_b32_e32 v60, v129
	v_mov_b32_e32 v61, v129
	v_mov_b32_e32 v62, v129
	v_mov_b32_e32 v63, v129
	v_mov_b64_e32 v[32:33], v[48:49]
	v_mov_b64_e32 v[16:17], v[48:49]
	v_mov_b64_e32 v[0:1], v[48:49]
	v_add_u32_e32 v171, s3, v133
	v_lshl_add_u32 v131, v201, 2, s3
	v_mov_b32_e32 v141, v129
	v_mov_b32_e32 v143, v129
	s_mov_b32 s2, 0
	v_mov_b32_e32 v172, 0
	s_mov_b32 s90, 0x8000
	s_movk_i32 s91, 0xbf
	v_mov_b64_e32 v[34:35], v[50:51]
	v_mov_b64_e32 v[36:37], v[52:53]
	v_mov_b64_e32 v[38:39], v[54:55]
	v_mov_b64_e32 v[40:41], v[56:57]
	v_mov_b64_e32 v[42:43], v[58:59]
	v_mov_b64_e32 v[44:45], v[60:61]
	v_mov_b64_e32 v[46:47], v[62:63]
	v_mov_b64_e32 v[18:19], v[50:51]
	v_mov_b64_e32 v[20:21], v[52:53]
	v_mov_b64_e32 v[22:23], v[54:55]
	v_mov_b64_e32 v[24:25], v[56:57]
	v_mov_b64_e32 v[26:27], v[58:59]
	v_mov_b64_e32 v[28:29], v[60:61]
	v_mov_b64_e32 v[30:31], v[62:63]
	v_mov_b64_e32 v[2:3], v[50:51]
	v_mov_b64_e32 v[4:5], v[52:53]
	v_mov_b64_e32 v[6:7], v[54:55]
	v_mov_b64_e32 v[8:9], v[56:57]
	v_mov_b64_e32 v[10:11], v[58:59]
	v_mov_b64_e32 v[12:13], v[60:61]
	v_mov_b64_e32 v[14:15], v[62:63]
	s_mov_b32 s72, 0
	v_mov_b32_e32 v211, v178
	v_mov_b32_e32 v208, v178
	v_mov_b32_e32 v210, v178
	v_mov_b32_e32 v206, v178
	v_mov_b32_e32 v209, v178
	v_mov_b32_e32 v205, v178
	v_mov_b32_e32 v207, v178
	v_mov_b32_e32 v202, v178
	v_mov_b32_e32 v204, v178
	v_mov_b32_e32 v200, v178
	v_mov_b32_e32 v203, v178
	v_mov_b32_e32 v198, v178
	v_mov_b32_e32 v201, v178
	v_mov_b32_e32 v179, v178
	v_mov_b32_e32 v199, v178
	v_mov_b32_e32 v158, v64
	v_mov_b32_e32 v159, v64
	v_mov_b32_e32 v162, v64
	v_mov_b32_e32 v163, v64
	v_mov_b32_e32 v166, v64
	v_mov_b32_e32 v167, v64
	v_mov_b32_e32 v156, v64
	v_mov_b32_e32 v157, v64
	v_mov_b32_e32 v160, v65
	v_mov_b32_e32 v161, v66
	v_mov_b32_e32 v164, v67
	v_mov_b32_e32 v165, v68
	v_mov_b32_e32 v168, v69
	v_mov_b32_e32 v169, v70
	v_mov_b32_e32 v154, v71
	v_readlane_b32 s96, v247, 9
	v_readlane_b32 s97, v247, 8

; #define LAS __attribute__((address_space(3)))
; __device__ __forceinline__ void finishSM(f32x16& p0, f32x16& p1, float alpha, float& l_reg, bf16x8& pa0, bf16x8& pa1, bf16x8& pa2, bf16x8& pa3) {
; #pragma unroll
;     for (int r = 0; r < 16; ++r) p1[r] = __builtin_amdgcn_exp2f(p1[r]);
;     float ps = 0;
; #pragma unroll
;     for (int r = 0; r < 16; ++r) ps += p0[r];
; #pragma unroll
;     for (int r = 0; r < 16; ++r) ps += p1[r];
;     { auto rr = __builtin_amdgcn_permlane32_swap(__float_as_uint(ps), __float_as_uint(ps), false, false);
;       ps = __uint_as_float(rr[0]) + __uint_as_float(rr[1]); }
;     l_reg = l_reg * alpha + ps;
;     ...
;     PK4(p0, 0, pa0); PK4(p0, 8, pa1); PK4(p1, 0, pa2); PK4(p1, 8, pa3);
;     ...
; }
; __device__ __forceinline__ void qkt(f32x16& p0, f32x16& p1, const char* Kslot, int r32, int hi, const bf16x8* qr, const LAS f32x4* cp) {
; #pragma unroll
;     for (int g = 0; g < 4; ++g) { const f32x4 c0 = cp[2 * g], c1 = cp[8 + 2 * g];
; #pragma unroll
;         for (int j = 0; j < 4; ++j) { p0[4 * g + j] = c0[j]; p1[4 * g + j] = c1[j]; } }
;     const char* kb[4];
; #pragma unroll
;     for (int dd = 0; dd < 4; ++dd) kb[dd] = Kslot + KSWZ(r32, (dd * 16 + hi * 8) * 2);
; #pragma unroll
;     for (int d0 = 0; d0 < 8; ++d0) { const char* a = kb[d0 & 3] + (d0 >> 2) * 128;
;         bf16x8 b0 = *reinterpret_cast<const bf16x8*>(a);
;         bf16x8 b1 = *reinterpret_cast<const bf16x8*>(a + 32 * 256);
;         p0 = __builtin_amdgcn_mfma_f32_32x32x16_bf16(b0, qr[d0], p0, 0, 0, 0);
;         p1 = __builtin_amdgcn_mfma_f32_32x32x16_bf16(b1, qr[d0], p1, 0, 0, 0); }
.LBB0_558:
	s_add_i32 s3, s86, s90
	v_lshl_add_u64 v[150:151], s[82:83], 0, v[140:141]
	v_lshl_add_u64 v[64:65], v[150:151], 0, s[84:85]
	s_mov_b32 m0, s3
	v_lshl_add_u64 v[152:153], s[82:83], 0, v[142:143]
	global_load_lds_dwordx4 v[64:65], off
	v_lshl_add_u64 v[64:65], v[152:153], 0, s[84:85]
	s_add_i32 m0, s3, 0x400
	s_nop 0
	global_load_lds_dwordx4 v[64:65], off
	s_add_i32 s3, s73, 0
	v_add_u32_e32 v175, s3, v193
	ds_read_b128 v[80:83], v197
	ds_read_b128 v[84:87], v197 offset:32
	ds_read_b128 v[64:67], v197 offset:128
	ds_read_b128 v[68:71], v197 offset:160
	ds_read_b128 v[88:91], v197 offset:64
	ds_read_b128 v[72:75], v197 offset:192
	ds_read_b128 v[92:95], v197 offset:96
	ds_read_b128 v[76:79], v197 offset:224
	ds_read_b128 v[212:215], v175 offset:49152
	ds_read_b128 v[216:219], v175 offset:57344
	v_add_u32_e32 v176, s3, v194
	v_add_u32_e32 v177, s3, v195
	s_waitcnt lgkmcnt(0)
	v_mfma_f32_32x32x16_bf16 v[80:95], v[212:215], v[96:99], v[80:95]
	v_add_u32_e32 v220, s3, v196
	v_exp_f32_e32 v163, v163
	v_exp_f32_e32 v166, v166
	v_exp_f32_e32 v167, v167
	v_exp_f32_e32 v168, v168
	v_exp_f32_e32 v169, v169
	v_exp_f32_e32 v221, v155
	v_mfma_f32_32x32x16_bf16 v[64:79], v[216:219], v[96:99], v[64:79]
	ds_read_b128 v[212:215], v176 offset:49152
	ds_read_b128 v[216:219], v176 offset:57344
	s_waitcnt lgkmcnt(0)
	v_mfma_f32_32x32x16_bf16 v[80:95], v[212:215], v[100:103], v[80:95]
	v_mfma_f32_32x32x16_bf16 v[64:79], v[216:219], v[100:103], v[64:79]
	ds_read_b128 v[212:215], v177 offset:49152
	ds_read_b128 v[216:219], v177 offset:57344
	s_waitcnt lgkmcnt(0)
	v_mfma_f32_32x32x16_bf16 v[80:95], v[212:215], v[104:107], v[80:95]
	v_mfma_f32_32x32x16_bf16 v[64:79], v[216:219], v[104:107], v[64:79]
	ds_read_b128 v[212:215], v220 offset:49152
	ds_read_b128 v[216:219], v220 offset:57344
	s_waitcnt lgkmcnt(0)
	v_mfma_f32_32x32x16_bf16 v[80:95], v[212:215], v[108:111], v[80:95]
	v_mfma_f32_32x32x16_bf16 v[64:79], v[216:219], v[108:111], v[64:79]
	v_xor_b32_e32 v249, 0x80, v175
	v_xor_b32_e32 v250, 0x80, v176
	v_xor_b32_e32 v251, 0x80, v177
	v_xor_b32_e32 v252, 0x80, v220
	ds_read_b128 v[212:215], v249 offset:49152
	ds_read_b128 v[216:219], v249 offset:57344
	s_waitcnt lgkmcnt(0)
	v_mfma_f32_32x32x16_bf16 v[80:95], v[212:215], v[112:115], v[80:95]
	v_mfma_f32_32x32x16_bf16 v[64:79], v[216:219], v[112:115], v[64:79]
	ds_read_b128 v[212:215], v250 offset:49152
	ds_read_b128 v[216:219], v250 offset:57344
	s_waitcnt lgkmcnt(0)
	v_mfma_f32_32x32x16_bf16 v[80:95], v[212:215], v[116:119], v[80:95]
	v_mfma_f32_32x32x16_bf16 v[64:79], v[216:219], v[116:119], v[64:79]
	ds_read_b128 v[212:215], v251 offset:49152
	ds_read_b128 v[216:219], v251 offset:57344
	v_exp_f32_e32 v177, v158
	s_waitcnt lgkmcnt(0)
	v_mfma_f32_32x32x16_bf16 v[80:95], v[212:215], v[120:123], v[80:95]
	v_mfma_f32_32x32x16_bf16 v[64:79], v[216:219], v[120:123], v[64:79]
	ds_read_b128 v[212:215], v252 offset:49152
	ds_read_b128 v[216:219], v252 offset:57344
	v_exp_f32_e32 v220, v154
	v_add_f32_e32 v154, 0, v178
	v_add_f32_e32 v154, v211, v154
	v_add_f32_e32 v154, v208, v154
	v_add_f32_e32 v154, v210, v154
	v_add_f32_e32 v154, v206, v154
	v_add_f32_e32 v154, v209, v154
	v_add_f32_e32 v154, v205, v154
	v_add_f32_e32 v154, v207, v154
	v_add_f32_e32 v154, v202, v154
	v_add_f32_e32 v154, v204, v154
	v_add_f32_e32 v154, v200, v154
	v_add_f32_e32 v154, v203, v154
	v_add_f32_e32 v154, v198, v154
	s_waitcnt lgkmcnt(0)
	v_mfma_f32_32x32x16_bf16 v[80:95], v[212:215], v[124:127], v[80:95]
	v_exp_f32_e32 v212, v159
	v_add_f32_e32 v154, v201, v154
	v_exp_f32_e32 v213, v162
	v_add_f32_e32 v154, v179, v154
	v_add_f32_e32 v154, v199, v154
	v_add_f32_e32 v154, v177, v154
	v_add_f32_e32 v154, v212, v154
	v_exp_f32_e32 v214, v156
	v_add_f32_e32 v154, v213, v154
	v_exp_f32_e32 v215, v157
	v_add_f32_e32 v154, v163, v154
	v_mfma_f32_32x32x16_bf16 v[64:79], v[216:219], v[124:127], v[64:79]
	v_exp_f32_e32 v216, v160
	v_add_f32_e32 v154, v166, v154
	v_exp_f32_e32 v217, v161
	v_add_f32_e32 v154, v167, v154
	v_exp_f32_e32 v218, v164
	v_add_f32_e32 v154, v214, v154
	v_exp_f32_e32 v219, v165
	v_add_f32_e32 v154, v215, v154
	v_add_f32_e32 v154, v216, v154
	v_add_f32_e32 v154, v217, v154
	v_add_f32_e32 v154, v218, v154
	v_add_f32_e32 v154, v219, v154
	v_add_f32_e32 v154, v168, v154
	v_add_f32_e32 v154, v169, v154
	v_add_f32_e32 v154, v220, v154
	v_add_f32_e32 v175, v221, v154
	v_mov_b32_e32 v176, v175
	s_nop 1
	v_permlane32_swap_b32_e32 v175, v176
	v_cvt_pk_bf16_f32 v154, v178, v211
	v_cvt_pk_bf16_f32 v155, v208, v210
	v_cvt_pk_bf16_f32 v156, v206, v209
	v_cvt_pk_bf16_f32 v157, v205, v207
	v_cvt_pk_bf16_f32 v158, v202, v204
	v_cvt_pk_bf16_f32 v159, v200, v203
	v_cvt_pk_bf16_f32 v160, v198, v201
	v_cvt_pk_bf16_f32 v161, v179, v199
	v_cvt_pk_bf16_f32 v162, v177, v212
	v_cvt_pk_bf16_f32 v163, v213, v163
	v_cvt_pk_bf16_f32 v164, v166, v167
	v_cvt_pk_bf16_f32 v165, v214, v215
	v_cvt_pk_bf16_f32 v166, v216, v217
	v_cvt_pk_bf16_f32 v167, v218, v219
	v_cvt_pk_bf16_f32 v168, v168, v169
	v_cvt_pk_bf16_f32 v169, v220, v221
	s_nop 0
	v_permlane32_swap_b32_e32 v154, v156
	v_permlane32_swap_b32_e32 v155, v157
	v_permlane32_swap_b32_e32 v158, v160
	v_permlane32_swap_b32_e32 v159, v161
	v_permlane32_swap_b32_e32 v162, v164
	v_permlane32_swap_b32_e32 v163, v165
	v_permlane32_swap_b32_e32 v166, v168
	v_permlane32_swap_b32_e32 v167, v169
	v_add_u32_e32 v177, s2, v192
	s_sub_i32 s2, s91, 64
	s_cmp_le_i32 s2, s88
	s_cbranch_scc0 .Lband_2
; #define SBAR() __builtin_amdgcn_sched_barrier(0)
; #define PV_RD(d0, kh, X) do { constexpr int b_ = v_rd_off(d0, 2 * (kh), 0); TRRD(X##l0, b_); TRRD(X##h0, b_ + 2048); TRRD(X##l1, b_ + 4096); TRRD(X##h1, b_ + 6144); } while (0)
; #define PV_MM(d0, X, PA, PB) do { \
;         o[d0] = __builtin_amdgcn_mfma_f32_32x32x16_bf16(PA, (bf16x8){X##l0[0], X##l0[1], X##l0[2], X##l0[3], X##h0[0], X##h0[1], X##h0[2], X##h0[3]}, o[d0], 0, 0, 0);   \
;         o[d0] = __builtin_amdgcn_mfma_f32_32x32x16_bf16(PB, (bf16x8){X##l1[0], X##l1[1], X##l1[2], X##l1[3], X##h1[0], X##h1[1], X##h1[2], X##h1[3]}, o[d0], 0, 0, 0); } while (0)
; #define PV_W4() do { asm volatile("s_waitcnt lgkmcnt(4)" ::: "memory"); SBAR(); } while (0)
; #define PV_W0() do { asm volatile("s_waitcnt lgkmcnt(0)" ::: "memory"); SBAR(); } while (0)
; __device__ __forceinline__ void partialSM(f32x16& p0, f32x16& p1, float& m_reg, float& mn, float& alpha) {
;     float pmax = p0[0];
; #pragma unroll
;     for (int r = 1; r < 16; ++r) pmax = fmaxf(pmax, p0[r]);
; #pragma unroll
;     for (int r = 0; r < 16; ++r) pmax = fmaxf(pmax, p1[r]);
;     { auto rr = __builtin_amdgcn_permlane32_swap(__float_as_uint(pmax), __float_as_uint(pmax), false, false);
;       pmax = fmaxf(__uint_as_float(rr[0]), __uint_as_float(rr[1])); }
;     if (__builtin_expect(__all((pmax - m_reg) <= THR2), 1)) { mn = m_reg; alpha = 1.f; }
;     else { mn = fmaxf(m_reg, pmax); alpha = __builtin_amdgcn_exp2f(m_reg - mn); m_reg = mn; }
; __device__ __forceinline__ void pv_tile(f32x16* o, int vb0, bf16x8 pa0, bf16x8 pa1, bf16x8 pa2, bf16x8 pa3) {
;     ...
;     s16x4 al0, al1, ah0, ah1, bl0, bl1, bh0, bh1;
;     PV_RD(0, 0, a);
;     PV_RD(0, 1, b); PV_W4(); PV_MM(0, a, pa0, pa1); SBAR();
;     PV_RD(1, 0, a); PV_W4(); PV_MM(0, b, pa2, pa3); SBAR();
;     PV_RD(1, 1, b); PV_W4(); PV_MM(1, a, pa0, pa1); SBAR();
;     PV_RD(2, 0, a); PV_W4(); PV_MM(1, b, pa2, pa3); SBAR();
;     PV_RD(2, 1, b); PV_W4(); PV_MM(2, a, pa0, pa1); SBAR();
;     PV_RD(3, 0, a); PV_W4(); PV_MM(2, b, pa2, pa3); SBAR();
;     PV_RD(3, 1, b); PV_W4(); PV_MM(3, a, pa0, pa1); SBAR();
;     PV_W0(); PV_MM(3, b, pa2, pa3);
	ds_read_b64_tr_b16 v[198:199], v177 offset:0
	ds_read_b64_tr_b16 v[200:201], v177 offset:0x800
	ds_read_b64_tr_b16 v[202:203], v177 offset:0x1000
	ds_read_b64_tr_b16 v[204:205], v177 offset:0x1800
	ds_read_b64_tr_b16 v[206:207], v177 offset:0x2000
	ds_read_b64_tr_b16 v[208:209], v177 offset:0x2800
	ds_read_b64_tr_b16 v[210:211], v177 offset:0x3000
	ds_read_b64_tr_b16 v[212:213], v177 offset:0x3800
	s_waitcnt lgkmcnt(4)
	s_nop 0
	v_mfma_f32_32x32x16_bf16 v[48:63], v[154:157], v[198:201], v[48:63]
	v_max_f32_e32 v253, v81, v81
	v_max_f32_e32 v254, v80, v80
	v_mfma_f32_32x32x16_bf16 v[48:63], v[158:161], v[202:205], v[48:63]
	v_max_f32_e32 v253, v254, v253
	v_max3_f32 v253, v253, v82, v83
	ds_read_b64_tr_b16 v[198:199], v177 offset:0x200
	ds_read_b64_tr_b16 v[200:201], v177 offset:0xa00
	ds_read_b64_tr_b16 v[202:203], v177 offset:0x1200
	ds_read_b64_tr_b16 v[204:205], v177 offset:0x1a00
	s_waitcnt lgkmcnt(4)
	v_mfma_f32_32x32x16_bf16 v[48:63], v[162:165], v[206:209], v[48:63]
	v_max3_f32 v253, v253, v84, v85
	v_max3_f32 v253, v253, v86, v87
	v_mfma_f32_32x32x16_bf16 v[48:63], v[166:169], v[210:213], v[48:63]
	v_max3_f32 v253, v253, v88, v89
	v_max3_f32 v253, v253, v90, v91
	ds_read_b64_tr_b16 v[206:207], v177 offset:0x2200
	ds_read_b64_tr_b16 v[208:209], v177 offset:0x2a00
	ds_read_b64_tr_b16 v[210:211], v177 offset:0x3200
	ds_read_b64_tr_b16 v[212:213], v177 offset:0x3a00
	s_waitcnt lgkmcnt(4)
	v_mfma_f32_32x32x16_bf16 v[32:47], v[154:157], v[198:201], v[32:47]
	v_max3_f32 v253, v253, v92, v93
	v_max3_f32 v253, v253, v94, v95
	v_mfma_f32_32x32x16_bf16 v[32:47], v[158:161], v[202:205], v[32:47]
	v_max3_f32 v253, v253, v64, v65
	v_max3_f32 v253, v253, v66, v67
	ds_read_b64_tr_b16 v[198:199], v177 offset:0x400
	ds_read_b64_tr_b16 v[200:201], v177 offset:0xc00
	ds_read_b64_tr_b16 v[202:203], v177 offset:0x1400
	ds_read_b64_tr_b16 v[204:205], v177 offset:0x1c00
	s_waitcnt lgkmcnt(4)
	v_mfma_f32_32x32x16_bf16 v[32:47], v[162:165], v[206:209], v[32:47]
	v_max3_f32 v253, v253, v68, v69
	v_max3_f32 v253, v253, v70, v71
	v_mfma_f32_32x32x16_bf16 v[32:47], v[166:169], v[210:213], v[32:47]
	v_max3_f32 v253, v253, v72, v73
	v_max3_f32 v253, v253, v74, v75
	ds_read_b64_tr_b16 v[206:207], v177 offset:0x2400
	ds_read_b64_tr_b16 v[208:209], v177 offset:0x2c00
	ds_read_b64_tr_b16 v[210:211], v177 offset:0x3400
	ds_read_b64_tr_b16 v[212:213], v177 offset:0x3c00
	s_waitcnt lgkmcnt(4)
	v_mfma_f32_32x32x16_bf16 v[16:31], v[154:157], v[198:201], v[16:31]
	v_max3_f32 v253, v253, v76, v77
	v_max3_f32 v253, v253, v78, v79
	v_mfma_f32_32x32x16_bf16 v[16:31], v[158:161], v[202:205], v[16:31]
	v_mov_b32_e32 v254, v253
	s_nop 1
	ds_read_b64_tr_b16 v[198:199], v177 offset:0x600
	ds_read_b64_tr_b16 v[200:201], v177 offset:0xe00
	ds_read_b64_tr_b16 v[202:203], v177 offset:0x1600
	ds_read_b64_tr_b16 v[204:205], v177 offset:0x1e00
	s_waitcnt lgkmcnt(4)
	v_mfma_f32_32x32x16_bf16 v[16:31], v[162:165], v[206:209], v[16:31]
	v_permlane32_swap_b32_e32 v253, v254
	v_max_f32_e32 v254, v254, v254
	v_mfma_f32_32x32x16_bf16 v[16:31], v[166:169], v[210:213], v[16:31]
	v_max_f32_e32 v253, v253, v253
	v_max_f32_e32 v253, v253, v254
	ds_read_b64_tr_b16 v[206:207], v177 offset:0x2600
	ds_read_b64_tr_b16 v[208:209], v177 offset:0x2e00
	ds_read_b64_tr_b16 v[210:211], v177 offset:0x3600
	ds_read_b64_tr_b16 v[212:213], v177 offset:0x3e00
	s_waitcnt lgkmcnt(4)
	v_mfma_f32_32x32x16_bf16 v[0:15], v[154:157], v[198:201], v[0:15]
	v_sub_f32_e32 v254, v253, v144
	v_cmp_ge_f32_e32 vcc, s33, v254
	v_mfma_f32_32x32x16_bf16 v[0:15], v[158:161], v[202:205], v[0:15]
	v_max_f32_e32 v254, v144, v144
	v_max_f32_e32 v253, v254, v253
	s_waitcnt lgkmcnt(0)
	v_mfma_f32_32x32x16_bf16 v[0:15], v[162:165], v[206:209], v[0:15]
	v_sub_f32_e32 v254, v144, v253
	v_exp_f32_e32 v254, v254
	v_mfma_f32_32x32x16_bf16 v[0:15], v[166:169], v[210:213], v[0:15]
	v_mov_b32_e32 v154, v253
	v_mov_b32_e32 v155, v254
	s_branch .Lmaxtail_2
; #define SBAR() __builtin_amdgcn_sched_barrier(0)
; #define PV_RD(d0, kh, X) do { constexpr int b_ = v_rd_off(d0, 2 * (kh), 0); TRRD(X##l0, b_); TRRD(X##h0, b_ + 2048); TRRD(X##l1, b_ + 4096); TRRD(X##h1, b_ + 6144); } while (0)
; #define PV_MM(d0, X, PA, PB) do { \
;         o[d0] = __builtin_amdgcn_mfma_f32_32x32x16_bf16(PA, (bf16x8){X##l0[0], X##l0[1], X##l0[2], X##l0[3], X##h0[0], X##h0[1], X##h0[2], X##h0[3]}, o[d0], 0, 0, 0);   \
;         o[d0] = __builtin_amdgcn_mfma_f32_32x32x16_bf16(PB, (bf16x8){X##l1[0], X##l1[1], X##l1[2], X##l1[3], X##h1[0], X##h1[1], X##h1[2], X##h1[3]}, o[d0], 0, 0, 0); } while (0)
; #define PV_W4() do { asm volatile("s_waitcnt lgkmcnt(4)" ::: "memory"); SBAR(); } while (0)
; #define PV_W0() do { asm volatile("s_waitcnt lgkmcnt(0)" ::: "memory"); SBAR(); } while (0)
; __device__ __forceinline__ void mask_tile(f32x16& p0, f32x16& p1, int dq) {
;     const float NEG = -__builtin_inff();
; #pragma unroll
;     for (int r = 0; r < 16; ++r) { const int c = (r & 3) + 8 * (r >> 2); if (dq - c < 0) p0[r] = NEG; if (dq - c - 32 < 0) p1[r] = NEG; }
; }
; __device__ __forceinline__ void pv_tile(f32x16* o, int vb0, bf16x8 pa0, bf16x8 pa1, bf16x8 pa2, bf16x8 pa3) {
;     ...
;     s16x4 al0, al1, ah0, ah1, bl0, bl1, bh0, bh1;
;     PV_RD(0, 0, a);
;     PV_RD(0, 1, b); PV_W4(); PV_MM(0, a, pa0, pa1); SBAR();
;     PV_RD(1, 0, a); PV_W4(); PV_MM(0, b, pa2, pa3); SBAR();
;     PV_RD(1, 1, b); PV_W4(); PV_MM(1, a, pa0, pa1); SBAR();
;     PV_RD(2, 0, a); PV_W4(); PV_MM(1, b, pa2, pa3); SBAR();
;     PV_RD(2, 1, b); PV_W4(); PV_MM(2, a, pa0, pa1); SBAR();
;     PV_RD(3, 0, a); PV_W4(); PV_MM(2, b, pa2, pa3); SBAR();
;     PV_RD(3, 1, b); PV_W4(); PV_MM(3, a, pa0, pa1); SBAR();
;     PV_W0(); PV_MM(3, b, pa2, pa3);
.Lband_2:
	ds_read_b64_tr_b16 v[198:199], v177 offset:0
	ds_read_b64_tr_b16 v[200:201], v177 offset:0x800
	ds_read_b64_tr_b16 v[202:203], v177 offset:0x1000
	ds_read_b64_tr_b16 v[204:205], v177 offset:0x1800
	ds_read_b64_tr_b16 v[206:207], v177 offset:0x2000
	ds_read_b64_tr_b16 v[208:209], v177 offset:0x2800
	ds_read_b64_tr_b16 v[210:211], v177 offset:0x3000
	ds_read_b64_tr_b16 v[212:213], v177 offset:0x3800
	s_waitcnt lgkmcnt(4)
	s_nop 0
	v_mfma_f32_32x32x16_bf16 v[48:63], v[154:157], v[198:201], v[48:63]
	v_mfma_f32_32x32x16_bf16 v[48:63], v[158:161], v[202:205], v[48:63]
	ds_read_b64_tr_b16 v[198:199], v177 offset:0x200
	ds_read_b64_tr_b16 v[200:201], v177 offset:0xa00
	ds_read_b64_tr_b16 v[202:203], v177 offset:0x1200
	ds_read_b64_tr_b16 v[204:205], v177 offset:0x1a00
	s_waitcnt lgkmcnt(4)
	v_mfma_f32_32x32x16_bf16 v[48:63], v[162:165], v[206:209], v[48:63]
	v_mfma_f32_32x32x16_bf16 v[48:63], v[166:169], v[210:213], v[48:63]
	ds_read_b64_tr_b16 v[206:207], v177 offset:0x2200
	ds_read_b64_tr_b16 v[208:209], v177 offset:0x2a00
	ds_read_b64_tr_b16 v[210:211], v177 offset:0x3200
	ds_read_b64_tr_b16 v[212:213], v177 offset:0x3a00
	s_waitcnt lgkmcnt(4)
	v_mfma_f32_32x32x16_bf16 v[32:47], v[154:157], v[198:201], v[32:47]
	v_mfma_f32_32x32x16_bf16 v[32:47], v[158:161], v[202:205], v[32:47]
	ds_read_b64_tr_b16 v[198:199], v177 offset:0x400
	ds_read_b64_tr_b16 v[200:201], v177 offset:0xc00
	ds_read_b64_tr_b16 v[202:203], v177 offset:0x1400
	ds_read_b64_tr_b16 v[204:205], v177 offset:0x1c00
	s_waitcnt lgkmcnt(4)
	v_mfma_f32_32x32x16_bf16 v[32:47], v[162:165], v[206:209], v[32:47]
	v_mfma_f32_32x32x16_bf16 v[32:47], v[166:169], v[210:213], v[32:47]
	ds_read_b64_tr_b16 v[206:207], v177 offset:0x2400
	ds_read_b64_tr_b16 v[208:209], v177 offset:0x2c00
	ds_read_b64_tr_b16 v[210:211], v177 offset:0x3400
	ds_read_b64_tr_b16 v[212:213], v177 offset:0x3c00
	s_waitcnt lgkmcnt(4)
	v_mfma_f32_32x32x16_bf16 v[16:31], v[154:157], v[198:201], v[16:31]
	v_mfma_f32_32x32x16_bf16 v[16:31], v[158:161], v[202:205], v[16:31]
	ds_read_b64_tr_b16 v[198:199], v177 offset:0x600
	ds_read_b64_tr_b16 v[200:201], v177 offset:0xe00
	ds_read_b64_tr_b16 v[202:203], v177 offset:0x1600
	ds_read_b64_tr_b16 v[204:205], v177 offset:0x1e00
	s_waitcnt lgkmcnt(4)
	v_mfma_f32_32x32x16_bf16 v[16:31], v[162:165], v[206:209], v[16:31]
	v_mfma_f32_32x32x16_bf16 v[16:31], v[166:169], v[210:213], v[16:31]
	ds_read_b64_tr_b16 v[206:207], v177 offset:0x2600
	ds_read_b64_tr_b16 v[208:209], v177 offset:0x2e00
	ds_read_b64_tr_b16 v[210:211], v177 offset:0x3600
	ds_read_b64_tr_b16 v[212:213], v177 offset:0x3e00
	s_waitcnt lgkmcnt(4)
	v_mfma_f32_32x32x16_bf16 v[0:15], v[154:157], v[198:201], v[0:15]
	v_mfma_f32_32x32x16_bf16 v[0:15], v[158:161], v[202:205], v[0:15]
	s_waitcnt lgkmcnt(0)
	v_mfma_f32_32x32x16_bf16 v[0:15], v[162:165], v[206:209], v[0:15]
	s_sub_i32 s2, s91, 64
	s_cmp_le_i32 s2, s88
	v_mfma_f32_32x32x16_bf16 v[0:15], v[166:169], v[210:213], v[0:15]
	s_cbranch_scc1 .LBB0_560
	v_cmp_gt_i32_e64 s[62:63], 26, v173
	v_cmp_gt_i32_e64 s[64:65], 27, v173
	v_cmp_gt_i32_e64 s[60:61], 25, v173
	s_and_b64 s[62:63], s[64:65], s[62:63]
	v_cmp_gt_i32_e64 s[58:59], 24, v173
	s_and_b64 s[60:61], s[62:63], s[60:61]
	v_cmp_gt_i32_e64 s[56:57], 19, v173
	s_and_b64 s[58:59], s[60:61], s[58:59]
	v_cmp_gt_i32_e64 s[54:55], 18, v173
	s_and_b64 s[56:57], s[58:59], s[56:57]
	v_cmp_gt_i32_e64 s[52:53], 17, v173
	s_and_b64 s[54:55], s[56:57], s[54:55]
	v_cmp_gt_i32_e64 s[50:51], 16, v173
	s_and_b64 s[52:53], s[54:55], s[52:53]
	v_cmp_gt_i32_e64 s[48:49], 11, v173
	s_and_b64 s[50:51], s[52:53], s[50:51]
	v_cmp_gt_i32_e64 s[46:47], 10, v173
	s_and_b64 s[48:49], s[50:51], s[48:49]
	v_cmp_gt_i32_e64 s[44:45], 9, v173
	s_and_b64 s[46:47], s[48:49], s[46:47]
	v_cmp_gt_i32_e64 s[42:43], 8, v173
	s_and_b64 s[44:45], s[46:47], s[44:45]
	v_cmp_gt_i32_e64 s[40:41], 3, v173
	s_and_b64 s[42:43], s[44:45], s[42:43]
	v_cmp_gt_i32_e64 s[38:39], 2, v173
	s_and_b64 s[40:41], s[42:43], s[40:41]
	v_cmp_gt_i32_e64 s[36:37], 1, v173
	s_and_b64 s[38:39], s[40:41], s[38:39]
	v_cmp_gt_i32_e64 s[34:35], 0, v173
	s_and_b64 s[36:37], s[38:39], s[36:37]
	s_and_b64 s[34:35], s[36:37], s[34:35]
	v_cmp_gt_i32_e64 s[28:29], 58, v173
	v_cndmask_b32_e64 v80, v80, v130, s[34:35]
	v_cmp_gt_i32_e64 s[34:35], 59, v173
	v_cmp_gt_i32_e64 s[26:27], 57, v173
	s_and_b64 s[28:29], s[34:35], s[28:29]
	v_cmp_gt_i32_e64 s[24:25], 56, v173
	s_and_b64 s[26:27], s[28:29], s[26:27]
	v_cmp_gt_i32_e64 s[22:23], 51, v173
	s_and_b64 s[24:25], s[26:27], s[24:25]
	v_cmp_gt_i32_e64 s[20:21], 50, v173
	s_and_b64 s[22:23], s[24:25], s[22:23]
	v_cmp_gt_i32_e64 s[18:19], 49, v173
	s_and_b64 s[20:21], s[22:23], s[20:21]
	v_cmp_gt_i32_e64 s[16:17], 48, v173
	s_and_b64 s[18:19], s[20:21], s[18:19]
	v_cmp_gt_i32_e64 s[14:15], 43, v173
	s_and_b64 s[16:17], s[18:19], s[16:17]
	v_cmp_gt_i32_e64 s[12:13], 42, v173
	s_and_b64 s[14:15], s[16:17], s[14:15]
	v_cmp_gt_i32_e64 s[10:11], 41, v173
	s_and_b64 s[12:13], s[14:15], s[12:13]
	v_cmp_gt_i32_e64 s[8:9], 40, v173
	s_and_b64 s[10:11], s[12:13], s[10:11]
	v_cmp_gt_i32_e64 s[6:7], 35, v173
	s_and_b64 s[8:9], s[10:11], s[8:9]
	v_cmp_gt_i32_e64 s[4:5], 34, v173
	s_and_b64 s[6:7], s[8:9], s[6:7]
	v_cmp_gt_i32_e64 s[2:3], 33, v173
	s_and_b64 s[4:5], s[6:7], s[4:5]
	v_cmp_gt_i32_e32 vcc, 32, v173
	s_and_b64 s[2:3], s[4:5], s[2:3]
	s_and_b64 vcc, s[2:3], vcc
	v_cndmask_b32_e64 v95, v95, v130, s[64:65]
	v_cndmask_b32_e64 v94, v94, v130, s[62:63]
	v_cndmask_b32_e64 v93, v93, v130, s[60:61]
	v_cndmask_b32_e64 v92, v92, v130, s[58:59]
	v_cndmask_b32_e64 v91, v91, v130, s[56:57]
	v_cndmask_b32_e64 v90, v90, v130, s[54:55]
	v_cndmask_b32_e64 v89, v89, v130, s[52:53]
	v_cndmask_b32_e64 v88, v88, v130, s[50:51]
	v_cndmask_b32_e64 v87, v87, v130, s[48:49]
	v_cndmask_b32_e64 v86, v86, v130, s[46:47]
	v_cndmask_b32_e64 v85, v85, v130, s[44:45]
	v_cndmask_b32_e64 v84, v84, v130, s[42:43]
	v_cndmask_b32_e64 v83, v83, v130, s[40:41]
	v_cndmask_b32_e64 v82, v82, v130, s[38:39]
	v_cndmask_b32_e64 v81, v81, v130, s[36:37]
	v_cndmask_b32_e64 v79, v79, v130, s[34:35]
	v_cndmask_b32_e64 v78, v78, v130, s[28:29]
	v_cndmask_b32_e64 v77, v77, v130, s[26:27]
	v_cndmask_b32_e64 v76, v76, v130, s[24:25]
	v_cndmask_b32_e64 v75, v75, v130, s[22:23]
	v_cndmask_b32_e64 v74, v74, v130, s[20:21]
	v_cndmask_b32_e64 v73, v73, v130, s[18:19]
	v_cndmask_b32_e64 v72, v72, v130, s[16:17]
	v_cndmask_b32_e64 v71, v71, v130, s[14:15]
	v_cndmask_b32_e64 v70, v70, v130, s[12:13]
	v_cndmask_b32_e64 v69, v69, v130, s[10:11]
	v_cndmask_b32_e64 v68, v68, v130, s[8:9]
	v_cndmask_b32_e64 v67, v67, v130, s[6:7]
	v_cndmask_b32_e64 v66, v66, v130, s[4:5]
	v_cndmask_b32_e64 v65, v65, v130, s[2:3]
	v_cndmask_b32_e32 v64, v64, v130, vcc

; __device__ __forceinline__ void partialSM(f32x16& p0, f32x16& p1, float& m_reg, float& mn, float& alpha) {
;     ...
;     if (__builtin_expect(__all((pmax - m_reg) <= THR2), 1)) { mn = m_reg; alpha = 1.f; }
;     else { mn = fmaxf(m_reg, pmax); alpha = __builtin_amdgcn_exp2f(m_reg - mn); m_reg = mn; }
.Lmaxtail_2:
	s_cmp_eq_u64 vcc, exec
	s_cselect_b64 s[2:3], -1, 0
	v_cndmask_b32_e64 v177, v155, 1.0, s[2:3]
	v_cmp_gt_f32_e32 vcc, 1.0, v177
	s_cbranch_vccz .LBB0_564
	s_and_saveexec_b64 s[4:5], s[0:1]
	ds_write_b32 v171, v177 offset:128
	s_or_b64 exec, exec, s[4:5]
	s_waitcnt lgkmcnt(0)
	ds_read_b128 v[156:159], v131 offset:224
	ds_read_b128 v[160:163], v131 offset:192
	ds_read_b128 v[164:167], v131 offset:160
	ds_read_b128 v[198:201], v131 offset:128
	s_waitcnt lgkmcnt(0)
	v_pk_mul_f32 v[62:63], v[62:63], v[158:159]
	v_pk_mul_f32 v[58:59], v[58:59], v[162:163]
	v_pk_mul_f32 v[54:55], v[54:55], v[166:167]
	v_pk_mul_f32 v[50:51], v[50:51], v[200:201]
	v_pk_mul_f32 v[60:61], v[60:61], v[156:157]
	v_pk_mul_f32 v[56:57], v[56:57], v[160:161]
	v_pk_mul_f32 v[52:53], v[52:53], v[164:165]
	v_pk_mul_f32 v[48:49], v[48:49], v[198:199]
	v_pk_mul_f32 v[46:47], v[46:47], v[158:159]
	v_pk_mul_f32 v[42:43], v[42:43], v[162:163]
	v_pk_mul_f32 v[38:39], v[38:39], v[166:167]
	v_pk_mul_f32 v[34:35], v[34:35], v[200:201]
	v_pk_mul_f32 v[44:45], v[44:45], v[156:157]
	v_pk_mul_f32 v[40:41], v[40:41], v[160:161]
	v_pk_mul_f32 v[36:37], v[36:37], v[164:165]
	v_pk_mul_f32 v[32:33], v[32:33], v[198:199]
	v_pk_mul_f32 v[30:31], v[30:31], v[158:159]
	v_pk_mul_f32 v[26:27], v[26:27], v[162:163]
	v_pk_mul_f32 v[22:23], v[22:23], v[166:167]
	v_pk_mul_f32 v[18:19], v[18:19], v[200:201]
	v_pk_mul_f32 v[28:29], v[28:29], v[156:157]
	v_pk_mul_f32 v[24:25], v[24:25], v[160:161]
	v_pk_mul_f32 v[20:21], v[20:21], v[164:165]
	v_pk_mul_f32 v[16:17], v[16:17], v[198:199]
	v_pk_mul_f32 v[14:15], v[14:15], v[158:159]
	v_pk_mul_f32 v[10:11], v[10:11], v[162:163]
	v_pk_mul_f32 v[6:7], v[6:7], v[166:167]
	v_pk_mul_f32 v[2:3], v[2:3], v[200:201]
	v_pk_mul_f32 v[12:13], v[12:13], v[156:157]
	v_pk_mul_f32 v[8:9], v[8:9], v[160:161]
	v_pk_mul_f32 v[4:5], v[4:5], v[164:165]
	v_pk_mul_f32 v[0:1], v[0:1], v[198:199]

; #define LAS __attribute__((address_space(3)))
; __device__ __forceinline__ void partialSM(f32x16& p0, f32x16& p1, float& m_reg, float& mn, float& alpha) {
;     ...
; #pragma unroll
;     for (int r = 0; r < 16; ++r) p0[r] = p0[r] - mn;
; #pragma unroll
;     for (int r = 0; r < 16; ++r) p1[r] = p1[r] - mn;
; #pragma unroll
;     for (int r = 0; r < 16; ++r) p0[r] = __builtin_amdgcn_exp2f(p0[r]);
; }
; __device__ __forceinline__ void finishSM(f32x16& p0, f32x16& p1, float alpha, float& l_reg, bf16x8& pa0, bf16x8& pa1, bf16x8& pa2, bf16x8& pa3) {
; #pragma unroll
;     for (int r = 0; r < 16; ++r) p1[r] = __builtin_amdgcn_exp2f(p1[r]);
;     float ps = 0;
; #pragma unroll
;     for (int r = 0; r < 16; ++r) ps += p0[r];
; #pragma unroll
;     for (int r = 0; r < 16; ++r) ps += p1[r];
;     { auto rr = __builtin_amdgcn_permlane32_swap(__float_as_uint(ps), __float_as_uint(ps), false, false);
;       ps = __uint_as_float(rr[0]) + __uint_as_float(rr[1]); }
;     l_reg = l_reg * alpha + ps;
;     ...
;     PK4(p0, 0, pa0); PK4(p0, 8, pa1); PK4(p1, 0, pa2); PK4(p1, 8, pa3);
;     ...
; }
; __device__ __forceinline__ void qkt(f32x16& p0, f32x16& p1, const char* Kslot, int r32, int hi, const bf16x8* qr, const LAS f32x4* cp) {
; #pragma unroll
;     for (int g = 0; g < 4; ++g) { const f32x4 c0 = cp[2 * g], c1 = cp[8 + 2 * g];
; #pragma unroll
;         for (int j = 0; j < 4; ++j) { p0[4 * g + j] = c0[j]; p1[4 * g + j] = c1[j]; } }
;     const char* kb[4];
; #pragma unroll
;     for (int dd = 0; dd < 4; ++dd) kb[dd] = Kslot + KSWZ(r32, (dd * 16 + hi * 8) * 2);
; #pragma unroll
;     for (int d0 = 0; d0 < 8; ++d0) { const char* a = kb[d0 & 3] + (d0 >> 2) * 128;
;         bf16x8 b0 = *reinterpret_cast<const bf16x8*>(a);
;         bf16x8 b1 = *reinterpret_cast<const bf16x8*>(a + 32 * 256);
;         p0 = __builtin_amdgcn_mfma_f32_32x32x16_bf16(b0, qr[d0], p0, 0, 0, 0);
;         p1 = __builtin_amdgcn_mfma_f32_32x32x16_bf16(b1, qr[d0], p1, 0, 0, 0); }
.LBB0_572:
	v_cndmask_b32_e64 v144, v154, v144, s[2:3]
	v_sub_f32_e32 v80, v80, v144
	v_sub_f32_e32 v81, v81, v144
	v_sub_f32_e32 v82, v82, v144
	v_sub_f32_e32 v83, v83, v144
	v_sub_f32_e32 v84, v84, v144
	v_sub_f32_e32 v85, v85, v144
	v_sub_f32_e32 v86, v86, v144
	v_sub_f32_e32 v87, v87, v144
	v_sub_f32_e32 v88, v88, v144
	v_sub_f32_e32 v89, v89, v144
	v_sub_f32_e32 v90, v90, v144
	v_sub_f32_e32 v91, v91, v144
	v_sub_f32_e32 v92, v92, v144
	v_sub_f32_e32 v93, v93, v144
	v_sub_f32_e32 v94, v94, v144
	v_sub_f32_e32 v95, v95, v144
	v_sub_f32_e32 v154, v64, v144
	v_sub_f32_e32 v155, v65, v144
	v_sub_f32_e32 v156, v66, v144
	v_sub_f32_e32 v157, v67, v144
	v_sub_f32_e32 v158, v68, v144
	v_sub_f32_e32 v159, v69, v144
	v_sub_f32_e32 v160, v70, v144
	v_sub_f32_e32 v161, v71, v144
	v_sub_f32_e32 v162, v72, v144
	v_sub_f32_e32 v163, v73, v144
	v_sub_f32_e32 v164, v74, v144
	v_sub_f32_e32 v165, v75, v144
	v_sub_f32_e32 v166, v76, v144
	v_exp_f32_e32 v167, v80
	v_exp_f32_e32 v168, v81
	v_exp_f32_e32 v169, v82
	v_exp_f32_e32 v178, v83
	v_exp_f32_e32 v179, v84
	v_exp_f32_e32 v198, v85
	v_exp_f32_e32 v199, v86
	v_exp_f32_e32 v200, v87
	v_exp_f32_e32 v201, v88
	v_exp_f32_e32 v202, v89
	v_exp_f32_e32 v203, v90
	v_exp_f32_e32 v204, v91
	v_exp_f32_e32 v205, v92
	v_exp_f32_e32 v206, v93
	v_exp_f32_e32 v207, v94
	v_exp_f32_e32 v208, v95
	v_sub_f32_e32 v209, v77, v144
	v_sub_f32_e32 v210, v78, v144
	v_sub_f32_e32 v211, v79, v144
	s_add_i32 s2, s90, 0
	v_add_u32_e32 v212, s2, v193
	ds_read_b128 v[80:83], v197 offset:256
	ds_read_b128 v[84:87], v197 offset:288
	ds_read_b128 v[64:67], v197 offset:384
	ds_read_b128 v[68:71], v197 offset:416
	ds_read_b128 v[88:91], v197 offset:320
	ds_read_b128 v[72:75], v197 offset:448
	ds_read_b128 v[92:95], v197 offset:352
	ds_read_b128 v[76:79], v197 offset:480
	ds_read_b128 v[146:149], v212 offset:49152
	ds_read_b128 v[150:153], v212 offset:57344
	v_add_u32_e32 v213, s2, v194
	v_add_u32_e32 v214, s2, v195
	s_waitcnt lgkmcnt(0)
	v_mfma_f32_32x32x16_bf16 v[80:95], v[146:149], v[96:99], v[80:95]
	v_add_u32_e32 v215, s2, v196
	v_exp_f32_e32 v157, v157
	v_exp_f32_e32 v158, v158
	v_exp_f32_e32 v159, v159
	v_exp_f32_e32 v160, v160
	v_exp_f32_e32 v161, v161
	v_exp_f32_e32 v162, v162
	v_mfma_f32_32x32x16_bf16 v[64:79], v[150:153], v[96:99], v[64:79]
	ds_read_b128 v[146:149], v213 offset:49152
	ds_read_b128 v[150:153], v213 offset:57344
	v_exp_f32_e32 v163, v163
	v_exp_f32_e32 v164, v164
	v_exp_f32_e32 v165, v165
	v_exp_f32_e32 v166, v166
	v_exp_f32_e32 v209, v209
	v_exp_f32_e32 v210, v210
	s_waitcnt lgkmcnt(0)
	v_mfma_f32_32x32x16_bf16 v[80:95], v[146:149], v[100:103], v[80:95]
	v_exp_f32_e32 v211, v211
	v_mfma_f32_32x32x16_bf16 v[64:79], v[150:153], v[100:103], v[64:79]
	ds_read_b128 v[146:149], v214 offset:49152
	ds_read_b128 v[150:153], v214 offset:57344
	s_waitcnt lgkmcnt(0)
	v_mfma_f32_32x32x16_bf16 v[80:95], v[146:149], v[104:107], v[80:95]
	v_mfma_f32_32x32x16_bf16 v[64:79], v[150:153], v[104:107], v[64:79]
	ds_read_b128 v[146:149], v215 offset:49152
	ds_read_b128 v[150:153], v215 offset:57344
	s_waitcnt lgkmcnt(0)
	v_mfma_f32_32x32x16_bf16 v[80:95], v[146:149], v[108:111], v[80:95]
	v_mfma_f32_32x32x16_bf16 v[64:79], v[150:153], v[108:111], v[64:79]
	v_xor_b32_e32 v249, 0x80, v212
	v_xor_b32_e32 v250, 0x80, v213
	v_xor_b32_e32 v251, 0x80, v214
	v_xor_b32_e32 v252, 0x80, v215
	ds_read_b128 v[146:149], v249 offset:49152
	ds_read_b128 v[150:153], v249 offset:57344
	v_exp_f32_e32 v212, v154
	s_waitcnt lgkmcnt(0)
	v_mfma_f32_32x32x16_bf16 v[80:95], v[146:149], v[112:115], v[80:95]
	v_mfma_f32_32x32x16_bf16 v[64:79], v[150:153], v[112:115], v[64:79]
	ds_read_b128 v[146:149], v250 offset:49152
	ds_read_b128 v[150:153], v250 offset:57344
	v_exp_f32_e32 v213, v155
	s_waitcnt lgkmcnt(0)
	v_mfma_f32_32x32x16_bf16 v[80:95], v[146:149], v[116:119], v[80:95]
	v_mfma_f32_32x32x16_bf16 v[64:79], v[150:153], v[116:119], v[64:79]
	ds_read_b128 v[146:149], v251 offset:49152
	ds_read_b128 v[150:153], v251 offset:57344
	v_exp_f32_e32 v214, v156
	s_waitcnt lgkmcnt(0)
	v_mfma_f32_32x32x16_bf16 v[80:95], v[146:149], v[120:123], v[80:95]
	v_mfma_f32_32x32x16_bf16 v[64:79], v[150:153], v[120:123], v[64:79]
	ds_read_b128 v[146:149], v252 offset:49152
	ds_read_b128 v[150:153], v252 offset:57344
	s_waitcnt lgkmcnt(0)
	v_mfma_f32_32x32x16_bf16 v[80:95], v[146:149], v[124:127], v[80:95]
	v_add_f32_e32 v146, 0, v167
	v_add_f32_e32 v146, v168, v146
	v_add_f32_e32 v146, v169, v146
	v_add_f32_e32 v146, v178, v146
	v_add_f32_e32 v146, v179, v146
	v_add_f32_e32 v146, v198, v146
	v_add_f32_e32 v146, v199, v146
	v_add_f32_e32 v146, v200, v146
	v_add_f32_e32 v146, v201, v146
	v_add_f32_e32 v146, v202, v146
	v_add_f32_e32 v146, v203, v146
	v_add_f32_e32 v146, v204, v146
	v_add_f32_e32 v146, v205, v146
	v_add_f32_e32 v146, v206, v146
	v_add_f32_e32 v146, v207, v146
	v_add_f32_e32 v146, v208, v146
	v_add_f32_e32 v146, v212, v146
	v_add_f32_e32 v146, v213, v146
	v_add_f32_e32 v146, v214, v146
	v_add_f32_e32 v146, v157, v146
	v_add_f32_e32 v146, v158, v146
	v_add_f32_e32 v146, v159, v146
	v_add_f32_e32 v146, v160, v146
	v_add_f32_e32 v146, v161, v146
	v_add_f32_e32 v146, v162, v146
	v_add_f32_e32 v146, v163, v146
	v_mfma_f32_32x32x16_bf16 v[64:79], v[150:153], v[124:127], v[64:79]
	v_add_f32_e32 v146, v164, v146
	v_add_f32_e32 v146, v165, v146
	v_add_f32_e32 v146, v166, v146
	v_add_f32_e32 v146, v209, v146
	v_add_f32_e32 v146, v210, v146
	v_add_f32_e32 v146, v211, v146
	v_mov_b32_e32 v147, v146
	s_nop 1
	v_permlane32_swap_b32_e32 v146, v147
	v_cvt_pk_bf16_f32 v148, v167, v168
	v_cvt_pk_bf16_f32 v149, v169, v178
	v_cvt_pk_bf16_f32 v150, v179, v198
	v_cvt_pk_bf16_f32 v151, v199, v200
	v_cvt_pk_bf16_f32 v152, v201, v202
	v_cvt_pk_bf16_f32 v153, v203, v204
	v_cvt_pk_bf16_f32 v154, v205, v206
	v_cvt_pk_bf16_f32 v155, v207, v208
	v_cvt_pk_bf16_f32 v156, v212, v213
	v_cvt_pk_bf16_f32 v157, v214, v157
	v_cvt_pk_bf16_f32 v158, v158, v159
	v_cvt_pk_bf16_f32 v159, v160, v161
	v_cvt_pk_bf16_f32 v160, v162, v163
	v_cvt_pk_bf16_f32 v161, v164, v165
	v_cvt_pk_bf16_f32 v162, v166, v209
	v_cvt_pk_bf16_f32 v163, v210, v211
	s_nop 0
	v_permlane32_swap_b32_e32 v148, v150
	v_permlane32_swap_b32_e32 v149, v151
	v_permlane32_swap_b32_e32 v152, v154
	v_permlane32_swap_b32_e32 v153, v155
	v_permlane32_swap_b32_e32 v156, v158
	v_permlane32_swap_b32_e32 v157, v159
	v_permlane32_swap_b32_e32 v160, v162
	v_permlane32_swap_b32_e32 v161, v163
	v_add_u32_e32 v168, s73, v192
	s_cmp_le_i32 s91, s88
	s_cbranch_scc0 .Lband_3
; #define SBAR() __builtin_amdgcn_sched_barrier(0)
; #define PV_RD(d0, kh, X) do { constexpr int b_ = v_rd_off(d0, 2 * (kh), 0); TRRD(X##l0, b_); TRRD(X##h0, b_ + 2048); TRRD(X##l1, b_ + 4096); TRRD(X##h1, b_ + 6144); } while (0)
; #define PV_MM(d0, X, PA, PB) do { \
;         o[d0] = __builtin_amdgcn_mfma_f32_32x32x16_bf16(PA, (bf16x8){X##l0[0], X##l0[1], X##l0[2], X##l0[3], X##h0[0], X##h0[1], X##h0[2], X##h0[3]}, o[d0], 0, 0, 0);   \
;         o[d0] = __builtin_amdgcn_mfma_f32_32x32x16_bf16(PB, (bf16x8){X##l1[0], X##l1[1], X##l1[2], X##l1[3], X##h1[0], X##h1[1], X##h1[2], X##h1[3]}, o[d0], 0, 0, 0); } while (0)
; #define PV_W4() do { asm volatile("s_waitcnt lgkmcnt(4)" ::: "memory"); SBAR(); } while (0)
; #define PV_W0() do { asm volatile("s_waitcnt lgkmcnt(0)" ::: "memory"); SBAR(); } while (0)
; __device__ __forceinline__ void partialSM(f32x16& p0, f32x16& p1, float& m_reg, float& mn, float& alpha) {
;     float pmax = p0[0];
; #pragma unroll
;     for (int r = 1; r < 16; ++r) pmax = fmaxf(pmax, p0[r]);
; #pragma unroll
;     for (int r = 0; r < 16; ++r) pmax = fmaxf(pmax, p1[r]);
;     { auto rr = __builtin_amdgcn_permlane32_swap(__float_as_uint(pmax), __float_as_uint(pmax), false, false);
;       pmax = fmaxf(__uint_as_float(rr[0]), __uint_as_float(rr[1])); }
;     if (__builtin_expect(__all((pmax - m_reg) <= THR2), 1)) { mn = m_reg; alpha = 1.f; }
;     else { mn = fmaxf(m_reg, pmax); alpha = __builtin_amdgcn_exp2f(m_reg - mn); m_reg = mn; }
; __device__ __forceinline__ void pv_tile(f32x16* o, int vb0, bf16x8 pa0, bf16x8 pa1, bf16x8 pa2, bf16x8 pa3) {
;     ...
;     s16x4 al0, al1, ah0, ah1, bl0, bl1, bh0, bh1;
;     PV_RD(0, 0, a);
;     PV_RD(0, 1, b); PV_W4(); PV_MM(0, a, pa0, pa1); SBAR();
;     PV_RD(1, 0, a); PV_W4(); PV_MM(0, b, pa2, pa3); SBAR();
;     PV_RD(1, 1, b); PV_W4(); PV_MM(1, a, pa0, pa1); SBAR();
;     PV_RD(2, 0, a); PV_W4(); PV_MM(1, b, pa2, pa3); SBAR();
;     PV_RD(2, 1, b); PV_W4(); PV_MM(2, a, pa0, pa1); SBAR();
;     PV_RD(3, 0, a); PV_W4(); PV_MM(2, b, pa2, pa3); SBAR();
;     PV_RD(3, 1, b); PV_W4(); PV_MM(3, a, pa0, pa1); SBAR();
;     PV_W0(); PV_MM(3, b, pa2, pa3);
	ds_read_b64_tr_b16 v[164:165], v168 offset:0
	ds_read_b64_tr_b16 v[166:167], v168 offset:0x800
	ds_read_b64_tr_b16 v[198:199], v168 offset:0x1000
	ds_read_b64_tr_b16 v[200:201], v168 offset:0x1800
	ds_read_b64_tr_b16 v[202:203], v168 offset:0x2000
	ds_read_b64_tr_b16 v[204:205], v168 offset:0x2800
	ds_read_b64_tr_b16 v[206:207], v168 offset:0x3000
	ds_read_b64_tr_b16 v[208:209], v168 offset:0x3800
	s_waitcnt lgkmcnt(4)
	s_nop 0
	v_mfma_f32_32x32x16_bf16 v[48:63], v[148:151], v[164:167], v[48:63]
	v_max_f32_e32 v253, v81, v81
	v_max_f32_e32 v254, v80, v80
	v_mfma_f32_32x32x16_bf16 v[48:63], v[152:155], v[198:201], v[48:63]
	v_max_f32_e32 v253, v254, v253
	v_max3_f32 v253, v253, v82, v83
	ds_read_b64_tr_b16 v[164:165], v168 offset:0x200
	ds_read_b64_tr_b16 v[166:167], v168 offset:0xa00
	ds_read_b64_tr_b16 v[198:199], v168 offset:0x1200
	ds_read_b64_tr_b16 v[200:201], v168 offset:0x1a00
	s_waitcnt lgkmcnt(4)
	v_mfma_f32_32x32x16_bf16 v[48:63], v[156:159], v[202:205], v[48:63]
	v_max3_f32 v253, v253, v84, v85
	v_max3_f32 v253, v253, v86, v87
	v_mfma_f32_32x32x16_bf16 v[48:63], v[160:163], v[206:209], v[48:63]
	v_max3_f32 v253, v253, v88, v89
	v_max3_f32 v253, v253, v90, v91
	ds_read_b64_tr_b16 v[202:203], v168 offset:0x2200
	ds_read_b64_tr_b16 v[204:205], v168 offset:0x2a00
	ds_read_b64_tr_b16 v[206:207], v168 offset:0x3200
	ds_read_b64_tr_b16 v[208:209], v168 offset:0x3a00
	s_waitcnt lgkmcnt(4)
	v_mfma_f32_32x32x16_bf16 v[32:47], v[148:151], v[164:167], v[32:47]
	v_max3_f32 v253, v253, v92, v93
	v_max3_f32 v253, v253, v94, v95
	v_mfma_f32_32x32x16_bf16 v[32:47], v[152:155], v[198:201], v[32:47]
	v_max3_f32 v253, v253, v64, v65
	v_max3_f32 v253, v253, v66, v67
	ds_read_b64_tr_b16 v[164:165], v168 offset:0x400
	ds_read_b64_tr_b16 v[166:167], v168 offset:0xc00
	ds_read_b64_tr_b16 v[198:199], v168 offset:0x1400
	ds_read_b64_tr_b16 v[200:201], v168 offset:0x1c00
	s_waitcnt lgkmcnt(4)
	v_mfma_f32_32x32x16_bf16 v[32:47], v[156:159], v[202:205], v[32:47]
	v_max3_f32 v253, v253, v68, v69
	v_max3_f32 v253, v253, v70, v71
	v_mfma_f32_32x32x16_bf16 v[32:47], v[160:163], v[206:209], v[32:47]
	v_max3_f32 v253, v253, v72, v73
	v_max3_f32 v253, v253, v74, v75
	ds_read_b64_tr_b16 v[202:203], v168 offset:0x2400
	ds_read_b64_tr_b16 v[204:205], v168 offset:0x2c00
	ds_read_b64_tr_b16 v[206:207], v168 offset:0x3400
	ds_read_b64_tr_b16 v[208:209], v168 offset:0x3c00
	s_waitcnt lgkmcnt(4)
	v_mfma_f32_32x32x16_bf16 v[16:31], v[148:151], v[164:167], v[16:31]
	v_max3_f32 v253, v253, v76, v77
	v_max3_f32 v253, v253, v78, v79
	v_mfma_f32_32x32x16_bf16 v[16:31], v[152:155], v[198:201], v[16:31]
	v_mov_b32_e32 v254, v253
	s_nop 1
	ds_read_b64_tr_b16 v[164:165], v168 offset:0x600
	ds_read_b64_tr_b16 v[166:167], v168 offset:0xe00
	ds_read_b64_tr_b16 v[198:199], v168 offset:0x1600
	ds_read_b64_tr_b16 v[200:201], v168 offset:0x1e00
	s_waitcnt lgkmcnt(4)
	v_mfma_f32_32x32x16_bf16 v[16:31], v[156:159], v[202:205], v[16:31]
	v_permlane32_swap_b32_e32 v253, v254
	v_max_f32_e32 v254, v254, v254
	v_mfma_f32_32x32x16_bf16 v[16:31], v[160:163], v[206:209], v[16:31]
	v_max_f32_e32 v253, v253, v253
	v_max_f32_e32 v253, v253, v254
	ds_read_b64_tr_b16 v[202:203], v168 offset:0x2600
	ds_read_b64_tr_b16 v[204:205], v168 offset:0x2e00
	ds_read_b64_tr_b16 v[206:207], v168 offset:0x3600
	ds_read_b64_tr_b16 v[208:209], v168 offset:0x3e00
	s_waitcnt lgkmcnt(4)
	v_mfma_f32_32x32x16_bf16 v[0:15], v[148:151], v[164:167], v[0:15]
	v_sub_f32_e32 v254, v253, v144
	v_cmp_ge_f32_e32 vcc, s33, v254
	v_mfma_f32_32x32x16_bf16 v[0:15], v[152:155], v[198:201], v[0:15]
	v_max_f32_e32 v254, v144, v144
	v_max_f32_e32 v254, v254, v253
	s_waitcnt lgkmcnt(0)
	v_mfma_f32_32x32x16_bf16 v[0:15], v[156:159], v[202:205], v[0:15]
	v_sub_f32_e32 v253, v144, v254
	v_exp_f32_e32 v253, v253
	v_mfma_f32_32x32x16_bf16 v[0:15], v[160:163], v[206:209], v[0:15]
	v_mov_b32_e32 v148, v253
	v_mov_b32_e32 v149, v254
	s_branch .Lmaxtail_3
; #define SBAR() __builtin_amdgcn_sched_barrier(0)
; #define PV_RD(d0, kh, X) do { constexpr int b_ = v_rd_off(d0, 2 * (kh), 0); TRRD(X##l0, b_); TRRD(X##h0, b_ + 2048); TRRD(X##l1, b_ + 4096); TRRD(X##h1, b_ + 6144); } while (0)
; #define PV_MM(d0, X, PA, PB) do { \
;         o[d0] = __builtin_amdgcn_mfma_f32_32x32x16_bf16(PA, (bf16x8){X##l0[0], X##l0[1], X##l0[2], X##l0[3], X##h0[0], X##h0[1], X##h0[2], X##h0[3]}, o[d0], 0, 0, 0);   \
;         o[d0] = __builtin_amdgcn_mfma_f32_32x32x16_bf16(PB, (bf16x8){X##l1[0], X##l1[1], X##l1[2], X##l1[3], X##h1[0], X##h1[1], X##h1[2], X##h1[3]}, o[d0], 0, 0, 0); } while (0)
; #define PV_W4() do { asm volatile("s_waitcnt lgkmcnt(4)" ::: "memory"); SBAR(); } while (0)
; #define PV_W0() do { asm volatile("s_waitcnt lgkmcnt(0)" ::: "memory"); SBAR(); } while (0)
; __device__ __forceinline__ void mask_tile(f32x16& p0, f32x16& p1, int dq) {
;     const float NEG = -__builtin_inff();
; #pragma unroll
;     for (int r = 0; r < 16; ++r) { const int c = (r & 3) + 8 * (r >> 2); if (dq - c < 0) p0[r] = NEG; if (dq - c - 32 < 0) p1[r] = NEG; }
; }
; __device__ __forceinline__ void pv_tile(f32x16* o, int vb0, bf16x8 pa0, bf16x8 pa1, bf16x8 pa2, bf16x8 pa3) {
;     ...
;     s16x4 al0, al1, ah0, ah1, bl0, bl1, bh0, bh1;
;     PV_RD(0, 0, a);
;     PV_RD(0, 1, b); PV_W4(); PV_MM(0, a, pa0, pa1); SBAR();
;     PV_RD(1, 0, a); PV_W4(); PV_MM(0, b, pa2, pa3); SBAR();
;     PV_RD(1, 1, b); PV_W4(); PV_MM(1, a, pa0, pa1); SBAR();
;     PV_RD(2, 0, a); PV_W4(); PV_MM(1, b, pa2, pa3); SBAR();
;     PV_RD(2, 1, b); PV_W4(); PV_MM(2, a, pa0, pa1); SBAR();
;     PV_RD(3, 0, a); PV_W4(); PV_MM(2, b, pa2, pa3); SBAR();
;     PV_RD(3, 1, b); PV_W4(); PV_MM(3, a, pa0, pa1); SBAR();
;     PV_W0(); PV_MM(3, b, pa2, pa3);
.Lband_3:
	ds_read_b64_tr_b16 v[164:165], v168 offset:0
	ds_read_b64_tr_b16 v[166:167], v168 offset:0x800
	ds_read_b64_tr_b16 v[198:199], v168 offset:0x1000
	ds_read_b64_tr_b16 v[200:201], v168 offset:0x1800
	ds_read_b64_tr_b16 v[202:203], v168 offset:0x2000
	ds_read_b64_tr_b16 v[204:205], v168 offset:0x2800
	ds_read_b64_tr_b16 v[206:207], v168 offset:0x3000
	ds_read_b64_tr_b16 v[208:209], v168 offset:0x3800
	s_waitcnt lgkmcnt(4)
	s_nop 0
	v_mfma_f32_32x32x16_bf16 v[48:63], v[148:151], v[164:167], v[48:63]
	v_mfma_f32_32x32x16_bf16 v[48:63], v[152:155], v[198:201], v[48:63]
	ds_read_b64_tr_b16 v[164:165], v168 offset:0x200
	ds_read_b64_tr_b16 v[166:167], v168 offset:0xa00
	ds_read_b64_tr_b16 v[198:199], v168 offset:0x1200
	ds_read_b64_tr_b16 v[200:201], v168 offset:0x1a00
	s_waitcnt lgkmcnt(4)
	v_mfma_f32_32x32x16_bf16 v[48:63], v[156:159], v[202:205], v[48:63]
	v_mfma_f32_32x32x16_bf16 v[48:63], v[160:163], v[206:209], v[48:63]
	ds_read_b64_tr_b16 v[202:203], v168 offset:0x2200
	ds_read_b64_tr_b16 v[204:205], v168 offset:0x2a00
	ds_read_b64_tr_b16 v[206:207], v168 offset:0x3200
	ds_read_b64_tr_b16 v[208:209], v168 offset:0x3a00
	s_waitcnt lgkmcnt(4)
	v_mfma_f32_32x32x16_bf16 v[32:47], v[148:151], v[164:167], v[32:47]
	v_mfma_f32_32x32x16_bf16 v[32:47], v[152:155], v[198:201], v[32:47]
	ds_read_b64_tr_b16 v[164:165], v168 offset:0x400
	ds_read_b64_tr_b16 v[166:167], v168 offset:0xc00
	ds_read_b64_tr_b16 v[198:199], v168 offset:0x1400
	ds_read_b64_tr_b16 v[200:201], v168 offset:0x1c00
	s_waitcnt lgkmcnt(4)
	v_mfma_f32_32x32x16_bf16 v[32:47], v[156:159], v[202:205], v[32:47]
	v_mfma_f32_32x32x16_bf16 v[32:47], v[160:163], v[206:209], v[32:47]
	ds_read_b64_tr_b16 v[202:203], v168 offset:0x2400
	ds_read_b64_tr_b16 v[204:205], v168 offset:0x2c00
	ds_read_b64_tr_b16 v[206:207], v168 offset:0x3400
	ds_read_b64_tr_b16 v[208:209], v168 offset:0x3c00
	s_waitcnt lgkmcnt(4)
	v_mfma_f32_32x32x16_bf16 v[16:31], v[148:151], v[164:167], v[16:31]
	v_mfma_f32_32x32x16_bf16 v[16:31], v[152:155], v[198:201], v[16:31]
	ds_read_b64_tr_b16 v[164:165], v168 offset:0x600
	ds_read_b64_tr_b16 v[166:167], v168 offset:0xe00
	ds_read_b64_tr_b16 v[198:199], v168 offset:0x1600
	ds_read_b64_tr_b16 v[200:201], v168 offset:0x1e00
	s_waitcnt lgkmcnt(4)
	v_mfma_f32_32x32x16_bf16 v[16:31], v[156:159], v[202:205], v[16:31]
	v_mfma_f32_32x32x16_bf16 v[16:31], v[160:163], v[206:209], v[16:31]
	ds_read_b64_tr_b16 v[202:203], v168 offset:0x2600
	ds_read_b64_tr_b16 v[204:205], v168 offset:0x2e00
	ds_read_b64_tr_b16 v[206:207], v168 offset:0x3600
	ds_read_b64_tr_b16 v[208:209], v168 offset:0x3e00
	s_waitcnt lgkmcnt(4)
	v_mfma_f32_32x32x16_bf16 v[0:15], v[148:151], v[164:167], v[0:15]
	v_mfma_f32_32x32x16_bf16 v[0:15], v[152:155], v[198:201], v[0:15]
	s_waitcnt lgkmcnt(0)
	v_mfma_f32_32x32x16_bf16 v[0:15], v[156:159], v[202:205], v[0:15]
	s_cmp_le_i32 s91, s88
	v_mfma_f32_32x32x16_bf16 v[0:15], v[160:163], v[206:209], v[0:15]
	s_cbranch_scc1 .LBB0_574
	v_subrev_u32_e32 v148, 64, v173
	v_cmp_gt_i32_e64 s[62:63], 26, v148
	v_cmp_gt_i32_e64 s[64:65], 27, v148
	v_cmp_gt_i32_e64 s[60:61], 25, v148
	s_and_b64 s[62:63], s[64:65], s[62:63]
	v_cmp_gt_i32_e64 s[58:59], 24, v148
	s_and_b64 s[60:61], s[62:63], s[60:61]
	v_cmp_gt_i32_e64 s[56:57], 19, v148
	s_and_b64 s[58:59], s[60:61], s[58:59]
	v_cmp_gt_i32_e64 s[54:55], 18, v148
	s_and_b64 s[56:57], s[58:59], s[56:57]
	v_cmp_gt_i32_e64 s[52:53], 17, v148
	s_and_b64 s[54:55], s[56:57], s[54:55]
	v_cmp_gt_i32_e64 s[50:51], 16, v148
	s_and_b64 s[52:53], s[54:55], s[52:53]
	v_cmp_gt_i32_e64 s[48:49], 11, v148
	s_and_b64 s[50:51], s[52:53], s[50:51]
	v_cmp_gt_i32_e64 s[46:47], 10, v148
	s_and_b64 s[48:49], s[50:51], s[48:49]
	v_cmp_gt_i32_e64 s[44:45], 9, v148
	s_and_b64 s[46:47], s[48:49], s[46:47]
	v_cmp_gt_i32_e64 s[42:43], 8, v148
	s_and_b64 s[44:45], s[46:47], s[44:45]
	v_cmp_gt_i32_e64 s[40:41], 3, v148
	s_and_b64 s[42:43], s[44:45], s[42:43]
	v_cmp_gt_i32_e64 s[38:39], 2, v148
	s_and_b64 s[40:41], s[42:43], s[40:41]
	v_cmp_gt_i32_e64 s[36:37], 1, v148
	s_and_b64 s[38:39], s[40:41], s[38:39]
	v_cmp_gt_i32_e64 s[34:35], 0, v148
	s_and_b64 s[36:37], s[38:39], s[36:37]
	s_and_b64 s[34:35], s[36:37], s[34:35]
	v_cmp_gt_i32_e64 s[28:29], 58, v148
	v_cndmask_b32_e64 v80, v80, v130, s[34:35]
	v_cmp_gt_i32_e64 s[34:35], 59, v148
	v_cmp_gt_i32_e64 s[26:27], 57, v148
	s_and_b64 s[28:29], s[34:35], s[28:29]
	v_cmp_gt_i32_e64 s[24:25], 56, v148
	s_and_b64 s[26:27], s[28:29], s[26:27]
	v_cmp_gt_i32_e64 s[22:23], 51, v148
	s_and_b64 s[24:25], s[26:27], s[24:25]
	v_cmp_gt_i32_e64 s[20:21], 50, v148
	s_and_b64 s[22:23], s[24:25], s[22:23]
	v_cmp_gt_i32_e64 s[18:19], 49, v148
	s_and_b64 s[20:21], s[22:23], s[20:21]
	v_cmp_gt_i32_e64 s[16:17], 48, v148
	s_and_b64 s[18:19], s[20:21], s[18:19]
	v_cmp_gt_i32_e64 s[14:15], 43, v148
	s_and_b64 s[16:17], s[18:19], s[16:17]
	v_cmp_gt_i32_e64 s[12:13], 42, v148
	s_and_b64 s[14:15], s[16:17], s[14:15]
	v_cmp_gt_i32_e64 s[10:11], 41, v148
	s_and_b64 s[12:13], s[14:15], s[12:13]
	v_cmp_gt_i32_e64 s[8:9], 40, v148
	s_and_b64 s[10:11], s[12:13], s[10:11]
	v_cmp_gt_i32_e64 s[6:7], 35, v148
	s_and_b64 s[8:9], s[10:11], s[8:9]
	v_cmp_gt_i32_e64 s[4:5], 34, v148
	s_and_b64 s[6:7], s[8:9], s[6:7]
	v_cmp_gt_i32_e64 s[2:3], 33, v148
	s_and_b64 s[4:5], s[6:7], s[4:5]
	v_cmp_gt_i32_e32 vcc, 32, v148
	s_and_b64 s[2:3], s[4:5], s[2:3]
	s_and_b64 vcc, s[2:3], vcc
	v_cndmask_b32_e64 v95, v95, v130, s[64:65]
	v_cndmask_b32_e64 v94, v94, v130, s[62:63]
	v_cndmask_b32_e64 v93, v93, v130, s[60:61]
	v_cndmask_b32_e64 v92, v92, v130, s[58:59]
	v_cndmask_b32_e64 v91, v91, v130, s[56:57]
	v_cndmask_b32_e64 v90, v90, v130, s[54:55]
	v_cndmask_b32_e64 v89, v89, v130, s[52:53]
	v_cndmask_b32_e64 v88, v88, v130, s[50:51]
	v_cndmask_b32_e64 v87, v87, v130, s[48:49]
	v_cndmask_b32_e64 v86, v86, v130, s[46:47]
	v_cndmask_b32_e64 v85, v85, v130, s[44:45]
	v_cndmask_b32_e64 v84, v84, v130, s[42:43]
	v_cndmask_b32_e64 v83, v83, v130, s[40:41]
	v_cndmask_b32_e64 v82, v82, v130, s[38:39]
	v_cndmask_b32_e64 v81, v81, v130, s[36:37]
	v_cndmask_b32_e64 v79, v79, v130, s[34:35]
	v_cndmask_b32_e64 v78, v78, v130, s[28:29]
	v_cndmask_b32_e64 v77, v77, v130, s[26:27]
	v_cndmask_b32_e64 v76, v76, v130, s[24:25]
	v_cndmask_b32_e64 v75, v75, v130, s[22:23]
	v_cndmask_b32_e64 v74, v74, v130, s[20:21]
	v_cndmask_b32_e64 v73, v73, v130, s[18:19]
	v_cndmask_b32_e64 v72, v72, v130, s[16:17]
	v_cndmask_b32_e64 v71, v71, v130, s[14:15]
	v_cndmask_b32_e64 v70, v70, v130, s[12:13]
	v_cndmask_b32_e64 v69, v69, v130, s[10:11]
	v_cndmask_b32_e64 v68, v68, v130, s[8:9]
	v_cndmask_b32_e64 v67, v67, v130, s[6:7]
	v_cndmask_b32_e64 v66, v66, v130, s[4:5]
	v_cndmask_b32_e64 v65, v65, v130, s[2:3]
	v_cndmask_b32_e32 v64, v64, v130, vcc

; __device__ __forceinline__ void partialSM(f32x16& p0, f32x16& p1, float& m_reg, float& mn, float& alpha) {
;     ...
;     if (__builtin_expect(__all((pmax - m_reg) <= THR2), 1)) { mn = m_reg; alpha = 1.f; }
;     else { mn = fmaxf(m_reg, pmax); alpha = __builtin_amdgcn_exp2f(m_reg - mn); m_reg = mn; }
.Lmaxtail_3:
	s_cmp_eq_u64 vcc, exec
	s_cselect_b64 s[2:3], -1, 0
	v_cndmask_b32_e64 v148, v148, 1.0, s[2:3]
	v_cmp_gt_f32_e32 vcc, 1.0, v148
	s_cbranch_vccz .LBB0_578
	s_and_saveexec_b64 s[4:5], s[0:1]
	ds_write_b32 v171, v148 offset:128
	s_or_b64 exec, exec, s[4:5]
	s_waitcnt lgkmcnt(0)
	ds_read_b128 v[150:153], v131 offset:224
	ds_read_b128 v[154:157], v131 offset:192
	ds_read_b128 v[158:161], v131 offset:160
	ds_read_b128 v[162:165], v131 offset:128
	s_waitcnt lgkmcnt(0)
	v_pk_mul_f32 v[62:63], v[62:63], v[152:153]
	v_pk_mul_f32 v[58:59], v[58:59], v[156:157]
	v_pk_mul_f32 v[54:55], v[54:55], v[160:161]
	v_pk_mul_f32 v[50:51], v[50:51], v[164:165]
	v_pk_mul_f32 v[60:61], v[60:61], v[150:151]
	v_pk_mul_f32 v[56:57], v[56:57], v[154:155]
	v_pk_mul_f32 v[52:53], v[52:53], v[158:159]
	v_pk_mul_f32 v[48:49], v[48:49], v[162:163]
	v_pk_mul_f32 v[46:47], v[46:47], v[152:153]
	v_pk_mul_f32 v[42:43], v[42:43], v[156:157]
	v_pk_mul_f32 v[38:39], v[38:39], v[160:161]
	v_pk_mul_f32 v[34:35], v[34:35], v[164:165]
	v_pk_mul_f32 v[44:45], v[44:45], v[150:151]
	v_pk_mul_f32 v[40:41], v[40:41], v[154:155]
	v_pk_mul_f32 v[36:37], v[36:37], v[158:159]
	v_pk_mul_f32 v[32:33], v[32:33], v[162:163]
	v_pk_mul_f32 v[30:31], v[30:31], v[152:153]
	v_pk_mul_f32 v[26:27], v[26:27], v[156:157]
	v_pk_mul_f32 v[22:23], v[22:23], v[160:161]
	v_pk_mul_f32 v[18:19], v[18:19], v[164:165]
	v_pk_mul_f32 v[28:29], v[28:29], v[150:151]
	v_pk_mul_f32 v[24:25], v[24:25], v[154:155]
	v_pk_mul_f32 v[20:21], v[20:21], v[158:159]
	v_pk_mul_f32 v[16:17], v[16:17], v[162:163]
	v_pk_mul_f32 v[14:15], v[14:15], v[152:153]
	v_pk_mul_f32 v[10:11], v[10:11], v[156:157]
	v_pk_mul_f32 v[6:7], v[6:7], v[160:161]
	v_pk_mul_f32 v[2:3], v[2:3], v[164:165]
	v_pk_mul_f32 v[12:13], v[12:13], v[150:151]
	v_pk_mul_f32 v[8:9], v[8:9], v[154:155]
	v_pk_mul_f32 v[4:5], v[4:5], v[158:159]
	v_pk_mul_f32 v[0:1], v[0:1], v[162:163]
